# GEMM main loops: each MFMA segment's LDS-read wait moved in front of the barrier that opens it (segment starts with its first MFMA); duplicate lgkmcnt(0) removed
# baseline (speedup 1.0000x reference)
; #define LDA(dst, b, h) for (int m = 0; m < 4; ++m) for (int k = 0; k < 2; ++k) \
;     dst[m][k] = *reinterpret_cast<const bf16x8*>((char*)SA(b, h) + a_thr + (m * 2 + k) * 1024)
; #define LDB(dst, b, h) for (int n = 0; n < 2; ++n) for (int k = 0; k < 2; ++k) \
;     dst[n][k] = *reinterpret_cast<const bf16x8*>((char*)SB(b, h) + b_thr + (n * 2 + k) * 1024)
; #define MMA(ai, bj, At, Btf) do { __builtin_amdgcn_s_setprio(1); \
;     for (int m = 0; m < 4; ++m) for (int n = 0; n < 2; ++n) for (int k = 0; k < 2; ++k) \
;       acc[ai][bj][m][n] = __builtin_amdgcn_mfma_f32_16x16x32_bf16(Btf[n][k], At[m][k], acc[ai][bj][m][n], 0, 0, 0); \
;     __builtin_amdgcn_s_setprio(0); } while (0)
; #define WAIT_V(n) asm volatile("s_waitcnt vmcnt(" #n ")" ::: "memory")
; #define WAIT_L(n) asm volatile("s_waitcnt lgkmcnt(" #n ")" ::: "memory")
; #define BAR __builtin_amdgcn_s_barrier()
; #define SCHED __builtin_amdgcn_sched_barrier(0)
; template <bool OVL, bool PANEL = false, class Epi>
; __device__ __forceinline__ void gemm_phase(const bf16_t* __restrict__ A, long lda, const bf16_t* __restrict__ Bt, long ldb, int nM, int nN, int K,
;                                            const Epi& epi, bf16_t* shm, int w0) {
;     ...
;     for (int t = 0; t < nt - 2; t += 2) {
;       LDB(B0, 0, 0); SCHED; LDA(At, 0, 0); STAGE(SA(1, 1), A, lda, aoff, brow + HALF, t + 1);
;       WAIT_L(8); BAR; WAIT_L(0); MMA(0, 0, At, B0); BAR; SCHED;
;       LDB(B1, 0, 1); STAGE(SB(0, 0), Bt, ldb, boff, bcol, t + 2);
;       BAR; WAIT_L(0); MMA(0, 1, At, B1); BAR;
;       LDA(At, 0, 1); STAGE(SA(0, 0), A, lda, aoff, brow, t + 2);
;       BAR; WAIT_L(0); MMA(1, 0, At, B0); BAR; SCHED;
;       STAGE(SB(0, 1), Bt, ldb, boff, bcol + HALF, t + 2);
;       WAIT_V(6); BAR; MMA(1, 1, At, B1); BAR;
.LBB0_125:
	ds_read_b128 v[138:141], v218
	ds_read_b128 v[142:145], v218 offset:1024
	ds_read_b128 v[146:149], v218 offset:2048
	ds_read_b128 v[150:153], v218 offset:3072
	s_add_u32 s8, s4, s6
	s_addc_u32 s9, s5, s7
	ds_read_b128 v[154:157], v213
	ds_read_b128 v[158:161], v213 offset:1024
	ds_read_b128 v[162:165], v213 offset:2048
	ds_read_b128 v[166:169], v213 offset:3072
	ds_read_b128 v[170:173], v213 offset:4096
	ds_read_b128 v[174:177], v213 offset:5120
	ds_read_b128 v[178:181], v213 offset:6144
	ds_read_b128 v[182:185], v213 offset:7168
	s_mov_b32 m0, s25
	s_add_u32 s98, s8, s14
	s_addc_u32 s99, s9, s15
	global_load_lds_dwordx4 v203, s[98:99]
	s_mov_b32 m0, s32
	s_add_u32 s98, s8, s16
	s_addc_u32 s99, s9, s17
	global_load_lds_dwordx4 v203, s[98:99]
	s_waitcnt lgkmcnt(0)
	s_waitcnt vmcnt(10)
	s_barrier
	v_mfma_f32_16x16x32_bf16 v[126:129], v[138:141], v[154:157], v[126:129]
	v_mfma_f32_16x16x32_bf16 v[122:125], v[146:149], v[154:157], v[122:125]
	v_mfma_f32_16x16x32_bf16 v[118:121], v[138:141], v[162:165], v[118:121]
	v_mfma_f32_16x16x32_bf16 v[114:117], v[146:149], v[162:165], v[114:117]
	v_mfma_f32_16x16x32_bf16 v[110:113], v[138:141], v[170:173], v[110:113]
	v_mfma_f32_16x16x32_bf16 v[106:109], v[146:149], v[170:173], v[106:109]
	v_mfma_f32_16x16x32_bf16 v[102:105], v[138:141], v[178:181], v[102:105]
	v_mfma_f32_16x16x32_bf16 v[98:101], v[146:149], v[178:181], v[98:101]
	v_mfma_f32_16x16x32_bf16 v[126:129], v[142:145], v[158:161], v[126:129]
	v_mfma_f32_16x16x32_bf16 v[122:125], v[150:153], v[158:161], v[122:125]
	v_mfma_f32_16x16x32_bf16 v[118:121], v[142:145], v[166:169], v[118:121]
	v_mfma_f32_16x16x32_bf16 v[114:117], v[150:153], v[166:169], v[114:117]
	v_mfma_f32_16x16x32_bf16 v[110:113], v[142:145], v[174:177], v[110:113]
	v_mfma_f32_16x16x32_bf16 v[106:109], v[150:153], v[174:177], v[106:109]
	v_mfma_f32_16x16x32_bf16 v[102:105], v[142:145], v[182:185], v[102:105]
	v_mfma_f32_16x16x32_bf16 v[98:101], v[150:153], v[182:185], v[98:101]
	s_barrier
	s_add_u32 vcc_lo, s0, s6
	ds_read_b128 v[186:189], v219
	ds_read_b128 v[190:193], v219 offset:1024
	ds_read_b128 v[194:197], v219 offset:2048
	ds_read_b128 v[198:201], v219 offset:3072
	s_addc_u32 vcc_hi, s1, s7
	s_mov_b32 m0, s44
	s_add_u32 s98, vcc_lo, s34
	s_addc_u32 s99, vcc_hi, s35
	global_load_lds_dwordx4 v203, s[98:99]
	s_mov_b32 m0, s45
	s_add_u32 s98, vcc_lo, s18
	s_addc_u32 s99, vcc_hi, s19
	global_load_lds_dwordx4 v203, s[98:99]
	s_waitcnt lgkmcnt(0)
	s_waitcnt vmcnt(10)
	s_barrier
	v_mfma_f32_16x16x32_bf16 v[94:97], v[186:189], v[154:157], v[94:97]
	v_mfma_f32_16x16x32_bf16 v[90:93], v[194:197], v[154:157], v[90:93]
	v_mfma_f32_16x16x32_bf16 v[86:89], v[186:189], v[162:165], v[86:89]
	v_mfma_f32_16x16x32_bf16 v[82:85], v[194:197], v[162:165], v[82:85]
	v_mfma_f32_16x16x32_bf16 v[78:81], v[186:189], v[170:173], v[78:81]
	v_mfma_f32_16x16x32_bf16 v[74:77], v[194:197], v[170:173], v[74:77]
	v_mfma_f32_16x16x32_bf16 v[70:73], v[186:189], v[178:181], v[70:73]
	v_mfma_f32_16x16x32_bf16 v[66:69], v[194:197], v[178:181], v[66:69]
	v_mfma_f32_16x16x32_bf16 v[94:97], v[190:193], v[158:161], v[94:97]
	v_mfma_f32_16x16x32_bf16 v[90:93], v[198:201], v[158:161], v[90:93]
	v_mfma_f32_16x16x32_bf16 v[86:89], v[190:193], v[166:169], v[86:89]
	v_mfma_f32_16x16x32_bf16 v[82:85], v[198:201], v[166:169], v[82:85]
	v_mfma_f32_16x16x32_bf16 v[78:81], v[190:193], v[174:177], v[78:81]
	v_mfma_f32_16x16x32_bf16 v[74:77], v[198:201], v[174:177], v[74:77]
	v_mfma_f32_16x16x32_bf16 v[70:73], v[190:193], v[182:185], v[70:73]
	v_mfma_f32_16x16x32_bf16 v[66:69], v[198:201], v[182:185], v[66:69]
	s_barrier
	ds_read_b128 v[154:157], v213 offset:16384
	ds_read_b128 v[158:161], v213 offset:17408
	ds_read_b128 v[162:165], v213 offset:18432
	ds_read_b128 v[166:169], v213 offset:19456
	ds_read_b128 v[170:173], v213 offset:20480
	ds_read_b128 v[174:177], v213 offset:21504
	ds_read_b128 v[178:181], v213 offset:22528
	ds_read_b128 v[182:185], v213 offset:23552
	s_mov_b32 m0, s46
	s_add_u32 s98, s8, s34
	s_addc_u32 s99, s9, s35
	global_load_lds_dwordx4 v203, s[98:99]
	s_mov_b32 m0, s47
	s_add_u32 s98, s8, s18
	s_addc_u32 s99, s9, s19
	global_load_lds_dwordx4 v203, s[98:99]
	s_waitcnt lgkmcnt(0)
	s_barrier
	v_mfma_f32_16x16x32_bf16 v[62:65], v[138:141], v[154:157], v[62:65]
	v_mfma_f32_16x16x32_bf16 v[58:61], v[146:149], v[154:157], v[58:61]
	v_mfma_f32_16x16x32_bf16 v[54:57], v[138:141], v[162:165], v[54:57]
	v_mfma_f32_16x16x32_bf16 v[50:53], v[146:149], v[162:165], v[50:53]
	v_mfma_f32_16x16x32_bf16 v[46:49], v[138:141], v[170:173], v[46:49]
	v_mfma_f32_16x16x32_bf16 v[42:45], v[146:149], v[170:173], v[42:45]
	v_mfma_f32_16x16x32_bf16 v[38:41], v[138:141], v[178:181], v[38:41]
	v_mfma_f32_16x16x32_bf16 v[34:37], v[146:149], v[178:181], v[34:37]
	v_mfma_f32_16x16x32_bf16 v[62:65], v[142:145], v[158:161], v[62:65]
	v_mfma_f32_16x16x32_bf16 v[58:61], v[150:153], v[158:161], v[58:61]
	v_mfma_f32_16x16x32_bf16 v[54:57], v[142:145], v[166:169], v[54:57]
	v_mfma_f32_16x16x32_bf16 v[50:53], v[150:153], v[166:169], v[50:53]
	v_mfma_f32_16x16x32_bf16 v[46:49], v[142:145], v[174:177], v[46:49]
	v_mfma_f32_16x16x32_bf16 v[42:45], v[150:153], v[174:177], v[42:45]
	v_mfma_f32_16x16x32_bf16 v[38:41], v[142:145], v[182:185], v[38:41]
	v_mfma_f32_16x16x32_bf16 v[34:37], v[150:153], v[182:185], v[34:37]
	s_barrier
	s_mov_b32 m0, s48
	s_add_u32 s98, vcc_lo, s30
	s_addc_u32 s99, vcc_hi, s31
	global_load_lds_dwordx4 v203, s[98:99]
	s_mov_b32 m0, s49
	s_add_u32 s98, vcc_lo, s40
	s_addc_u32 s99, vcc_hi, s41
	global_load_lds_dwordx4 v203, s[98:99]
	s_waitcnt vmcnt(10)
	s_barrier
; #define LDA(dst, b, h) for (int m = 0; m < 4; ++m) for (int k = 0; k < 2; ++k) \
;     dst[m][k] = *reinterpret_cast<const bf16x8*>((char*)SA(b, h) + a_thr + (m * 2 + k) * 1024)
; #define LDB(dst, b, h) for (int n = 0; n < 2; ++n) for (int k = 0; k < 2; ++k) \
;     dst[n][k] = *reinterpret_cast<const bf16x8*>((char*)SB(b, h) + b_thr + (n * 2 + k) * 1024)
; #define MMA(ai, bj, At, Btf) do { __builtin_amdgcn_s_setprio(1); \
;     for (int m = 0; m < 4; ++m) for (int n = 0; n < 2; ++n) for (int k = 0; k < 2; ++k) \
;       acc[ai][bj][m][n] = __builtin_amdgcn_mfma_f32_16x16x32_bf16(Btf[n][k], At[m][k], acc[ai][bj][m][n], 0, 0, 0); \
;     __builtin_amdgcn_s_setprio(0); } while (0)
; #define WAIT_V(n) asm volatile("s_waitcnt vmcnt(" #n ")" ::: "memory")
; #define WAIT_L(n) asm volatile("s_waitcnt lgkmcnt(" #n ")" ::: "memory")
; #define BAR __builtin_amdgcn_s_barrier()
; #define SCHED __builtin_amdgcn_sched_barrier(0)
; template <bool OVL, bool PANEL = false, class Epi>
; __device__ __forceinline__ void gemm_phase(const bf16_t* __restrict__ A, long lda, const bf16_t* __restrict__ Bt, long ldb, int nM, int nN, int K,
;                                            const Epi& epi, bf16_t* shm, int w0) {
;     ...
;       WAIT_V(6); BAR; MMA(1, 1, At, B1); BAR;
;       LDB(B0, 1, 0); SCHED; LDA(At, 1, 0); STAGE(SA(0, 1), A, lda, aoff, brow + HALF, t + 2);
;       WAIT_L(8); BAR; WAIT_L(0); MMA(0, 0, At, B0); BAR; SCHED;
;       LDB(B1, 1, 1); STAGE(SB(1, 0), Bt, ldb, boff, bcol, t + 3);
;       BAR; WAIT_L(0); MMA(0, 1, At, B1); BAR;
	v_mfma_f32_16x16x32_bf16 v[30:33], v[186:189], v[154:157], v[30:33]
	v_mfma_f32_16x16x32_bf16 v[26:29], v[194:197], v[154:157], v[26:29]
	v_mfma_f32_16x16x32_bf16 v[22:25], v[186:189], v[162:165], v[22:25]
	v_mfma_f32_16x16x32_bf16 v[18:21], v[194:197], v[162:165], v[18:21]
	v_mfma_f32_16x16x32_bf16 v[14:17], v[186:189], v[170:173], v[14:17]
	v_mfma_f32_16x16x32_bf16 v[10:13], v[194:197], v[170:173], v[10:13]
	v_mfma_f32_16x16x32_bf16 v[6:9], v[186:189], v[178:181], v[6:9]
	v_mfma_f32_16x16x32_bf16 v[2:5], v[194:197], v[178:181], v[2:5]
	v_mfma_f32_16x16x32_bf16 v[30:33], v[190:193], v[158:161], v[30:33]
	v_mfma_f32_16x16x32_bf16 v[26:29], v[198:201], v[158:161], v[26:29]
	v_mfma_f32_16x16x32_bf16 v[22:25], v[190:193], v[166:169], v[22:25]
	v_mfma_f32_16x16x32_bf16 v[18:21], v[198:201], v[166:169], v[18:21]
	v_mfma_f32_16x16x32_bf16 v[14:17], v[190:193], v[174:177], v[14:17]
	v_mfma_f32_16x16x32_bf16 v[10:13], v[198:201], v[174:177], v[10:13]
	v_mfma_f32_16x16x32_bf16 v[6:9], v[190:193], v[182:185], v[6:9]
	v_mfma_f32_16x16x32_bf16 v[2:5], v[198:201], v[182:185], v[2:5]
	s_barrier
	ds_read_b128 v[138:141], v220
	ds_read_b128 v[142:145], v220 offset:1024
	ds_read_b128 v[146:149], v220 offset:2048
	ds_read_b128 v[150:153], v220 offset:3072
	ds_read_b128 v[154:157], v213 offset:32768
	ds_read_b128 v[158:161], v213 offset:33792
	ds_read_b128 v[162:165], v213 offset:34816
	ds_read_b128 v[166:169], v213 offset:35840
	ds_read_b128 v[170:173], v213 offset:36864
	ds_read_b128 v[174:177], v213 offset:37888
	ds_read_b128 v[178:181], v213 offset:38912
	ds_read_b128 v[182:185], v213 offset:39936
	s_mov_b32 m0, s50
	s_add_u32 s98, s8, s30
	s_addc_u32 s99, s9, s31
	global_load_lds_dwordx4 v203, s[98:99]
	s_mov_b32 m0, s51
	s_add_u32 s98, s8, s40
	s_addc_u32 s99, s9, s41
	global_load_lds_dwordx4 v203, s[98:99]
	s_waitcnt lgkmcnt(0)
	s_waitcnt vmcnt(10)
	s_barrier
	v_mfma_f32_16x16x32_bf16 v[126:129], v[138:141], v[154:157], v[126:129]
	v_mfma_f32_16x16x32_bf16 v[122:125], v[146:149], v[154:157], v[122:125]
	v_mfma_f32_16x16x32_bf16 v[118:121], v[138:141], v[162:165], v[118:121]
	v_mfma_f32_16x16x32_bf16 v[114:117], v[146:149], v[162:165], v[114:117]
	v_mfma_f32_16x16x32_bf16 v[110:113], v[138:141], v[170:173], v[110:113]
	v_mfma_f32_16x16x32_bf16 v[106:109], v[146:149], v[170:173], v[106:109]
	v_mfma_f32_16x16x32_bf16 v[102:105], v[138:141], v[178:181], v[102:105]
	v_mfma_f32_16x16x32_bf16 v[98:101], v[146:149], v[178:181], v[98:101]
	v_mfma_f32_16x16x32_bf16 v[126:129], v[142:145], v[158:161], v[126:129]
	v_mfma_f32_16x16x32_bf16 v[122:125], v[150:153], v[158:161], v[122:125]
	v_mfma_f32_16x16x32_bf16 v[118:121], v[142:145], v[166:169], v[118:121]
	v_mfma_f32_16x16x32_bf16 v[114:117], v[150:153], v[166:169], v[114:117]
	v_mfma_f32_16x16x32_bf16 v[110:113], v[142:145], v[174:177], v[110:113]
	v_mfma_f32_16x16x32_bf16 v[106:109], v[150:153], v[174:177], v[106:109]
	v_mfma_f32_16x16x32_bf16 v[102:105], v[142:145], v[182:185], v[102:105]
	v_mfma_f32_16x16x32_bf16 v[98:101], v[150:153], v[182:185], v[98:101]
	s_barrier
	ds_read_b128 v[186:189], v221
	ds_read_b128 v[190:193], v221 offset:1024
	ds_read_b128 v[194:197], v221 offset:2048
	ds_read_b128 v[198:201], v221 offset:3072
	s_mov_b32 m0, s52
	s_add_u32 s98, vcc_lo, s94
	s_addc_u32 s99, vcc_hi, s95
	global_load_lds_dwordx4 v203, s[98:99]
	s_mov_b32 m0, s53
	s_add_u32 s98, vcc_lo, s42
	s_addc_u32 s99, vcc_hi, s43
	global_load_lds_dwordx4 v203, s[98:99]
	s_waitcnt lgkmcnt(0)
	s_waitcnt vmcnt(10)
	s_barrier
	v_mfma_f32_16x16x32_bf16 v[94:97], v[186:189], v[154:157], v[94:97]
	v_mfma_f32_16x16x32_bf16 v[90:93], v[194:197], v[154:157], v[90:93]
	v_mfma_f32_16x16x32_bf16 v[86:89], v[186:189], v[162:165], v[86:89]
	v_mfma_f32_16x16x32_bf16 v[82:85], v[194:197], v[162:165], v[82:85]
	v_mfma_f32_16x16x32_bf16 v[78:81], v[186:189], v[170:173], v[78:81]
	v_mfma_f32_16x16x32_bf16 v[74:77], v[194:197], v[170:173], v[74:77]
	v_mfma_f32_16x16x32_bf16 v[70:73], v[186:189], v[178:181], v[70:73]
	v_mfma_f32_16x16x32_bf16 v[66:69], v[194:197], v[178:181], v[66:69]
	v_mfma_f32_16x16x32_bf16 v[94:97], v[190:193], v[158:161], v[94:97]
	v_mfma_f32_16x16x32_bf16 v[90:93], v[198:201], v[158:161], v[90:93]
	v_mfma_f32_16x16x32_bf16 v[86:89], v[190:193], v[166:169], v[86:89]
	v_mfma_f32_16x16x32_bf16 v[82:85], v[198:201], v[166:169], v[82:85]
	v_mfma_f32_16x16x32_bf16 v[78:81], v[190:193], v[174:177], v[78:81]
	v_mfma_f32_16x16x32_bf16 v[74:77], v[198:201], v[174:177], v[74:77]
	v_mfma_f32_16x16x32_bf16 v[70:73], v[190:193], v[182:185], v[70:73]
	v_mfma_f32_16x16x32_bf16 v[66:69], v[198:201], v[182:185], v[66:69]
	s_barrier
; #define LDA(dst, b, h) for (int m = 0; m < 4; ++m) for (int k = 0; k < 2; ++k) \
;     dst[m][k] = *reinterpret_cast<const bf16x8*>((char*)SA(b, h) + a_thr + (m * 2 + k) * 1024)
; #define LDB(dst, b, h) for (int n = 0; n < 2; ++n) for (int k = 0; k < 2; ++k) \
;     dst[n][k] = *reinterpret_cast<const bf16x8*>((char*)SB(b, h) + b_thr + (n * 2 + k) * 1024)
; #define MMA(ai, bj, At, Btf) do { __builtin_amdgcn_s_setprio(1); \
;     for (int m = 0; m < 4; ++m) for (int n = 0; n < 2; ++n) for (int k = 0; k < 2; ++k) \
;       acc[ai][bj][m][n] = __builtin_amdgcn_mfma_f32_16x16x32_bf16(Btf[n][k], At[m][k], acc[ai][bj][m][n], 0, 0, 0); \
;     __builtin_amdgcn_s_setprio(0); } while (0)
; #define WAIT_V(n) asm volatile("s_waitcnt vmcnt(" #n ")" ::: "memory")
; #define WAIT_L(n) asm volatile("s_waitcnt lgkmcnt(" #n ")" ::: "memory")
; #define BAR __builtin_amdgcn_s_barrier()
; #define SCHED __builtin_amdgcn_sched_barrier(0)
; template <bool OVL, bool PANEL = false, class Epi>
; __device__ __forceinline__ void gemm_phase(const bf16_t* __restrict__ A, long lda, const bf16_t* __restrict__ Bt, long ldb, int nM, int nN, int K,
;                                            const Epi& epi, bf16_t* shm, int w0) {
;     ...
;       LDA(At, 1, 1); STAGE(SA(1, 0), A, lda, aoff, brow, t + 3);
;       BAR; WAIT_L(0); MMA(1, 0, At, B0); BAR; SCHED;
;       STAGE(SB(1, 1), Bt, ldb, boff, bcol + HALF, t + 3);
;       WAIT_V(6); BAR; MMA(1, 1, At, B1); BAR;
;     }
;     { LDB(B0, 0, 0); LDA(At, 0, 0); STAGE(SA(1, 1), A, lda, aoff, brow + HALF, nt - 1);
;       BAR; WAIT_L(0); MMA(0, 0, At, B0); BAR;
	ds_read_b128 v[154:157], v213 offset:49152
	ds_read_b128 v[158:161], v213 offset:50176
	ds_read_b128 v[162:165], v213 offset:51200
	ds_read_b128 v[166:169], v213 offset:52224
	ds_read_b128 v[170:173], v213 offset:53248
	ds_read_b128 v[174:177], v213 offset:54272
	ds_read_b128 v[178:181], v213 offset:55296
	ds_read_b128 v[182:185], v213 offset:56320
	s_mov_b32 m0, s54
	s_add_u32 s98, s8, s94
	s_addc_u32 s99, s9, s95
	global_load_lds_dwordx4 v203, s[98:99]
	s_mov_b32 m0, s55
	s_add_u32 s98, s8, s42
	s_addc_u32 s99, s9, s43
	global_load_lds_dwordx4 v203, s[98:99]
	s_waitcnt lgkmcnt(0)
	s_barrier
	v_mfma_f32_16x16x32_bf16 v[62:65], v[138:141], v[154:157], v[62:65]
	v_mfma_f32_16x16x32_bf16 v[58:61], v[146:149], v[154:157], v[58:61]
	v_mfma_f32_16x16x32_bf16 v[54:57], v[138:141], v[162:165], v[54:57]
	v_mfma_f32_16x16x32_bf16 v[50:53], v[146:149], v[162:165], v[50:53]
	v_mfma_f32_16x16x32_bf16 v[46:49], v[138:141], v[170:173], v[46:49]
	v_mfma_f32_16x16x32_bf16 v[42:45], v[146:149], v[170:173], v[42:45]
	v_mfma_f32_16x16x32_bf16 v[38:41], v[138:141], v[178:181], v[38:41]
	v_mfma_f32_16x16x32_bf16 v[34:37], v[146:149], v[178:181], v[34:37]
	v_mfma_f32_16x16x32_bf16 v[62:65], v[142:145], v[158:161], v[62:65]
	v_mfma_f32_16x16x32_bf16 v[58:61], v[150:153], v[158:161], v[58:61]
	v_mfma_f32_16x16x32_bf16 v[54:57], v[142:145], v[166:169], v[54:57]
	v_mfma_f32_16x16x32_bf16 v[50:53], v[150:153], v[166:169], v[50:53]
	v_mfma_f32_16x16x32_bf16 v[46:49], v[142:145], v[174:177], v[46:49]
	v_mfma_f32_16x16x32_bf16 v[42:45], v[150:153], v[174:177], v[42:45]
	v_mfma_f32_16x16x32_bf16 v[38:41], v[142:145], v[182:185], v[38:41]
	v_mfma_f32_16x16x32_bf16 v[34:37], v[150:153], v[182:185], v[34:37]
	s_barrier
	s_mov_b64 s[8:9], 0xb0180
	s_mov_b64 s[8:9], 0x108180
	s_mov_b32 m0, s60
	s_add_u32 s98, vcc_lo, 0xb0180
	s_addc_u32 s99, vcc_hi, 0
	global_load_lds_dwordx4 v203, s[98:99]
	s_mov_b32 m0, s61
	s_add_u32 s98, vcc_lo, 0x108180
	s_addc_u32 s99, vcc_hi, 0
	global_load_lds_dwordx4 v203, s[98:99]
	s_add_i32 s2, s2, 2
	s_add_u32 s6, s6, 0x100
	s_addc_u32 s7, s7, 0
	s_cmp_gt_u32 s2, 39
	s_waitcnt vmcnt(10)
	s_barrier
	v_mfma_f32_16x16x32_bf16 v[30:33], v[186:189], v[154:157], v[30:33]
	v_mfma_f32_16x16x32_bf16 v[26:29], v[194:197], v[154:157], v[26:29]
	v_mfma_f32_16x16x32_bf16 v[22:25], v[186:189], v[162:165], v[22:25]
	v_mfma_f32_16x16x32_bf16 v[18:21], v[194:197], v[162:165], v[18:21]
	v_mfma_f32_16x16x32_bf16 v[14:17], v[186:189], v[170:173], v[14:17]
	v_mfma_f32_16x16x32_bf16 v[10:13], v[194:197], v[170:173], v[10:13]
	v_mfma_f32_16x16x32_bf16 v[6:9], v[186:189], v[178:181], v[6:9]
	v_mfma_f32_16x16x32_bf16 v[2:5], v[194:197], v[178:181], v[2:5]
	v_mfma_f32_16x16x32_bf16 v[30:33], v[190:193], v[158:161], v[30:33]
	v_mfma_f32_16x16x32_bf16 v[26:29], v[198:201], v[158:161], v[26:29]
	v_mfma_f32_16x16x32_bf16 v[22:25], v[190:193], v[166:169], v[22:25]
	v_mfma_f32_16x16x32_bf16 v[18:21], v[198:201], v[166:169], v[18:21]
	v_mfma_f32_16x16x32_bf16 v[14:17], v[190:193], v[174:177], v[14:17]
	v_mfma_f32_16x16x32_bf16 v[10:13], v[198:201], v[174:177], v[10:13]
	v_mfma_f32_16x16x32_bf16 v[6:9], v[190:193], v[182:185], v[6:9]
	v_mfma_f32_16x16x32_bf16 v[2:5], v[198:201], v[182:185], v[2:5]
	s_barrier
	s_cbranch_scc0 .LBB0_125
	s_waitcnt vmcnt(6)
	s_or_b32 s0, s28, 0x80
	s_mul_hi_i32 s1, s0, 0x1600
	s_mulk_i32 s0, 0x1600
	v_readlane_b32 s2, v250, 49
	v_add_u32_e32 v227, 16, v212
	s_add_u32 s0, s2, s0
	v_readlane_b32 s2, v250, 50
	v_add_u32_e32 v0, 0x10000, v227
	s_addc_u32 s1, s2, s1
	v_readfirstlane_b32 s2, v136
	ds_read_b128 v[130:133], v0
	ds_read_b128 v[138:141], v0 offset:1024
	ds_read_b128 v[142:145], v0 offset:2048
	ds_read_b128 v[146:149], v0 offset:3072
	ds_read_b128 v[150:153], v213
	ds_read_b128 v[154:157], v213 offset:1024
	ds_read_b128 v[158:161], v213 offset:2048
	ds_read_b128 v[162:165], v213 offset:3072
	ds_read_b128 v[166:169], v213 offset:4096
	ds_read_b128 v[170:173], v213 offset:5120
	ds_read_b128 v[174:177], v213 offset:6144
	ds_read_b128 v[178:181], v213 offset:7168
	v_mov_b32_e32 v0, v203
	s_mov_b32 m0, s2
	s_nop 0
	v_lshl_add_u64 v[134:135], s[0:1], 0, v[0:1]
	global_load_lds_dwordx4 v0, s[0:1]
	v_readfirstlane_b32 s0, v137
	v_lshl_add_u64 v[134:135], v[134:135], 0, s[26:27]
	s_mov_b32 m0, s0
	s_nop 0
	global_load_lds_dwordx4 v[134:135], off
	s_barrier
	s_waitcnt lgkmcnt(0)

; #define MMA(ai, bj, At, Btf) do { __builtin_amdgcn_s_setprio(1); \
;     for (int m = 0; m < 4; ++m) for (int n = 0; n < 2; ++n) for (int k = 0; k < 2; ++k) \
;       acc[ai][bj][m][n] = __builtin_amdgcn_mfma_f32_16x16x32_bf16(Btf[n][k], At[m][k], acc[ai][bj][m][n], 0, 0, 0); \
;     __builtin_amdgcn_s_setprio(0); } while (0)
; #define WAIT_L(n) asm volatile("s_waitcnt lgkmcnt(" #n ")" ::: "memory")
; #define BAR __builtin_amdgcn_s_barrier()
; template <bool OVL, bool PANEL = false, class Epi>
; __device__ __forceinline__ void gemm_phase(const bf16_t* __restrict__ A, long lda, const bf16_t* __restrict__ Bt, long ldb, int nM, int nN, int K,
;                                            const Epi& epi, bf16_t* shm, int w0) {
;     ...
;       BAR; WAIT_L(0); MMA(0, 0, At, B0); BAR;
	s_waitcnt lgkmcnt(0)
	v_mfma_f32_16x16x32_bf16 v[126:129], v[130:133], v[150:153], v[126:129]
	v_mfma_f32_16x16x32_bf16 v[122:125], v[142:145], v[150:153], v[122:125]
	v_mfma_f32_16x16x32_bf16 v[118:121], v[130:133], v[158:161], v[118:121]
	v_mfma_f32_16x16x32_bf16 v[114:117], v[142:145], v[158:161], v[114:117]
	v_mfma_f32_16x16x32_bf16 v[110:113], v[130:133], v[166:169], v[110:113]
	v_mfma_f32_16x16x32_bf16 v[106:109], v[142:145], v[166:169], v[106:109]
	v_mfma_f32_16x16x32_bf16 v[102:105], v[130:133], v[174:177], v[102:105]
	v_mfma_f32_16x16x32_bf16 v[98:101], v[142:145], v[174:177], v[98:101]
	v_mfma_f32_16x16x32_bf16 v[126:129], v[138:141], v[154:157], v[126:129]
	v_mfma_f32_16x16x32_bf16 v[122:125], v[146:149], v[154:157], v[122:125]
	v_mfma_f32_16x16x32_bf16 v[118:121], v[138:141], v[162:165], v[118:121]
	v_mfma_f32_16x16x32_bf16 v[114:117], v[146:149], v[162:165], v[114:117]
	v_mfma_f32_16x16x32_bf16 v[110:113], v[138:141], v[170:173], v[110:113]
	v_mfma_f32_16x16x32_bf16 v[106:109], v[146:149], v[170:173], v[106:109]
	v_mfma_f32_16x16x32_bf16 v[102:105], v[138:141], v[178:181], v[102:105]
	v_mfma_f32_16x16x32_bf16 v[98:101], v[146:149], v[178:181], v[98:101]

; #define LDB(dst, b, h) for (int n = 0; n < 2; ++n) for (int k = 0; k < 2; ++k) \
;     dst[n][k] = *reinterpret_cast<const bf16x8*>((char*)SB(b, h) + b_thr + (n * 2 + k) * 1024)
; #define MMA(ai, bj, At, Btf) do { __builtin_amdgcn_s_setprio(1); \
;     for (int m = 0; m < 4; ++m) for (int n = 0; n < 2; ++n) for (int k = 0; k < 2; ++k) \
;       acc[ai][bj][m][n] = __builtin_amdgcn_mfma_f32_16x16x32_bf16(Btf[n][k], At[m][k], acc[ai][bj][m][n], 0, 0, 0); \
;     __builtin_amdgcn_s_setprio(0); } while (0)
; #define WAIT_L(n) asm volatile("s_waitcnt lgkmcnt(" #n ")" ::: "memory")
; #define BAR __builtin_amdgcn_s_barrier()
; template <bool OVL, bool PANEL = false, class Epi>
; __device__ __forceinline__ void gemm_phase(const bf16_t* __restrict__ A, long lda, const bf16_t* __restrict__ Bt, long ldb, int nM, int nN, int K,
;                                            const Epi& epi, bf16_t* shm, int w0) {
;     ...
;       LDB(B1, 0, 1); BAR; WAIT_L(0); MMA(0, 1, At, B1); BAR;
	v_add_u32_e32 v0, 0x14000, v227
	s_barrier
	ds_read_b128 v[134:137], v0
	ds_read_b128 v[182:185], v0 offset:1024
	ds_read_b128 v[186:189], v0 offset:2048
	ds_read_b128 v[190:193], v0 offset:3072
	s_barrier
	s_waitcnt lgkmcnt(0)

; #define LDB(dst, b, h) for (int n = 0; n < 2; ++n) for (int k = 0; k < 2; ++k) \
;     dst[n][k] = *reinterpret_cast<const bf16x8*>((char*)SB(b, h) + b_thr + (n * 2 + k) * 1024)
; #define MMA(ai, bj, At, Btf) do { __builtin_amdgcn_s_setprio(1); \
;     for (int m = 0; m < 4; ++m) for (int n = 0; n < 2; ++n) for (int k = 0; k < 2; ++k) \
;       acc[ai][bj][m][n] = __builtin_amdgcn_mfma_f32_16x16x32_bf16(Btf[n][k], At[m][k], acc[ai][bj][m][n], 0, 0, 0); \
;     __builtin_amdgcn_s_setprio(0); } while (0)
; #define WAIT_L(n) asm volatile("s_waitcnt lgkmcnt(" #n ")" ::: "memory")
; #define BAR __builtin_amdgcn_s_barrier()
; template <bool OVL, bool PANEL = false, class Epi>
; __device__ __forceinline__ void gemm_phase(const bf16_t* __restrict__ A, long lda, const bf16_t* __restrict__ Bt, long ldb, int nM, int nN, int K,
;                                            const Epi& epi, bf16_t* shm, int w0) {
;     ...
;       LDB(B1, 0, 1); BAR; WAIT_L(0); MMA(0, 1, At, B1); BAR;
	s_waitcnt lgkmcnt(0)
	v_mfma_f32_16x16x32_bf16 v[94:97], v[134:137], v[150:153], v[94:97]
	v_mfma_f32_16x16x32_bf16 v[90:93], v[186:189], v[150:153], v[90:93]
	v_mfma_f32_16x16x32_bf16 v[86:89], v[134:137], v[158:161], v[86:89]
	v_mfma_f32_16x16x32_bf16 v[82:85], v[186:189], v[158:161], v[82:85]
	v_mfma_f32_16x16x32_bf16 v[78:81], v[134:137], v[166:169], v[78:81]
	v_mfma_f32_16x16x32_bf16 v[66:69], v[186:189], v[174:177], v[66:69]
	v_mfma_f32_16x16x32_bf16 v[94:97], v[182:185], v[154:157], v[94:97]
	v_mfma_f32_16x16x32_bf16 v[90:93], v[190:193], v[154:157], v[90:93]
	v_mfma_f32_16x16x32_bf16 v[86:89], v[182:185], v[162:165], v[86:89]
	v_mfma_f32_16x16x32_bf16 v[82:85], v[190:193], v[162:165], v[82:85]
	v_mfma_f32_16x16x32_bf16 v[78:81], v[182:185], v[170:173], v[78:81]
	v_mfma_f32_16x16x32_bf16 v[74:77], v[186:189], v[166:169], v[74:77]
	v_mfma_f32_16x16x32_bf16 v[70:73], v[134:137], v[174:177], v[70:73]
	v_mfma_f32_16x16x32_bf16 v[66:69], v[190:193], v[178:181], v[66:69]
	v_mfma_f32_16x16x32_bf16 v[150:153], v[190:193], v[170:173], v[74:77]
	v_mfma_f32_16x16x32_bf16 v[154:157], v[182:185], v[178:181], v[70:73]

; #define LDA(dst, b, h) for (int m = 0; m < 4; ++m) for (int k = 0; k < 2; ++k) \
;     dst[m][k] = *reinterpret_cast<const bf16x8*>((char*)SA(b, h) + a_thr + (m * 2 + k) * 1024)
; #define MMA(ai, bj, At, Btf) do { __builtin_amdgcn_s_setprio(1); \
;     for (int m = 0; m < 4; ++m) for (int n = 0; n < 2; ++n) for (int k = 0; k < 2; ++k) \
;       acc[ai][bj][m][n] = __builtin_amdgcn_mfma_f32_16x16x32_bf16(Btf[n][k], At[m][k], acc[ai][bj][m][n], 0, 0, 0); \
;     __builtin_amdgcn_s_setprio(0); } while (0)
; #define WAIT_V(n) asm volatile("s_waitcnt vmcnt(" #n ")" ::: "memory")
; #define WAIT_L(n) asm volatile("s_waitcnt lgkmcnt(" #n ")" ::: "memory")
; #define BAR __builtin_amdgcn_s_barrier()
; template <bool OVL, bool PANEL = false, class Epi>
; __device__ __forceinline__ void gemm_phase(const bf16_t* __restrict__ A, long lda, const bf16_t* __restrict__ Bt, long ldb, int nM, int nN, int K,
;                                            const Epi& epi, bf16_t* shm, int w0) {
;     ...
;       LDA(At, 0, 1); WAIT_V(4); BAR; WAIT_L(0); MMA(1, 0, At, B0); MMA(1, 1, At, B1); BAR; }
	s_barrier
	s_nop 2
	ds_read_b128 v[70:73], v213 offset:16384
	ds_read_b128 v[74:77], v213 offset:17408
	ds_read_b128 v[158:161], v213 offset:18432
	ds_read_b128 v[162:165], v213 offset:19456
	ds_read_b128 v[166:169], v213 offset:20480
	ds_read_b128 v[170:173], v213 offset:21504
	ds_read_b128 v[174:177], v213 offset:22528
	ds_read_b128 v[178:181], v213 offset:23552
	s_waitcnt vmcnt(4)
	s_barrier
	s_waitcnt lgkmcnt(0)

; #define LDA(dst, b, h) for (int m = 0; m < 4; ++m) for (int k = 0; k < 2; ++k) \
;     dst[m][k] = *reinterpret_cast<const bf16x8*>((char*)SA(b, h) + a_thr + (m * 2 + k) * 1024)
; #define MMA(ai, bj, At, Btf) do { __builtin_amdgcn_s_setprio(1); \
;     for (int m = 0; m < 4; ++m) for (int n = 0; n < 2; ++n) for (int k = 0; k < 2; ++k) \
;       acc[ai][bj][m][n] = __builtin_amdgcn_mfma_f32_16x16x32_bf16(Btf[n][k], At[m][k], acc[ai][bj][m][n], 0, 0, 0); \
;     __builtin_amdgcn_s_setprio(0); } while (0)
; #define WAIT_V(n) asm volatile("s_waitcnt vmcnt(" #n ")" ::: "memory")
; #define WAIT_L(n) asm volatile("s_waitcnt lgkmcnt(" #n ")" ::: "memory")
; #define BAR __builtin_amdgcn_s_barrier()
; template <bool OVL, bool PANEL = false, class Epi>
; __device__ __forceinline__ void gemm_phase(const bf16_t* __restrict__ A, long lda, const bf16_t* __restrict__ Bt, long ldb, int nM, int nN, int K,
;                                            const Epi& epi, bf16_t* shm, int w0) {
;     ...
;       LDA(At, 0, 1); WAIT_V(4); BAR; WAIT_L(0); MMA(1, 0, At, B0); MMA(1, 1, At, B1); BAR; }
	s_waitcnt lgkmcnt(0)
	v_mfma_f32_16x16x32_bf16 v[58:61], v[142:145], v[70:73], v[58:61]
	v_mfma_f32_16x16x32_bf16 v[54:57], v[130:133], v[158:161], v[54:57]
	v_mfma_f32_16x16x32_bf16 v[62:65], v[130:133], v[70:73], v[62:65]
	v_mfma_f32_16x16x32_bf16 v[58:61], v[146:149], v[74:77], v[58:61]
	v_mfma_f32_16x16x32_bf16 v[54:57], v[138:141], v[162:165], v[54:57]
	v_mfma_f32_16x16x32_bf16 v[50:53], v[142:145], v[158:161], v[50:53]
	v_mfma_f32_16x16x32_bf16 v[46:49], v[130:133], v[166:169], v[46:49]
	v_mfma_f32_16x16x32_bf16 v[42:45], v[142:145], v[166:169], v[42:45]
	v_mfma_f32_16x16x32_bf16 v[38:41], v[130:133], v[174:177], v[38:41]
	v_mfma_f32_16x16x32_bf16 v[34:37], v[142:145], v[174:177], v[34:37]
	v_mfma_f32_16x16x32_bf16 v[194:197], v[138:141], v[74:77], v[62:65]
	v_mfma_f32_16x16x32_bf16 v[198:201], v[146:149], v[162:165], v[50:53]
	v_mfma_f32_16x16x32_bf16 v[214:217], v[138:141], v[170:173], v[46:49]
	v_mfma_f32_16x16x32_bf16 v[218:221], v[146:149], v[170:173], v[42:45]
	v_mfma_f32_16x16x32_bf16 v[130:133], v[138:141], v[178:181], v[38:41]
	v_mfma_f32_16x16x32_bf16 v[138:141], v[146:149], v[178:181], v[34:37]


; #define LDA(dst, b, h) for (int m = 0; m < 4; ++m) for (int k = 0; k < 2; ++k) \
;     dst[m][k] = *reinterpret_cast<const bf16x8*>((char*)SA(b, h) + a_thr + (m * 2 + k) * 1024)
; #define MMA(ai, bj, At, Btf) do { __builtin_amdgcn_s_setprio(1); \
;     for (int m = 0; m < 4; ++m) for (int n = 0; n < 2; ++n) for (int k = 0; k < 2; ++k) \
;       acc[ai][bj][m][n] = __builtin_amdgcn_mfma_f32_16x16x32_bf16(Btf[n][k], At[m][k], acc[ai][bj][m][n], 0, 0, 0); \
;     __builtin_amdgcn_s_setprio(0); } while (0)
; #define WAIT_V(n) asm volatile("s_waitcnt vmcnt(" #n ")" ::: "memory")
; #define WAIT_L(n) asm volatile("s_waitcnt lgkmcnt(" #n ")" ::: "memory")
; #define BAR __builtin_amdgcn_s_barrier()
; template <bool OVL, bool PANEL = false, class Epi>
; __device__ __forceinline__ void gemm_phase(const bf16_t* __restrict__ A, long lda, const bf16_t* __restrict__ Bt, long ldb, int nM, int nN, int K,
;                                            const Epi& epi, bf16_t* shm, int w0) {
;     ...
;       LDA(At, 0, 1); WAIT_V(4); BAR; WAIT_L(0); MMA(1, 0, At, B0); MMA(1, 1, At, B1); BAR; }
	v_mfma_f32_16x16x32_bf16 v[30:33], v[134:137], v[70:73], v[30:33]
	v_mfma_f32_16x16x32_bf16 v[26:29], v[186:189], v[70:73], v[26:29]
	v_mfma_f32_16x16x32_bf16 v[22:25], v[134:137], v[158:161], v[22:25]
	v_mfma_f32_16x16x32_bf16 v[18:21], v[186:189], v[158:161], v[18:21]
	v_mfma_f32_16x16x32_bf16 v[14:17], v[134:137], v[166:169], v[14:17]
	v_mfma_f32_16x16x32_bf16 v[10:13], v[186:189], v[166:169], v[10:13]
	v_mfma_f32_16x16x32_bf16 v[6:9], v[134:137], v[174:177], v[6:9]
	v_mfma_f32_16x16x32_bf16 v[2:5], v[186:189], v[174:177], v[2:5]
	v_mfma_f32_16x16x32_bf16 v[142:145], v[182:185], v[74:77], v[30:33]
	v_mfma_f32_16x16x32_bf16 v[146:149], v[190:193], v[74:77], v[26:29]
	v_mfma_f32_16x16x32_bf16 v[222:225], v[182:185], v[162:165], v[22:25]
	v_mfma_f32_16x16x32_bf16 v[158:161], v[190:193], v[162:165], v[18:21]
	v_mfma_f32_16x16x32_bf16 v[162:165], v[182:185], v[170:173], v[14:17]
	v_mfma_f32_16x16x32_bf16 v[166:169], v[190:193], v[170:173], v[10:13]
	v_mfma_f32_16x16x32_bf16 v[134:137], v[182:185], v[178:181], v[6:9]
	v_mfma_f32_16x16x32_bf16 v[170:173], v[190:193], v[178:181], v[2:5]

; #define LDA(dst, b, h) for (int m = 0; m < 4; ++m) for (int k = 0; k < 2; ++k) \
;     dst[m][k] = *reinterpret_cast<const bf16x8*>((char*)SA(b, h) + a_thr + (m * 2 + k) * 1024)
; #define LDB(dst, b, h) for (int n = 0; n < 2; ++n) for (int k = 0; k < 2; ++k) \
;     dst[n][k] = *reinterpret_cast<const bf16x8*>((char*)SB(b, h) + b_thr + (n * 2 + k) * 1024)
; #define MMA(ai, bj, At, Btf) do { __builtin_amdgcn_s_setprio(1); \
;     for (int m = 0; m < 4; ++m) for (int n = 0; n < 2; ++n) for (int k = 0; k < 2; ++k) \
;       acc[ai][bj][m][n] = __builtin_amdgcn_mfma_f32_16x16x32_bf16(Btf[n][k], At[m][k], acc[ai][bj][m][n], 0, 0, 0); \
;     __builtin_amdgcn_s_setprio(0); } while (0)
; #define WAIT_V(n) asm volatile("s_waitcnt vmcnt(" #n ")" ::: "memory")
; #define WAIT_L(n) asm volatile("s_waitcnt lgkmcnt(" #n ")" ::: "memory")
; #define BAR __builtin_amdgcn_s_barrier()
; template <bool OVL, bool PANEL = false, class Epi>
; __device__ __forceinline__ void gemm_phase(const bf16_t* __restrict__ A, long lda, const bf16_t* __restrict__ Bt, long ldb, int nM, int nN, int K,
;                                            const Epi& epi, bf16_t* shm, int w0) {
;     ...
;     { LDB(B0, 1, 0); LDA(At, 1, 0); WAIT_V(2); BAR; WAIT_L(0); MMA(0, 0, At, B0); BAR;
	v_add_u32_e32 v0, 0x18000, v227
	s_barrier
	ds_read_b128 v[34:37], v0
	ds_read_b128 v[174:177], v0 offset:1024
	ds_read_b128 v[178:181], v0 offset:2048
	ds_read_b128 v[182:185], v0 offset:3072
	ds_read_b128 v[18:21], v213 offset:32768
	ds_read_b128 v[22:25], v213 offset:33792
	ds_read_b128 v[26:29], v213 offset:34816
	ds_read_b128 v[50:53], v213 offset:35840
	ds_read_b128 v[186:189], v213 offset:36864
	ds_read_b128 v[190:193], v213 offset:37888
	ds_read_b128 v[228:231], v213 offset:38912
	ds_read_b128 v[232:235], v213 offset:39936
	s_waitcnt vmcnt(2)
	s_barrier
	s_waitcnt lgkmcnt(0)

; #define LDA(dst, b, h) for (int m = 0; m < 4; ++m) for (int k = 0; k < 2; ++k) \
;     dst[m][k] = *reinterpret_cast<const bf16x8*>((char*)SA(b, h) + a_thr + (m * 2 + k) * 1024)
; #define LDB(dst, b, h) for (int n = 0; n < 2; ++n) for (int k = 0; k < 2; ++k) \
;     dst[n][k] = *reinterpret_cast<const bf16x8*>((char*)SB(b, h) + b_thr + (n * 2 + k) * 1024)
; #define MMA(ai, bj, At, Btf) do { __builtin_amdgcn_s_setprio(1); \
;     for (int m = 0; m < 4; ++m) for (int n = 0; n < 2; ++n) for (int k = 0; k < 2; ++k) \
;       acc[ai][bj][m][n] = __builtin_amdgcn_mfma_f32_16x16x32_bf16(Btf[n][k], At[m][k], acc[ai][bj][m][n], 0, 0, 0); \
;     __builtin_amdgcn_s_setprio(0); } while (0)
; #define WAIT_V(n) asm volatile("s_waitcnt vmcnt(" #n ")" ::: "memory")
; #define WAIT_L(n) asm volatile("s_waitcnt lgkmcnt(" #n ")" ::: "memory")
; #define BAR __builtin_amdgcn_s_barrier()
; template <bool OVL, bool PANEL = false, class Epi>
; __device__ __forceinline__ void gemm_phase(const bf16_t* __restrict__ A, long lda, const bf16_t* __restrict__ Bt, long ldb, int nM, int nN, int K,
;                                            const Epi& epi, bf16_t* shm, int w0) {
;     ...
;     { LDB(B0, 1, 0); LDA(At, 1, 0); WAIT_V(2); BAR; WAIT_L(0); MMA(0, 0, At, B0); BAR;
	s_waitcnt lgkmcnt(0)
	v_mfma_f32_16x16x32_bf16 v[6:9], v[178:181], v[18:21], v[122:125]
	v_mfma_f32_16x16x32_bf16 v[10:13], v[178:181], v[26:29], v[114:117]
	v_mfma_f32_16x16x32_bf16 v[14:17], v[178:181], v[186:189], v[106:109]
	v_mfma_f32_16x16x32_bf16 v[2:5], v[34:37], v[18:21], v[126:129]
	v_mfma_f32_16x16x32_bf16 v[30:33], v[182:185], v[22:25], v[6:9]
	v_mfma_f32_16x16x32_bf16 v[6:9], v[34:37], v[26:29], v[118:121]
	v_mfma_f32_16x16x32_bf16 v[38:41], v[182:185], v[50:53], v[10:13]
	v_mfma_f32_16x16x32_bf16 v[10:13], v[34:37], v[186:189], v[110:113]
	v_mfma_f32_16x16x32_bf16 v[42:45], v[182:185], v[190:193], v[14:17]
	v_mfma_f32_16x16x32_bf16 v[14:17], v[34:37], v[228:231], v[102:105]
	v_mfma_f32_16x16x32_bf16 v[46:49], v[178:181], v[228:231], v[98:101]
	v_mfma_f32_16x16x32_bf16 v[2:5], v[174:177], v[22:25], v[2:5]
	v_mfma_f32_16x16x32_bf16 v[6:9], v[174:177], v[50:53], v[6:9]
	v_mfma_f32_16x16x32_bf16 v[10:13], v[174:177], v[190:193], v[10:13]
	v_mfma_f32_16x16x32_bf16 v[14:17], v[174:177], v[232:235], v[14:17]
	v_mfma_f32_16x16x32_bf16 v[46:49], v[182:185], v[232:235], v[46:49]

; #define LDB(dst, b, h) for (int n = 0; n < 2; ++n) for (int k = 0; k < 2; ++k) \
;     dst[n][k] = *reinterpret_cast<const bf16x8*>((char*)SB(b, h) + b_thr + (n * 2 + k) * 1024)
; #define MMA(ai, bj, At, Btf) do { __builtin_amdgcn_s_setprio(1); \
;     for (int m = 0; m < 4; ++m) for (int n = 0; n < 2; ++n) for (int k = 0; k < 2; ++k) \
;       acc[ai][bj][m][n] = __builtin_amdgcn_mfma_f32_16x16x32_bf16(Btf[n][k], At[m][k], acc[ai][bj][m][n], 0, 0, 0); \
;     __builtin_amdgcn_s_setprio(0); } while (0)
; #define WAIT_V(n) asm volatile("s_waitcnt vmcnt(" #n ")" ::: "memory")
; #define WAIT_L(n) asm volatile("s_waitcnt lgkmcnt(" #n ")" ::: "memory")
; #define BAR __builtin_amdgcn_s_barrier()
; template <bool OVL, bool PANEL = false, class Epi>
; __device__ __forceinline__ void gemm_phase(const bf16_t* __restrict__ A, long lda, const bf16_t* __restrict__ Bt, long ldb, int nM, int nN, int K,
;                                            const Epi& epi, bf16_t* shm, int w0) {
;     ...
;       LDB(B1, 1, 1); WAIT_V(0); BAR; WAIT_L(0); MMA(0, 1, At, B1); BAR;
	v_add_u32_e32 v0, 0x1c000, v227
	s_barrier
	ds_read_b128 v[102:105], v0
	ds_read_b128 v[236:239], v0 offset:1024
	ds_read_b128 v[240:243], v0 offset:2048
	ds_read_b128 v[244:247], v0 offset:3072
	s_waitcnt vmcnt(0)
	s_barrier
	s_waitcnt lgkmcnt(0)

; #define LDB(dst, b, h) for (int n = 0; n < 2; ++n) for (int k = 0; k < 2; ++k) \
;     dst[n][k] = *reinterpret_cast<const bf16x8*>((char*)SB(b, h) + b_thr + (n * 2 + k) * 1024)
; #define MMA(ai, bj, At, Btf) do { __builtin_amdgcn_s_setprio(1); \
;     for (int m = 0; m < 4; ++m) for (int n = 0; n < 2; ++n) for (int k = 0; k < 2; ++k) \
;       acc[ai][bj][m][n] = __builtin_amdgcn_mfma_f32_16x16x32_bf16(Btf[n][k], At[m][k], acc[ai][bj][m][n], 0, 0, 0); \
;     __builtin_amdgcn_s_setprio(0); } while (0)
; #define WAIT_V(n) asm volatile("s_waitcnt vmcnt(" #n ")" ::: "memory")
; #define WAIT_L(n) asm volatile("s_waitcnt lgkmcnt(" #n ")" ::: "memory")
; #define BAR __builtin_amdgcn_s_barrier()
; template <bool OVL, bool PANEL = false, class Epi>
; __device__ __forceinline__ void gemm_phase(const bf16_t* __restrict__ A, long lda, const bf16_t* __restrict__ Bt, long ldb, int nM, int nN, int K,
;                                            const Epi& epi, bf16_t* shm, int w0) {
;     ...
;       LDB(B1, 1, 1); WAIT_V(0); BAR; WAIT_L(0); MMA(0, 1, At, B1); BAR;
	s_waitcnt lgkmcnt(0)
	v_mfma_f32_16x16x32_bf16 v[62:65], v[102:105], v[18:21], v[94:97]
	v_mfma_f32_16x16x32_bf16 v[18:21], v[240:243], v[18:21], v[90:93]
	v_mfma_f32_16x16x32_bf16 v[98:101], v[244:247], v[22:25], v[18:21]
	v_mfma_f32_16x16x32_bf16 v[18:21], v[102:105], v[26:29], v[86:89]
	v_mfma_f32_16x16x32_bf16 v[70:73], v[236:239], v[50:53], v[18:21]
	v_mfma_f32_16x16x32_bf16 v[18:21], v[240:243], v[26:29], v[82:85]
	v_mfma_f32_16x16x32_bf16 v[106:109], v[244:247], v[50:53], v[18:21]
	v_mfma_f32_16x16x32_bf16 v[18:21], v[102:105], v[186:189], v[78:81]
	v_mfma_f32_16x16x32_bf16 v[74:77], v[236:239], v[190:193], v[18:21]
	v_mfma_f32_16x16x32_bf16 v[18:21], v[240:243], v[186:189], v[150:153]
	v_mfma_f32_16x16x32_bf16 v[110:113], v[244:247], v[190:193], v[18:21]
	v_mfma_f32_16x16x32_bf16 v[18:21], v[102:105], v[228:231], v[154:157]
	v_mfma_f32_16x16x32_bf16 v[78:81], v[236:239], v[232:235], v[18:21]
	v_mfma_f32_16x16x32_bf16 v[18:21], v[240:243], v[228:231], v[66:69]
	v_mfma_f32_16x16x32_bf16 v[62:65], v[236:239], v[22:25], v[62:65]
	v_mfma_f32_16x16x32_bf16 v[114:117], v[244:247], v[232:235], v[18:21]

; #define LDA(dst, b, h) for (int m = 0; m < 4; ++m) for (int k = 0; k < 2; ++k) \
;     dst[m][k] = *reinterpret_cast<const bf16x8*>((char*)SA(b, h) + a_thr + (m * 2 + k) * 1024)
; #define MMA(ai, bj, At, Btf) do { __builtin_amdgcn_s_setprio(1); \
;     for (int m = 0; m < 4; ++m) for (int n = 0; n < 2; ++n) for (int k = 0; k < 2; ++k) \
;       acc[ai][bj][m][n] = __builtin_amdgcn_mfma_f32_16x16x32_bf16(Btf[n][k], At[m][k], acc[ai][bj][m][n], 0, 0, 0); \
;     __builtin_amdgcn_s_setprio(0); } while (0)
; #define WAIT_L(n) asm volatile("s_waitcnt lgkmcnt(" #n ")" ::: "memory")
; #define BAR __builtin_amdgcn_s_barrier()
; template <bool OVL, bool PANEL = false, class Epi>
; __device__ __forceinline__ void gemm_phase(const bf16_t* __restrict__ A, long lda, const bf16_t* __restrict__ Bt, long ldb, int nM, int nN, int K,
;                                            const Epi& epi, bf16_t* shm, int w0) {
;     ...
;       LDA(At, 1, 1); BAR; WAIT_L(0); MMA(1, 0, At, B0); MMA(1, 1, At, B1); BAR; }
	s_barrier
	ds_read_b128 v[86:89], v213 offset:49152
	ds_read_b128 v[90:93], v213 offset:50176
	ds_read_b128 v[94:97], v213 offset:51200
	ds_read_b128 v[118:121], v213 offset:52224
	ds_read_b128 v[150:153], v213 offset:53248
	ds_read_b128 v[154:157], v213 offset:54272
	ds_read_b128 v[186:189], v213 offset:55296
	ds_read_b128 v[190:193], v213 offset:56320
	s_barrier
	s_waitcnt lgkmcnt(0)

; #define LDA(dst, b, h) for (int m = 0; m < 4; ++m) for (int k = 0; k < 2; ++k) \
;     dst[m][k] = *reinterpret_cast<const bf16x8*>((char*)SA(b, h) + a_thr + (m * 2 + k) * 1024)
; #define MMA(ai, bj, At, Btf) do { __builtin_amdgcn_s_setprio(1); \
;     for (int m = 0; m < 4; ++m) for (int n = 0; n < 2; ++n) for (int k = 0; k < 2; ++k) \
;       acc[ai][bj][m][n] = __builtin_amdgcn_mfma_f32_16x16x32_bf16(Btf[n][k], At[m][k], acc[ai][bj][m][n], 0, 0, 0); \
;     __builtin_amdgcn_s_setprio(0); } while (0)
; #define WAIT_L(n) asm volatile("s_waitcnt lgkmcnt(" #n ")" ::: "memory")
; #define BAR __builtin_amdgcn_s_barrier()
; template <bool OVL, bool PANEL = false, class Epi>
; __device__ __forceinline__ void gemm_phase(const bf16_t* __restrict__ A, long lda, const bf16_t* __restrict__ Bt, long ldb, int nM, int nN, int K,
;                                            const Epi& epi, bf16_t* shm, int w0) {
;     ...
;       LDA(At, 1, 1); BAR; WAIT_L(0); MMA(1, 0, At, B0); MMA(1, 1, At, B1); BAR; }
	s_waitcnt lgkmcnt(0)
	v_mfma_f32_16x16x32_bf16 v[22:25], v[178:181], v[86:89], v[58:61]
	v_mfma_f32_16x16x32_bf16 v[26:29], v[178:181], v[94:97], v[198:201]
	v_mfma_f32_16x16x32_bf16 v[18:21], v[34:37], v[86:89], v[194:197]
	v_mfma_f32_16x16x32_bf16 v[50:53], v[182:185], v[90:93], v[22:25]
	v_mfma_f32_16x16x32_bf16 v[22:25], v[34:37], v[94:97], v[54:57]
	v_mfma_f32_16x16x32_bf16 v[54:57], v[182:185], v[118:121], v[26:29]
	v_mfma_f32_16x16x32_bf16 v[26:29], v[34:37], v[150:153], v[214:217]
	v_mfma_f32_16x16x32_bf16 v[58:61], v[178:181], v[150:153], v[218:221]
	v_mfma_f32_16x16x32_bf16 v[34:37], v[34:37], v[186:189], v[130:133]
	v_mfma_f32_16x16x32_bf16 v[66:69], v[178:181], v[186:189], v[138:141]
	v_mfma_f32_16x16x32_bf16 v[18:21], v[174:177], v[90:93], v[18:21]
	v_mfma_f32_16x16x32_bf16 v[22:25], v[174:177], v[118:121], v[22:25]
	v_mfma_f32_16x16x32_bf16 v[26:29], v[174:177], v[154:157], v[26:29]
	v_mfma_f32_16x16x32_bf16 v[58:61], v[182:185], v[154:157], v[58:61]
	v_mfma_f32_16x16x32_bf16 v[34:37], v[174:177], v[190:193], v[34:37]
	v_mfma_f32_16x16x32_bf16 v[66:69], v[182:185], v[190:193], v[66:69]


; #define LDA(dst, b, h) for (int m = 0; m < 4; ++m) for (int k = 0; k < 2; ++k) \
;     dst[m][k] = *reinterpret_cast<const bf16x8*>((char*)SA(b, h) + a_thr + (m * 2 + k) * 1024)
; #define MMA(ai, bj, At, Btf) do { __builtin_amdgcn_s_setprio(1); \
;     for (int m = 0; m < 4; ++m) for (int n = 0; n < 2; ++n) for (int k = 0; k < 2; ++k) \
;       acc[ai][bj][m][n] = __builtin_amdgcn_mfma_f32_16x16x32_bf16(Btf[n][k], At[m][k], acc[ai][bj][m][n], 0, 0, 0); \
;     __builtin_amdgcn_s_setprio(0); } while (0)
; #define WAIT_L(n) asm volatile("s_waitcnt lgkmcnt(" #n ")" ::: "memory")
; #define BAR __builtin_amdgcn_s_barrier()
; template <bool OVL, bool PANEL = false, class Epi>
; __device__ __forceinline__ void gemm_phase(const bf16_t* __restrict__ A, long lda, const bf16_t* __restrict__ Bt, long ldb, int nM, int nN, int K,
;                                            const Epi& epi, bf16_t* shm, int w0) {
;     ...
;       LDA(At, 1, 1); BAR; WAIT_L(0); MMA(1, 0, At, B0); MMA(1, 1, At, B1); BAR; }
	v_mfma_f32_16x16x32_bf16 v[82:85], v[102:105], v[86:89], v[142:145]
	v_mfma_f32_16x16x32_bf16 v[86:89], v[240:243], v[86:89], v[146:149]
	v_mfma_f32_16x16x32_bf16 v[82:85], v[236:239], v[90:93], v[82:85]
	v_mfma_f32_16x16x32_bf16 v[122:125], v[244:247], v[90:93], v[86:89]
	v_mfma_f32_16x16x32_bf16 v[86:89], v[102:105], v[94:97], v[222:225]
	v_mfma_f32_16x16x32_bf16 v[90:93], v[240:243], v[94:97], v[158:161]
	v_mfma_f32_16x16x32_bf16 v[94:97], v[240:243], v[150:153], v[166:169]
	v_mfma_f32_16x16x32_bf16 v[86:89], v[236:239], v[118:121], v[86:89]
	v_mfma_f32_16x16x32_bf16 v[126:129], v[244:247], v[118:121], v[90:93]
	v_mfma_f32_16x16x32_bf16 v[118:121], v[244:247], v[154:157], v[94:97]
	v_mfma_f32_16x16x32_bf16 v[94:97], v[102:105], v[186:189], v[134:137]
	v_mfma_f32_16x16x32_bf16 v[90:93], v[102:105], v[150:153], v[162:165]
	v_mfma_f32_16x16x32_bf16 v[102:105], v[236:239], v[190:193], v[94:97]
	v_mfma_f32_16x16x32_bf16 v[94:97], v[240:243], v[186:189], v[170:173]
	v_mfma_f32_16x16x32_bf16 v[90:93], v[236:239], v[154:157], v[90:93]
	v_mfma_f32_16x16x32_bf16 v[94:97], v[244:247], v[190:193], v[94:97]

; #define LDA(dst, b, h) for (int m = 0; m < 4; ++m) for (int k = 0; k < 2; ++k) \
;     dst[m][k] = *reinterpret_cast<const bf16x8*>((char*)SA(b, h) + a_thr + (m * 2 + k) * 1024)
; #define MMA(ai, bj, At, Btf) do { __builtin_amdgcn_s_setprio(1); \
;     for (int m = 0; m < 4; ++m) for (int n = 0; n < 2; ++n) for (int k = 0; k < 2; ++k) \
;       acc[ai][bj][m][n] = __builtin_amdgcn_mfma_f32_16x16x32_bf16(Btf[n][k], At[m][k], acc[ai][bj][m][n], 0, 0, 0); \
;     __builtin_amdgcn_s_setprio(0); } while (0)
; #define WAIT_L(n) asm volatile("s_waitcnt lgkmcnt(" #n ")" ::: "memory")
; #define BAR __builtin_amdgcn_s_barrier()
; template <bool OVL, bool PANEL = false, class Epi>
; __device__ __forceinline__ void gemm_phase(const bf16_t* __restrict__ A, long lda, const bf16_t* __restrict__ Bt, long ldb, int nM, int nN, int K,
;                                            const Epi& epi, bf16_t* shm, int w0) {
;     ...
;       LDA(At, 1, 1); BAR; WAIT_L(0); MMA(1, 0, At, B0); MMA(1, 1, At, B1); BAR; }
;     if (wr == 0) BAR;
	s_barrier
	s_and_saveexec_b64 s[0:1], s[58:59]
	s_cbranch_execz .LBB0_128
	s_barrier

; #define LDA(dst, b, h) for (int m = 0; m < 4; ++m) for (int k = 0; k < 2; ++k) \
;     dst[m][k] = *reinterpret_cast<const bf16x8*>((char*)SA(b, h) + a_thr + (m * 2 + k) * 1024)
; #define LDB(dst, b, h) for (int n = 0; n < 2; ++n) for (int k = 0; k < 2; ++k) \
;     dst[n][k] = *reinterpret_cast<const bf16x8*>((char*)SB(b, h) + b_thr + (n * 2 + k) * 1024)
; #define MMA(ai, bj, At, Btf) do { __builtin_amdgcn_s_setprio(1); \
;     for (int m = 0; m < 4; ++m) for (int n = 0; n < 2; ++n) for (int k = 0; k < 2; ++k) \
;       acc[ai][bj][m][n] = __builtin_amdgcn_mfma_f32_16x16x32_bf16(Btf[n][k], At[m][k], acc[ai][bj][m][n], 0, 0, 0); \
;     __builtin_amdgcn_s_setprio(0); } while (0)
; #define WAIT_V(n) asm volatile("s_waitcnt vmcnt(" #n ")" ::: "memory")
; #define WAIT_L(n) asm volatile("s_waitcnt lgkmcnt(" #n ")" ::: "memory")
; #define BAR __builtin_amdgcn_s_barrier()
; #define SCHED __builtin_amdgcn_sched_barrier(0)
; template <bool OVL, bool PANEL = false, class Epi>
; __device__ __forceinline__ void gemm_phase(const bf16_t* __restrict__ A, long lda, const bf16_t* __restrict__ Bt, long ldb, int nM, int nN, int K,
;                                            const Epi& epi, bf16_t* shm, int w0) {
;     ...
;       LDB(B0, 0, 0); SCHED; LDA(At, 0, 0); STAGE(SA(1, 1), A, lda, aoff, brow + HALF, t + 1);
;       WAIT_L(8); BAR; WAIT_L(0); MMA(0, 0, At, B0); BAR; SCHED;
;       LDB(B1, 0, 1); STAGE(SB(0, 0), Bt, ldb, boff, bcol, t + 2);
;       BAR; WAIT_L(0); MMA(0, 1, At, B1); BAR;
;       LDA(At, 0, 1); STAGE(SA(0, 0), A, lda, aoff, brow, t + 2);
;       BAR; WAIT_L(0); MMA(1, 0, At, B0); BAR; SCHED;
;       STAGE(SB(0, 1), Bt, ldb, boff, bcol + HALF, t + 2);
;       WAIT_V(6); BAR; MMA(1, 1, At, B1); BAR;
.LBB0_386:
	ds_read_b128 v[150:153], v218
	ds_read_b128 v[154:157], v218 offset:1024
	ds_read_b128 v[158:161], v218 offset:2048
	ds_read_b128 v[162:165], v218 offset:3072
	s_add_u32 s42, s10, vcc_lo
	s_addc_u32 s43, s11, vcc_hi
	ds_read_b128 v[166:169], v141
	ds_read_b128 v[170:173], v141 offset:1024
	ds_read_b128 v[174:177], v141 offset:2048
	ds_read_b128 v[178:181], v141 offset:3072
	ds_read_b128 v[182:185], v141 offset:4096
	ds_read_b128 v[186:189], v141 offset:5120
	ds_read_b128 v[190:193], v141 offset:6144
	ds_read_b128 v[194:197], v141 offset:7168
	s_mov_b32 m0, s16
	s_add_u32 s98, s42, s28
	s_addc_u32 s99, s43, s29
	global_load_lds_dwordx4 v131, s[98:99]
	s_mov_b32 m0, s32
	s_add_u32 s98, s42, s36
	s_addc_u32 s99, s43, s37
	global_load_lds_dwordx4 v131, s[98:99]
	s_waitcnt lgkmcnt(0)
	s_waitcnt vmcnt(10)
	s_barrier
	v_mfma_f32_16x16x32_bf16 v[126:129], v[150:153], v[166:169], v[126:129]
	v_mfma_f32_16x16x32_bf16 v[122:125], v[158:161], v[166:169], v[122:125]
	v_mfma_f32_16x16x32_bf16 v[118:121], v[150:153], v[174:177], v[118:121]
	v_mfma_f32_16x16x32_bf16 v[114:117], v[158:161], v[174:177], v[114:117]
	v_mfma_f32_16x16x32_bf16 v[110:113], v[150:153], v[182:185], v[110:113]
	v_mfma_f32_16x16x32_bf16 v[106:109], v[158:161], v[182:185], v[106:109]
	v_mfma_f32_16x16x32_bf16 v[102:105], v[150:153], v[190:193], v[102:105]
	v_mfma_f32_16x16x32_bf16 v[98:101], v[158:161], v[190:193], v[98:101]
	v_mfma_f32_16x16x32_bf16 v[126:129], v[154:157], v[170:173], v[126:129]
	v_mfma_f32_16x16x32_bf16 v[122:125], v[162:165], v[170:173], v[122:125]
	v_mfma_f32_16x16x32_bf16 v[118:121], v[154:157], v[178:181], v[118:121]
	v_mfma_f32_16x16x32_bf16 v[114:117], v[162:165], v[178:181], v[114:117]
	v_mfma_f32_16x16x32_bf16 v[110:113], v[154:157], v[186:189], v[110:113]
	v_mfma_f32_16x16x32_bf16 v[106:109], v[162:165], v[186:189], v[106:109]
	v_mfma_f32_16x16x32_bf16 v[102:105], v[154:157], v[194:197], v[102:105]
	v_mfma_f32_16x16x32_bf16 v[98:101], v[162:165], v[194:197], v[98:101]
	s_barrier
	s_add_u32 s66, s8, vcc_lo
	ds_read_b128 v[198:201], v219
	ds_read_b128 v[202:205], v219 offset:1024
	ds_read_b128 v[206:209], v219 offset:2048
	ds_read_b128 v[210:213], v219 offset:3072
	s_addc_u32 s67, s9, vcc_hi
	s_mov_b32 m0, s46
	s_add_u32 s98, s66, s34
	s_addc_u32 s99, s67, s35
	global_load_lds_dwordx4 v131, s[98:99]
	s_mov_b32 m0, s47
	s_add_u32 s98, s66, s64
	s_addc_u32 s99, s67, s65
	global_load_lds_dwordx4 v131, s[98:99]
	s_waitcnt lgkmcnt(0)
	s_waitcnt vmcnt(10)
	s_barrier
	v_mfma_f32_16x16x32_bf16 v[94:97], v[198:201], v[166:169], v[94:97]
	v_mfma_f32_16x16x32_bf16 v[90:93], v[206:209], v[166:169], v[90:93]
	v_mfma_f32_16x16x32_bf16 v[86:89], v[198:201], v[174:177], v[86:89]
	v_mfma_f32_16x16x32_bf16 v[82:85], v[206:209], v[174:177], v[82:85]
	v_mfma_f32_16x16x32_bf16 v[78:81], v[198:201], v[182:185], v[78:81]
	v_mfma_f32_16x16x32_bf16 v[74:77], v[206:209], v[182:185], v[74:77]
	v_mfma_f32_16x16x32_bf16 v[70:73], v[198:201], v[190:193], v[70:73]
	v_mfma_f32_16x16x32_bf16 v[66:69], v[206:209], v[190:193], v[66:69]
	v_mfma_f32_16x16x32_bf16 v[94:97], v[202:205], v[170:173], v[94:97]
	v_mfma_f32_16x16x32_bf16 v[90:93], v[210:213], v[170:173], v[90:93]
	v_mfma_f32_16x16x32_bf16 v[86:89], v[202:205], v[178:181], v[86:89]
	v_mfma_f32_16x16x32_bf16 v[82:85], v[210:213], v[178:181], v[82:85]
	v_mfma_f32_16x16x32_bf16 v[78:81], v[202:205], v[186:189], v[78:81]
	v_mfma_f32_16x16x32_bf16 v[74:77], v[210:213], v[186:189], v[74:77]
	v_mfma_f32_16x16x32_bf16 v[70:73], v[202:205], v[194:197], v[70:73]
	v_mfma_f32_16x16x32_bf16 v[66:69], v[210:213], v[194:197], v[66:69]
	s_barrier
	ds_read_b128 v[166:169], v141 offset:16384
	ds_read_b128 v[170:173], v141 offset:17408
	ds_read_b128 v[174:177], v141 offset:18432
	ds_read_b128 v[178:181], v141 offset:19456
	ds_read_b128 v[182:185], v141 offset:20480
	ds_read_b128 v[186:189], v141 offset:21504
	ds_read_b128 v[190:193], v141 offset:22528
	ds_read_b128 v[194:197], v141 offset:23552
	s_mov_b32 m0, s48
	s_add_u32 s98, s42, s34
	s_addc_u32 s99, s43, s35
	global_load_lds_dwordx4 v131, s[98:99]
	s_mov_b32 m0, s49
	s_add_u32 s98, s42, s64
	s_addc_u32 s99, s43, s65
	global_load_lds_dwordx4 v131, s[98:99]
	s_waitcnt lgkmcnt(0)
	s_barrier
	v_mfma_f32_16x16x32_bf16 v[62:65], v[150:153], v[166:169], v[62:65]
	v_mfma_f32_16x16x32_bf16 v[58:61], v[158:161], v[166:169], v[58:61]
	v_mfma_f32_16x16x32_bf16 v[54:57], v[150:153], v[174:177], v[54:57]
	v_mfma_f32_16x16x32_bf16 v[50:53], v[158:161], v[174:177], v[50:53]
	v_mfma_f32_16x16x32_bf16 v[46:49], v[150:153], v[182:185], v[46:49]
	v_mfma_f32_16x16x32_bf16 v[42:45], v[158:161], v[182:185], v[42:45]
	v_mfma_f32_16x16x32_bf16 v[38:41], v[150:153], v[190:193], v[38:41]
	v_mfma_f32_16x16x32_bf16 v[34:37], v[158:161], v[190:193], v[34:37]
	v_mfma_f32_16x16x32_bf16 v[62:65], v[154:157], v[170:173], v[62:65]
	v_mfma_f32_16x16x32_bf16 v[58:61], v[162:165], v[170:173], v[58:61]
	v_mfma_f32_16x16x32_bf16 v[54:57], v[154:157], v[178:181], v[54:57]
	v_mfma_f32_16x16x32_bf16 v[50:53], v[162:165], v[178:181], v[50:53]
	v_mfma_f32_16x16x32_bf16 v[46:49], v[154:157], v[186:189], v[46:49]
	v_mfma_f32_16x16x32_bf16 v[42:45], v[162:165], v[186:189], v[42:45]
	v_mfma_f32_16x16x32_bf16 v[38:41], v[154:157], v[194:197], v[38:41]
	v_mfma_f32_16x16x32_bf16 v[34:37], v[162:165], v[194:197], v[34:37]
	s_barrier
	s_mov_b32 m0, s50
	s_add_u32 s98, s66, s68
	s_addc_u32 s99, s67, s69
	global_load_lds_dwordx4 v131, s[98:99]
	s_mov_b32 m0, s51
	s_add_u32 s98, s66, s70
	s_addc_u32 s99, s67, s71
	global_load_lds_dwordx4 v131, s[98:99]
	s_waitcnt vmcnt(10)
	s_barrier
; #define LDA(dst, b, h) for (int m = 0; m < 4; ++m) for (int k = 0; k < 2; ++k) \
;     dst[m][k] = *reinterpret_cast<const bf16x8*>((char*)SA(b, h) + a_thr + (m * 2 + k) * 1024)
; #define LDB(dst, b, h) for (int n = 0; n < 2; ++n) for (int k = 0; k < 2; ++k) \
;     dst[n][k] = *reinterpret_cast<const bf16x8*>((char*)SB(b, h) + b_thr + (n * 2 + k) * 1024)
; #define MMA(ai, bj, At, Btf) do { __builtin_amdgcn_s_setprio(1); \
;     for (int m = 0; m < 4; ++m) for (int n = 0; n < 2; ++n) for (int k = 0; k < 2; ++k) \
;       acc[ai][bj][m][n] = __builtin_amdgcn_mfma_f32_16x16x32_bf16(Btf[n][k], At[m][k], acc[ai][bj][m][n], 0, 0, 0); \
;     __builtin_amdgcn_s_setprio(0); } while (0)
; #define WAIT_V(n) asm volatile("s_waitcnt vmcnt(" #n ")" ::: "memory")
; #define WAIT_L(n) asm volatile("s_waitcnt lgkmcnt(" #n ")" ::: "memory")
; #define BAR __builtin_amdgcn_s_barrier()
; #define SCHED __builtin_amdgcn_sched_barrier(0)
; template <bool OVL, bool PANEL = false, class Epi>
; __device__ __forceinline__ void gemm_phase(const bf16_t* __restrict__ A, long lda, const bf16_t* __restrict__ Bt, long ldb, int nM, int nN, int K,
;                                            const Epi& epi, bf16_t* shm, int w0) {
;     ...
;       WAIT_V(6); BAR; MMA(1, 1, At, B1); BAR;
;       LDB(B0, 1, 0); SCHED; LDA(At, 1, 0); STAGE(SA(0, 1), A, lda, aoff, brow + HALF, t + 2);
;       WAIT_L(8); BAR; WAIT_L(0); MMA(0, 0, At, B0); BAR; SCHED;
;       LDB(B1, 1, 1); STAGE(SB(1, 0), Bt, ldb, boff, bcol, t + 3);
;       BAR; WAIT_L(0); MMA(0, 1, At, B1); BAR;
	v_mfma_f32_16x16x32_bf16 v[30:33], v[198:201], v[166:169], v[30:33]
	v_mfma_f32_16x16x32_bf16 v[26:29], v[206:209], v[166:169], v[26:29]
	v_mfma_f32_16x16x32_bf16 v[22:25], v[198:201], v[174:177], v[22:25]
	v_mfma_f32_16x16x32_bf16 v[18:21], v[206:209], v[174:177], v[18:21]
	v_mfma_f32_16x16x32_bf16 v[14:17], v[198:201], v[182:185], v[14:17]
	v_mfma_f32_16x16x32_bf16 v[10:13], v[206:209], v[182:185], v[10:13]
	v_mfma_f32_16x16x32_bf16 v[6:9], v[198:201], v[190:193], v[6:9]
	v_mfma_f32_16x16x32_bf16 v[2:5], v[206:209], v[190:193], v[2:5]
	v_mfma_f32_16x16x32_bf16 v[30:33], v[202:205], v[170:173], v[30:33]
	v_mfma_f32_16x16x32_bf16 v[26:29], v[210:213], v[170:173], v[26:29]
	v_mfma_f32_16x16x32_bf16 v[22:25], v[202:205], v[178:181], v[22:25]
	v_mfma_f32_16x16x32_bf16 v[18:21], v[210:213], v[178:181], v[18:21]
	v_mfma_f32_16x16x32_bf16 v[14:17], v[202:205], v[186:189], v[14:17]
	v_mfma_f32_16x16x32_bf16 v[10:13], v[210:213], v[186:189], v[10:13]
	v_mfma_f32_16x16x32_bf16 v[6:9], v[202:205], v[194:197], v[6:9]
	v_mfma_f32_16x16x32_bf16 v[2:5], v[210:213], v[194:197], v[2:5]
	s_barrier
	ds_read_b128 v[150:153], v220
	ds_read_b128 v[154:157], v220 offset:1024
	ds_read_b128 v[158:161], v220 offset:2048
	ds_read_b128 v[162:165], v220 offset:3072
	ds_read_b128 v[166:169], v141 offset:32768
	ds_read_b128 v[170:173], v141 offset:33792
	ds_read_b128 v[174:177], v141 offset:34816
	ds_read_b128 v[178:181], v141 offset:35840
	ds_read_b128 v[182:185], v141 offset:36864
	ds_read_b128 v[186:189], v141 offset:37888
	ds_read_b128 v[190:193], v141 offset:38912
	ds_read_b128 v[194:197], v141 offset:39936
	s_mov_b32 m0, s52
	s_add_u32 s98, s42, s68
	s_addc_u32 s99, s43, s69
	global_load_lds_dwordx4 v131, s[98:99]
	s_mov_b32 m0, s53
	s_add_u32 s98, s42, s70
	s_addc_u32 s99, s43, s71
	global_load_lds_dwordx4 v131, s[98:99]
	s_waitcnt lgkmcnt(0)
	s_waitcnt vmcnt(10)
	s_barrier
	v_mfma_f32_16x16x32_bf16 v[126:129], v[150:153], v[166:169], v[126:129]
	v_mfma_f32_16x16x32_bf16 v[122:125], v[158:161], v[166:169], v[122:125]
	v_mfma_f32_16x16x32_bf16 v[118:121], v[150:153], v[174:177], v[118:121]
	v_mfma_f32_16x16x32_bf16 v[114:117], v[158:161], v[174:177], v[114:117]
	v_mfma_f32_16x16x32_bf16 v[110:113], v[150:153], v[182:185], v[110:113]
	v_mfma_f32_16x16x32_bf16 v[106:109], v[158:161], v[182:185], v[106:109]
	v_mfma_f32_16x16x32_bf16 v[102:105], v[150:153], v[190:193], v[102:105]
	v_mfma_f32_16x16x32_bf16 v[98:101], v[158:161], v[190:193], v[98:101]
	v_mfma_f32_16x16x32_bf16 v[126:129], v[154:157], v[170:173], v[126:129]
	v_mfma_f32_16x16x32_bf16 v[122:125], v[162:165], v[170:173], v[122:125]
	v_mfma_f32_16x16x32_bf16 v[118:121], v[154:157], v[178:181], v[118:121]
	v_mfma_f32_16x16x32_bf16 v[114:117], v[162:165], v[178:181], v[114:117]
	v_mfma_f32_16x16x32_bf16 v[110:113], v[154:157], v[186:189], v[110:113]
	v_mfma_f32_16x16x32_bf16 v[106:109], v[162:165], v[186:189], v[106:109]
	v_mfma_f32_16x16x32_bf16 v[102:105], v[154:157], v[194:197], v[102:105]
	v_mfma_f32_16x16x32_bf16 v[98:101], v[162:165], v[194:197], v[98:101]
	s_barrier
	ds_read_b128 v[198:201], v221
	ds_read_b128 v[202:205], v221 offset:1024
	ds_read_b128 v[206:209], v221 offset:2048
	ds_read_b128 v[210:213], v221 offset:3072
	s_mov_b32 m0, s54
	s_add_u32 s98, s66, s94
	s_addc_u32 s99, s67, s95
	global_load_lds_dwordx4 v131, s[98:99]
	s_mov_b32 m0, s55
	s_add_u32 s98, s66, s72
	s_addc_u32 s99, s67, s73
	global_load_lds_dwordx4 v131, s[98:99]
	s_waitcnt lgkmcnt(0)
	s_waitcnt vmcnt(10)
	s_barrier
	v_mfma_f32_16x16x32_bf16 v[94:97], v[198:201], v[166:169], v[94:97]
	v_mfma_f32_16x16x32_bf16 v[90:93], v[206:209], v[166:169], v[90:93]
	v_mfma_f32_16x16x32_bf16 v[86:89], v[198:201], v[174:177], v[86:89]
	v_mfma_f32_16x16x32_bf16 v[82:85], v[206:209], v[174:177], v[82:85]
	v_mfma_f32_16x16x32_bf16 v[78:81], v[198:201], v[182:185], v[78:81]
	v_mfma_f32_16x16x32_bf16 v[74:77], v[206:209], v[182:185], v[74:77]
	v_mfma_f32_16x16x32_bf16 v[70:73], v[198:201], v[190:193], v[70:73]
	v_mfma_f32_16x16x32_bf16 v[66:69], v[206:209], v[190:193], v[66:69]
	v_mfma_f32_16x16x32_bf16 v[94:97], v[202:205], v[170:173], v[94:97]
	v_mfma_f32_16x16x32_bf16 v[90:93], v[210:213], v[170:173], v[90:93]
	v_mfma_f32_16x16x32_bf16 v[86:89], v[202:205], v[178:181], v[86:89]
	v_mfma_f32_16x16x32_bf16 v[82:85], v[210:213], v[178:181], v[82:85]
	v_mfma_f32_16x16x32_bf16 v[78:81], v[202:205], v[186:189], v[78:81]
	v_mfma_f32_16x16x32_bf16 v[74:77], v[210:213], v[186:189], v[74:77]
	v_mfma_f32_16x16x32_bf16 v[70:73], v[202:205], v[194:197], v[70:73]
	v_mfma_f32_16x16x32_bf16 v[66:69], v[210:213], v[194:197], v[66:69]
	s_barrier
; #define LDA(dst, b, h) for (int m = 0; m < 4; ++m) for (int k = 0; k < 2; ++k) \
;     dst[m][k] = *reinterpret_cast<const bf16x8*>((char*)SA(b, h) + a_thr + (m * 2 + k) * 1024)
; #define LDB(dst, b, h) for (int n = 0; n < 2; ++n) for (int k = 0; k < 2; ++k) \
;     dst[n][k] = *reinterpret_cast<const bf16x8*>((char*)SB(b, h) + b_thr + (n * 2 + k) * 1024)
; #define MMA(ai, bj, At, Btf) do { __builtin_amdgcn_s_setprio(1); \
;     for (int m = 0; m < 4; ++m) for (int n = 0; n < 2; ++n) for (int k = 0; k < 2; ++k) \
;       acc[ai][bj][m][n] = __builtin_amdgcn_mfma_f32_16x16x32_bf16(Btf[n][k], At[m][k], acc[ai][bj][m][n], 0, 0, 0); \
;     __builtin_amdgcn_s_setprio(0); } while (0)
; #define WAIT_V(n) asm volatile("s_waitcnt vmcnt(" #n ")" ::: "memory")
; #define WAIT_L(n) asm volatile("s_waitcnt lgkmcnt(" #n ")" ::: "memory")
; #define BAR __builtin_amdgcn_s_barrier()
; #define SCHED __builtin_amdgcn_sched_barrier(0)
; template <bool OVL, bool PANEL = false, class Epi>
; __device__ __forceinline__ void gemm_phase(const bf16_t* __restrict__ A, long lda, const bf16_t* __restrict__ Bt, long ldb, int nM, int nN, int K,
;                                            const Epi& epi, bf16_t* shm, int w0) {
;     ...
;       LDA(At, 1, 1); STAGE(SA(1, 0), A, lda, aoff, brow, t + 3);
;       BAR; WAIT_L(0); MMA(1, 0, At, B0); BAR; SCHED;
;       STAGE(SB(1, 1), Bt, ldb, boff, bcol + HALF, t + 3);
;       WAIT_V(6); BAR; MMA(1, 1, At, B1); BAR;
;     }
;     { LDB(B0, 0, 0); LDA(At, 0, 0); STAGE(SA(1, 1), A, lda, aoff, brow + HALF, nt - 1);
	ds_read_b128 v[166:169], v141 offset:49152
	ds_read_b128 v[170:173], v141 offset:50176
	ds_read_b128 v[174:177], v141 offset:51200
	ds_read_b128 v[178:181], v141 offset:52224
	ds_read_b128 v[182:185], v141 offset:53248
	ds_read_b128 v[186:189], v141 offset:54272
	ds_read_b128 v[190:193], v141 offset:55296
	ds_read_b128 v[194:197], v141 offset:56320
	s_mov_b32 m0, s56
	s_add_u32 s98, s42, s94
	s_addc_u32 s99, s43, s95
	global_load_lds_dwordx4 v131, s[98:99]
	s_mov_b32 m0, s57
	s_add_u32 s98, s42, s72
	s_addc_u32 s99, s43, s73
	global_load_lds_dwordx4 v131, s[98:99]
	s_waitcnt lgkmcnt(0)
	s_barrier
	v_mfma_f32_16x16x32_bf16 v[62:65], v[150:153], v[166:169], v[62:65]
	v_mfma_f32_16x16x32_bf16 v[58:61], v[158:161], v[166:169], v[58:61]
	v_mfma_f32_16x16x32_bf16 v[54:57], v[150:153], v[174:177], v[54:57]
	v_mfma_f32_16x16x32_bf16 v[50:53], v[158:161], v[174:177], v[50:53]
	v_mfma_f32_16x16x32_bf16 v[46:49], v[150:153], v[182:185], v[46:49]
	v_mfma_f32_16x16x32_bf16 v[42:45], v[158:161], v[182:185], v[42:45]
	v_mfma_f32_16x16x32_bf16 v[38:41], v[150:153], v[190:193], v[38:41]
	v_mfma_f32_16x16x32_bf16 v[34:37], v[158:161], v[190:193], v[34:37]
	v_mfma_f32_16x16x32_bf16 v[62:65], v[154:157], v[170:173], v[62:65]
	v_mfma_f32_16x16x32_bf16 v[58:61], v[162:165], v[170:173], v[58:61]
	v_mfma_f32_16x16x32_bf16 v[54:57], v[154:157], v[178:181], v[54:57]
	v_mfma_f32_16x16x32_bf16 v[50:53], v[162:165], v[178:181], v[50:53]
	v_mfma_f32_16x16x32_bf16 v[46:49], v[154:157], v[186:189], v[46:49]
	v_mfma_f32_16x16x32_bf16 v[42:45], v[162:165], v[186:189], v[42:45]
	v_mfma_f32_16x16x32_bf16 v[38:41], v[154:157], v[194:197], v[38:41]
	v_mfma_f32_16x16x32_bf16 v[34:37], v[162:165], v[194:197], v[34:37]
	s_barrier
	s_mov_b32 m0, s58
	s_add_u32 s98, s66, s30
	s_addc_u32 s99, s67, s31
	global_load_lds_dwordx4 v131, s[98:99]
	s_mov_b32 m0, s59
	s_add_u32 s98, s66, s44
	s_addc_u32 s99, s67, s45
	global_load_lds_dwordx4 v131, s[98:99]
	s_add_i32 s18, s18, 2
	s_add_u32 vcc_lo, vcc_lo, 0x100
	s_addc_u32 vcc_hi, vcc_hi, 0
	s_cmp_lt_u32 s18, 12
	s_waitcnt vmcnt(10)
	s_barrier
	v_mfma_f32_16x16x32_bf16 v[30:33], v[198:201], v[166:169], v[30:33]
	v_mfma_f32_16x16x32_bf16 v[26:29], v[206:209], v[166:169], v[26:29]
	v_mfma_f32_16x16x32_bf16 v[22:25], v[198:201], v[174:177], v[22:25]
	v_mfma_f32_16x16x32_bf16 v[18:21], v[206:209], v[174:177], v[18:21]
	v_mfma_f32_16x16x32_bf16 v[14:17], v[198:201], v[182:185], v[14:17]
	v_mfma_f32_16x16x32_bf16 v[10:13], v[206:209], v[182:185], v[10:13]
	v_mfma_f32_16x16x32_bf16 v[6:9], v[198:201], v[190:193], v[6:9]
	v_mfma_f32_16x16x32_bf16 v[2:5], v[206:209], v[190:193], v[2:5]
	v_mfma_f32_16x16x32_bf16 v[30:33], v[202:205], v[170:173], v[30:33]
	v_mfma_f32_16x16x32_bf16 v[26:29], v[210:213], v[170:173], v[26:29]
	v_mfma_f32_16x16x32_bf16 v[22:25], v[202:205], v[178:181], v[22:25]
	v_mfma_f32_16x16x32_bf16 v[18:21], v[210:213], v[178:181], v[18:21]
	v_mfma_f32_16x16x32_bf16 v[14:17], v[202:205], v[186:189], v[14:17]
	v_mfma_f32_16x16x32_bf16 v[10:13], v[210:213], v[186:189], v[10:13]
	v_mfma_f32_16x16x32_bf16 v[6:9], v[202:205], v[194:197], v[6:9]
	v_mfma_f32_16x16x32_bf16 v[2:5], v[210:213], v[194:197], v[2:5]
	s_barrier
	s_cbranch_scc1 .LBB0_386
	s_waitcnt vmcnt(6)
	s_or_b32 s8, s2, 0x80
	s_mov_b32 s9, s3
	v_readlane_b32 s44, v252, 20
	s_lshl_b64 s[8:9], s[8:9], 11
	v_readlane_b32 s50, v252, 26
	v_add_u32_e32 v214, 16, v140
	v_readlane_b32 s51, v252, 27
	s_add_u32 s8, s50, s8
	v_add_u32_e32 v0, 0x10000, v214
	s_addc_u32 s9, s51, s9
	ds_read_b128 v[142:145], v0
	ds_read_b128 v[150:153], v0 offset:1024
	ds_read_b128 v[154:157], v0 offset:2048
	ds_read_b128 v[158:161], v0 offset:3072
	ds_read_b128 v[162:165], v141
	ds_read_b128 v[166:169], v141 offset:1024
	ds_read_b128 v[170:173], v141 offset:2048
	ds_read_b128 v[174:177], v141 offset:3072
	ds_read_b128 v[178:181], v141 offset:4096
	ds_read_b128 v[182:185], v141 offset:5120
	ds_read_b128 v[186:189], v141 offset:6144
	ds_read_b128 v[190:193], v141 offset:7168
	v_mov_b32_e32 v0, v131
	v_readlane_b32 s45, v252, 21
	v_lshl_add_u64 v[146:147], s[8:9], 0, v[0:1]
	s_mov_b64 s[8:9], 0x780
	v_lshl_add_u64 v[194:195], v[146:147], 0, s[8:9]
	v_readfirstlane_b32 s8, v148
	s_mov_b32 m0, s8
	s_mov_b64 s[8:9], 0x20780
	v_lshl_add_u64 v[146:147], v[146:147], 0, s[8:9]
	v_readfirstlane_b32 s8, v149
	global_load_lds_dwordx4 v[194:195], off
	s_mov_b32 m0, s8
	v_readlane_b32 s46, v252, 22
	global_load_lds_dwordx4 v[146:147], off
	s_barrier
	s_waitcnt lgkmcnt(0)
	v_readlane_b32 s47, v252, 23
	v_readlane_b32 s48, v252, 24
	v_readlane_b32 s49, v252, 25
	v_readlane_b32 s52, v252, 28
	v_readlane_b32 s53, v252, 29
	v_readlane_b32 s54, v252, 30
	v_readlane_b32 s55, v252, 31
	v_readlane_b32 s56, v252, 32
	v_readlane_b32 s57, v252, 33
	v_readlane_b32 s58, v252, 34
	v_readlane_b32 s59, v252, 35

; #define MMA(ai, bj, At, Btf) do { __builtin_amdgcn_s_setprio(1); \
;     for (int m = 0; m < 4; ++m) for (int n = 0; n < 2; ++n) for (int k = 0; k < 2; ++k) \
;       acc[ai][bj][m][n] = __builtin_amdgcn_mfma_f32_16x16x32_bf16(Btf[n][k], At[m][k], acc[ai][bj][m][n], 0, 0, 0); \
;     __builtin_amdgcn_s_setprio(0); } while (0)
; #define WAIT_L(n) asm volatile("s_waitcnt lgkmcnt(" #n ")" ::: "memory")
; #define BAR __builtin_amdgcn_s_barrier()
; template <bool OVL, bool PANEL = false, class Epi>
; __device__ __forceinline__ void gemm_phase(const bf16_t* __restrict__ A, long lda, const bf16_t* __restrict__ Bt, long ldb, int nM, int nN, int K,
;                                            const Epi& epi, bf16_t* shm, int w0) {
;     ...
;       BAR; WAIT_L(0); MMA(0, 0, At, B0); BAR;
	s_waitcnt lgkmcnt(0)
	v_mfma_f32_16x16x32_bf16 v[126:129], v[142:145], v[162:165], v[126:129]
	v_mfma_f32_16x16x32_bf16 v[122:125], v[154:157], v[162:165], v[122:125]
	v_mfma_f32_16x16x32_bf16 v[118:121], v[142:145], v[170:173], v[118:121]
	v_mfma_f32_16x16x32_bf16 v[114:117], v[154:157], v[170:173], v[114:117]
	v_mfma_f32_16x16x32_bf16 v[110:113], v[142:145], v[178:181], v[110:113]
	v_mfma_f32_16x16x32_bf16 v[106:109], v[154:157], v[178:181], v[106:109]
	v_mfma_f32_16x16x32_bf16 v[98:101], v[154:157], v[186:189], v[98:101]
	v_mfma_f32_16x16x32_bf16 v[126:129], v[150:153], v[166:169], v[126:129]
	v_mfma_f32_16x16x32_bf16 v[122:125], v[158:161], v[166:169], v[122:125]
	v_mfma_f32_16x16x32_bf16 v[118:121], v[150:153], v[174:177], v[118:121]
	v_mfma_f32_16x16x32_bf16 v[114:117], v[158:161], v[174:177], v[114:117]
	v_mfma_f32_16x16x32_bf16 v[110:113], v[150:153], v[182:185], v[110:113]
	v_mfma_f32_16x16x32_bf16 v[106:109], v[158:161], v[182:185], v[106:109]
	v_mfma_f32_16x16x32_bf16 v[102:105], v[142:145], v[186:189], v[102:105]
	v_mfma_f32_16x16x32_bf16 v[98:101], v[158:161], v[190:193], v[98:101]
	v_mfma_f32_16x16x32_bf16 v[146:149], v[150:153], v[190:193], v[102:105]

; #define LDB(dst, b, h) for (int n = 0; n < 2; ++n) for (int k = 0; k < 2; ++k) \
;     dst[n][k] = *reinterpret_cast<const bf16x8*>((char*)SB(b, h) + b_thr + (n * 2 + k) * 1024)
; #define MMA(ai, bj, At, Btf) do { __builtin_amdgcn_s_setprio(1); \
;     for (int m = 0; m < 4; ++m) for (int n = 0; n < 2; ++n) for (int k = 0; k < 2; ++k) \
;       acc[ai][bj][m][n] = __builtin_amdgcn_mfma_f32_16x16x32_bf16(Btf[n][k], At[m][k], acc[ai][bj][m][n], 0, 0, 0); \
;     __builtin_amdgcn_s_setprio(0); } while (0)
; #define WAIT_L(n) asm volatile("s_waitcnt lgkmcnt(" #n ")" ::: "memory")
; #define BAR __builtin_amdgcn_s_barrier()
; template <bool OVL, bool PANEL = false, class Epi>
; __device__ __forceinline__ void gemm_phase(const bf16_t* __restrict__ A, long lda, const bf16_t* __restrict__ Bt, long ldb, int nM, int nN, int K,
;                                            const Epi& epi, bf16_t* shm, int w0) {
;     ...
;       LDB(B1, 0, 1); BAR; WAIT_L(0); MMA(0, 1, At, B1); BAR;
	v_add_u32_e32 v0, 0x14000, v214
	s_barrier
	s_nop 2
	ds_read_b128 v[102:105], v0
	ds_read_b128 v[194:197], v0 offset:1024
	ds_read_b128 v[198:201], v0 offset:2048
	ds_read_b128 v[202:205], v0 offset:3072
	s_barrier
	s_waitcnt lgkmcnt(0)

; #define LDB(dst, b, h) for (int n = 0; n < 2; ++n) for (int k = 0; k < 2; ++k) \
;     dst[n][k] = *reinterpret_cast<const bf16x8*>((char*)SB(b, h) + b_thr + (n * 2 + k) * 1024)
; #define MMA(ai, bj, At, Btf) do { __builtin_amdgcn_s_setprio(1); \
;     for (int m = 0; m < 4; ++m) for (int n = 0; n < 2; ++n) for (int k = 0; k < 2; ++k) \
;       acc[ai][bj][m][n] = __builtin_amdgcn_mfma_f32_16x16x32_bf16(Btf[n][k], At[m][k], acc[ai][bj][m][n], 0, 0, 0); \
;     __builtin_amdgcn_s_setprio(0); } while (0)
; #define WAIT_L(n) asm volatile("s_waitcnt lgkmcnt(" #n ")" ::: "memory")
; #define BAR __builtin_amdgcn_s_barrier()
; template <bool OVL, bool PANEL = false, class Epi>
; __device__ __forceinline__ void gemm_phase(const bf16_t* __restrict__ A, long lda, const bf16_t* __restrict__ Bt, long ldb, int nM, int nN, int K,
;                                            const Epi& epi, bf16_t* shm, int w0) {
;     ...
;       LDB(B1, 0, 1); BAR; WAIT_L(0); MMA(0, 1, At, B1); BAR;
	s_waitcnt lgkmcnt(0)
	v_mfma_f32_16x16x32_bf16 v[94:97], v[102:105], v[162:165], v[94:97]
	v_mfma_f32_16x16x32_bf16 v[86:89], v[102:105], v[170:173], v[86:89]
	v_mfma_f32_16x16x32_bf16 v[78:81], v[102:105], v[178:181], v[78:81]
	v_mfma_f32_16x16x32_bf16 v[74:77], v[198:201], v[178:181], v[74:77]
	v_mfma_f32_16x16x32_bf16 v[94:97], v[194:197], v[166:169], v[94:97]
	v_mfma_f32_16x16x32_bf16 v[90:93], v[198:201], v[162:165], v[90:93]
	v_mfma_f32_16x16x32_bf16 v[86:89], v[194:197], v[174:177], v[86:89]
	v_mfma_f32_16x16x32_bf16 v[82:85], v[198:201], v[170:173], v[82:85]
	v_mfma_f32_16x16x32_bf16 v[78:81], v[194:197], v[182:185], v[78:81]
	v_mfma_f32_16x16x32_bf16 v[74:77], v[202:205], v[182:185], v[74:77]
	v_mfma_f32_16x16x32_bf16 v[70:73], v[102:105], v[186:189], v[70:73]
	v_mfma_f32_16x16x32_bf16 v[66:69], v[198:201], v[186:189], v[66:69]
	v_mfma_f32_16x16x32_bf16 v[162:165], v[202:205], v[166:169], v[90:93]
	v_mfma_f32_16x16x32_bf16 v[166:169], v[202:205], v[174:177], v[82:85]
	v_mfma_f32_16x16x32_bf16 v[170:173], v[194:197], v[190:193], v[70:73]
	v_mfma_f32_16x16x32_bf16 v[174:177], v[202:205], v[190:193], v[66:69]

; #define LDA(dst, b, h) for (int m = 0; m < 4; ++m) for (int k = 0; k < 2; ++k) \
;     dst[m][k] = *reinterpret_cast<const bf16x8*>((char*)SA(b, h) + a_thr + (m * 2 + k) * 1024)
; #define MMA(ai, bj, At, Btf) do { __builtin_amdgcn_s_setprio(1); \
;     for (int m = 0; m < 4; ++m) for (int n = 0; n < 2; ++n) for (int k = 0; k < 2; ++k) \
;       acc[ai][bj][m][n] = __builtin_amdgcn_mfma_f32_16x16x32_bf16(Btf[n][k], At[m][k], acc[ai][bj][m][n], 0, 0, 0); \
;     __builtin_amdgcn_s_setprio(0); } while (0)
; #define WAIT_V(n) asm volatile("s_waitcnt vmcnt(" #n ")" ::: "memory")
; #define WAIT_L(n) asm volatile("s_waitcnt lgkmcnt(" #n ")" ::: "memory")
; #define BAR __builtin_amdgcn_s_barrier()
; template <bool OVL, bool PANEL = false, class Epi>
; __device__ __forceinline__ void gemm_phase(const bf16_t* __restrict__ A, long lda, const bf16_t* __restrict__ Bt, long ldb, int nM, int nN, int K,
;                                            const Epi& epi, bf16_t* shm, int w0) {
;     ...
;       LDA(At, 0, 1); WAIT_V(4); BAR; WAIT_L(0); MMA(1, 0, At, B0); MMA(1, 1, At, B1); BAR; }
	s_barrier
	s_nop 1
	ds_read_b128 v[66:69], v141 offset:16384
	ds_read_b128 v[70:73], v141 offset:17408
	ds_read_b128 v[82:85], v141 offset:18432
	ds_read_b128 v[90:93], v141 offset:19456
	ds_read_b128 v[178:181], v141 offset:20480
	ds_read_b128 v[182:185], v141 offset:21504
	ds_read_b128 v[186:189], v141 offset:22528
	ds_read_b128 v[190:193], v141 offset:23552
	s_waitcnt vmcnt(4)
	s_barrier
	s_waitcnt lgkmcnt(0)

; #define LDA(dst, b, h) for (int m = 0; m < 4; ++m) for (int k = 0; k < 2; ++k) \
;     dst[m][k] = *reinterpret_cast<const bf16x8*>((char*)SA(b, h) + a_thr + (m * 2 + k) * 1024)
; #define MMA(ai, bj, At, Btf) do { __builtin_amdgcn_s_setprio(1); \
;     for (int m = 0; m < 4; ++m) for (int n = 0; n < 2; ++n) for (int k = 0; k < 2; ++k) \
;       acc[ai][bj][m][n] = __builtin_amdgcn_mfma_f32_16x16x32_bf16(Btf[n][k], At[m][k], acc[ai][bj][m][n], 0, 0, 0); \
;     __builtin_amdgcn_s_setprio(0); } while (0)
; #define WAIT_V(n) asm volatile("s_waitcnt vmcnt(" #n ")" ::: "memory")
; #define WAIT_L(n) asm volatile("s_waitcnt lgkmcnt(" #n ")" ::: "memory")
; #define BAR __builtin_amdgcn_s_barrier()
; template <bool OVL, bool PANEL = false, class Epi>
; __device__ __forceinline__ void gemm_phase(const bf16_t* __restrict__ A, long lda, const bf16_t* __restrict__ Bt, long ldb, int nM, int nN, int K,
;                                            const Epi& epi, bf16_t* shm, int w0) {
;     ...
;       LDA(At, 0, 1); WAIT_V(4); BAR; WAIT_L(0); MMA(1, 0, At, B0); MMA(1, 1, At, B1); BAR; }
	s_waitcnt lgkmcnt(0)
	v_mfma_f32_16x16x32_bf16 v[62:65], v[142:145], v[66:69], v[62:65]
	v_mfma_f32_16x16x32_bf16 v[54:57], v[142:145], v[82:85], v[54:57]
	v_mfma_f32_16x16x32_bf16 v[46:49], v[142:145], v[178:181], v[46:49]
	v_mfma_f32_16x16x32_bf16 v[42:45], v[154:157], v[178:181], v[42:45]
	v_mfma_f32_16x16x32_bf16 v[38:41], v[142:145], v[186:189], v[38:41]
	v_mfma_f32_16x16x32_bf16 v[34:37], v[154:157], v[186:189], v[34:37]
	v_mfma_f32_16x16x32_bf16 v[62:65], v[150:153], v[70:73], v[62:65]
	v_mfma_f32_16x16x32_bf16 v[58:61], v[154:157], v[66:69], v[58:61]
	v_mfma_f32_16x16x32_bf16 v[54:57], v[150:153], v[90:93], v[54:57]
	v_mfma_f32_16x16x32_bf16 v[50:53], v[154:157], v[82:85], v[50:53]
	v_mfma_f32_16x16x32_bf16 v[46:49], v[150:153], v[182:185], v[46:49]
	v_mfma_f32_16x16x32_bf16 v[42:45], v[158:161], v[182:185], v[42:45]
	v_mfma_f32_16x16x32_bf16 v[38:41], v[150:153], v[190:193], v[38:41]
	v_mfma_f32_16x16x32_bf16 v[34:37], v[158:161], v[190:193], v[34:37]
	v_mfma_f32_16x16x32_bf16 v[206:209], v[158:161], v[70:73], v[58:61]
	v_mfma_f32_16x16x32_bf16 v[210:213], v[158:161], v[90:93], v[50:53]


; #define LDA(dst, b, h) for (int m = 0; m < 4; ++m) for (int k = 0; k < 2; ++k) \
;     dst[m][k] = *reinterpret_cast<const bf16x8*>((char*)SA(b, h) + a_thr + (m * 2 + k) * 1024)
; #define MMA(ai, bj, At, Btf) do { __builtin_amdgcn_s_setprio(1); \
;     for (int m = 0; m < 4; ++m) for (int n = 0; n < 2; ++n) for (int k = 0; k < 2; ++k) \
;       acc[ai][bj][m][n] = __builtin_amdgcn_mfma_f32_16x16x32_bf16(Btf[n][k], At[m][k], acc[ai][bj][m][n], 0, 0, 0); \
;     __builtin_amdgcn_s_setprio(0); } while (0)
; #define WAIT_V(n) asm volatile("s_waitcnt vmcnt(" #n ")" ::: "memory")
; #define WAIT_L(n) asm volatile("s_waitcnt lgkmcnt(" #n ")" ::: "memory")
; #define BAR __builtin_amdgcn_s_barrier()
; template <bool OVL, bool PANEL = false, class Epi>
; __device__ __forceinline__ void gemm_phase(const bf16_t* __restrict__ A, long lda, const bf16_t* __restrict__ Bt, long ldb, int nM, int nN, int K,
;                                            const Epi& epi, bf16_t* shm, int w0) {
;     ...
;       LDA(At, 0, 1); WAIT_V(4); BAR; WAIT_L(0); MMA(1, 0, At, B0); MMA(1, 1, At, B1); BAR; }
	v_mfma_f32_16x16x32_bf16 v[30:33], v[102:105], v[66:69], v[30:33]
	v_mfma_f32_16x16x32_bf16 v[26:29], v[198:201], v[66:69], v[26:29]
	v_mfma_f32_16x16x32_bf16 v[22:25], v[102:105], v[82:85], v[22:25]
	v_mfma_f32_16x16x32_bf16 v[18:21], v[198:201], v[82:85], v[18:21]
	v_mfma_f32_16x16x32_bf16 v[14:17], v[102:105], v[178:181], v[14:17]
	v_mfma_f32_16x16x32_bf16 v[10:13], v[198:201], v[178:181], v[10:13]
	v_mfma_f32_16x16x32_bf16 v[6:9], v[102:105], v[186:189], v[6:9]
	v_mfma_f32_16x16x32_bf16 v[2:5], v[198:201], v[186:189], v[2:5]
	v_mfma_f32_16x16x32_bf16 v[30:33], v[194:197], v[70:73], v[30:33]
	v_mfma_f32_16x16x32_bf16 v[26:29], v[202:205], v[70:73], v[26:29]
	v_mfma_f32_16x16x32_bf16 v[22:25], v[194:197], v[90:93], v[22:25]
	v_mfma_f32_16x16x32_bf16 v[18:21], v[202:205], v[90:93], v[18:21]
	v_mfma_f32_16x16x32_bf16 v[14:17], v[194:197], v[182:185], v[14:17]
	v_mfma_f32_16x16x32_bf16 v[10:13], v[202:205], v[182:185], v[10:13]
	v_mfma_f32_16x16x32_bf16 v[6:9], v[194:197], v[190:193], v[6:9]
	v_mfma_f32_16x16x32_bf16 v[2:5], v[202:205], v[190:193], v[2:5]

; #define LDA(dst, b, h) for (int m = 0; m < 4; ++m) for (int k = 0; k < 2; ++k) \
;     dst[m][k] = *reinterpret_cast<const bf16x8*>((char*)SA(b, h) + a_thr + (m * 2 + k) * 1024)
; #define LDB(dst, b, h) for (int n = 0; n < 2; ++n) for (int k = 0; k < 2; ++k) \
;     dst[n][k] = *reinterpret_cast<const bf16x8*>((char*)SB(b, h) + b_thr + (n * 2 + k) * 1024)
; #define MMA(ai, bj, At, Btf) do { __builtin_amdgcn_s_setprio(1); \
;     for (int m = 0; m < 4; ++m) for (int n = 0; n < 2; ++n) for (int k = 0; k < 2; ++k) \
;       acc[ai][bj][m][n] = __builtin_amdgcn_mfma_f32_16x16x32_bf16(Btf[n][k], At[m][k], acc[ai][bj][m][n], 0, 0, 0); \
;     __builtin_amdgcn_s_setprio(0); } while (0)
; #define WAIT_V(n) asm volatile("s_waitcnt vmcnt(" #n ")" ::: "memory")
; #define WAIT_L(n) asm volatile("s_waitcnt lgkmcnt(" #n ")" ::: "memory")
; #define BAR __builtin_amdgcn_s_barrier()
; template <bool OVL, bool PANEL = false, class Epi>
; __device__ __forceinline__ void gemm_phase(const bf16_t* __restrict__ A, long lda, const bf16_t* __restrict__ Bt, long ldb, int nM, int nN, int K,
;                                            const Epi& epi, bf16_t* shm, int w0) {
;     ...
;     { LDB(B0, 1, 0); LDA(At, 1, 0); WAIT_V(2); BAR; WAIT_L(0); MMA(0, 0, At, B0); BAR;
	v_add_u32_e32 v0, 0x18000, v214
	s_barrier
	ds_read_b128 v[142:145], v0
	ds_read_b128 v[150:153], v0 offset:1024
	ds_read_b128 v[154:157], v0 offset:2048
	ds_read_b128 v[158:161], v0 offset:3072
	ds_read_b128 v[50:53], v141 offset:32768
	ds_read_b128 v[58:61], v141 offset:33792
	ds_read_b128 v[66:69], v141 offset:34816
	ds_read_b128 v[70:73], v141 offset:35840
	ds_read_b128 v[178:181], v141 offset:36864
	ds_read_b128 v[182:185], v141 offset:37888
	ds_read_b128 v[186:189], v141 offset:38912
	ds_read_b128 v[190:193], v141 offset:39936
	s_waitcnt vmcnt(2)
	s_barrier
	s_waitcnt lgkmcnt(0)

; #define LDA(dst, b, h) for (int m = 0; m < 4; ++m) for (int k = 0; k < 2; ++k) \
;     dst[m][k] = *reinterpret_cast<const bf16x8*>((char*)SA(b, h) + a_thr + (m * 2 + k) * 1024)
; #define LDB(dst, b, h) for (int n = 0; n < 2; ++n) for (int k = 0; k < 2; ++k) \
;     dst[n][k] = *reinterpret_cast<const bf16x8*>((char*)SB(b, h) + b_thr + (n * 2 + k) * 1024)
; #define MMA(ai, bj, At, Btf) do { __builtin_amdgcn_s_setprio(1); \
;     for (int m = 0; m < 4; ++m) for (int n = 0; n < 2; ++n) for (int k = 0; k < 2; ++k) \
;       acc[ai][bj][m][n] = __builtin_amdgcn_mfma_f32_16x16x32_bf16(Btf[n][k], At[m][k], acc[ai][bj][m][n], 0, 0, 0); \
;     __builtin_amdgcn_s_setprio(0); } while (0)
; #define WAIT_V(n) asm volatile("s_waitcnt vmcnt(" #n ")" ::: "memory")
; #define WAIT_L(n) asm volatile("s_waitcnt lgkmcnt(" #n ")" ::: "memory")
; #define BAR __builtin_amdgcn_s_barrier()
; template <bool OVL, bool PANEL = false, class Epi>
; __device__ __forceinline__ void gemm_phase(const bf16_t* __restrict__ A, long lda, const bf16_t* __restrict__ Bt, long ldb, int nM, int nN, int K,
;                                            const Epi& epi, bf16_t* shm, int w0) {
;     ...
;     { LDB(B0, 1, 0); LDA(At, 1, 0); WAIT_V(2); BAR; WAIT_L(0); MMA(0, 0, At, B0); BAR;
	s_waitcnt lgkmcnt(0)
	v_mfma_f32_16x16x32_bf16 v[82:85], v[142:145], v[50:53], v[126:129]
	v_mfma_f32_16x16x32_bf16 v[126:129], v[150:153], v[58:61], v[82:85]
	v_mfma_f32_16x16x32_bf16 v[82:85], v[154:157], v[50:53], v[122:125]
	v_mfma_f32_16x16x32_bf16 v[122:125], v[158:161], v[58:61], v[82:85]
	v_mfma_f32_16x16x32_bf16 v[82:85], v[142:145], v[66:69], v[118:121]
	v_mfma_f32_16x16x32_bf16 v[118:121], v[150:153], v[70:73], v[82:85]
	v_mfma_f32_16x16x32_bf16 v[82:85], v[154:157], v[66:69], v[114:117]
	v_mfma_f32_16x16x32_bf16 v[114:117], v[158:161], v[70:73], v[82:85]
	v_mfma_f32_16x16x32_bf16 v[82:85], v[142:145], v[178:181], v[110:113]
	v_mfma_f32_16x16x32_bf16 v[110:113], v[150:153], v[182:185], v[82:85]
	v_mfma_f32_16x16x32_bf16 v[82:85], v[154:157], v[178:181], v[106:109]
	v_mfma_f32_16x16x32_bf16 v[102:105], v[158:161], v[182:185], v[82:85]
	v_mfma_f32_16x16x32_bf16 v[82:85], v[142:145], v[186:189], v[146:149]
	v_mfma_f32_16x16x32_bf16 v[90:93], v[150:153], v[190:193], v[82:85]
	v_mfma_f32_16x16x32_bf16 v[82:85], v[154:157], v[186:189], v[98:101]
	v_mfma_f32_16x16x32_bf16 v[82:85], v[158:161], v[190:193], v[82:85]

; #define LDB(dst, b, h) for (int n = 0; n < 2; ++n) for (int k = 0; k < 2; ++k) \
;     dst[n][k] = *reinterpret_cast<const bf16x8*>((char*)SB(b, h) + b_thr + (n * 2 + k) * 1024)
; #define MMA(ai, bj, At, Btf) do { __builtin_amdgcn_s_setprio(1); \
;     for (int m = 0; m < 4; ++m) for (int n = 0; n < 2; ++n) for (int k = 0; k < 2; ++k) \
;       acc[ai][bj][m][n] = __builtin_amdgcn_mfma_f32_16x16x32_bf16(Btf[n][k], At[m][k], acc[ai][bj][m][n], 0, 0, 0); \
;     __builtin_amdgcn_s_setprio(0); } while (0)
; #define WAIT_V(n) asm volatile("s_waitcnt vmcnt(" #n ")" ::: "memory")
; #define WAIT_L(n) asm volatile("s_waitcnt lgkmcnt(" #n ")" ::: "memory")
; #define BAR __builtin_amdgcn_s_barrier()
; template <bool OVL, bool PANEL = false, class Epi>
; __device__ __forceinline__ void gemm_phase(const bf16_t* __restrict__ A, long lda, const bf16_t* __restrict__ Bt, long ldb, int nM, int nN, int K,
;                                            const Epi& epi, bf16_t* shm, int w0) {
;     ...
;       LDB(B1, 1, 1); WAIT_V(0); BAR; WAIT_L(0); MMA(0, 1, At, B1); BAR;
	v_add_u32_e32 v0, 0x1c000, v214
	s_barrier
	ds_read_b128 v[146:149], v0
	ds_read_b128 v[194:197], v0 offset:1024
	ds_read_b128 v[198:201], v0 offset:2048
	ds_read_b128 v[202:205], v0 offset:3072
	s_waitcnt vmcnt(0)
	s_barrier
	s_waitcnt lgkmcnt(0)

; #define LDB(dst, b, h) for (int n = 0; n < 2; ++n) for (int k = 0; k < 2; ++k) \
;     dst[n][k] = *reinterpret_cast<const bf16x8*>((char*)SB(b, h) + b_thr + (n * 2 + k) * 1024)
; #define MMA(ai, bj, At, Btf) do { __builtin_amdgcn_s_setprio(1); \
;     for (int m = 0; m < 4; ++m) for (int n = 0; n < 2; ++n) for (int k = 0; k < 2; ++k) \
;       acc[ai][bj][m][n] = __builtin_amdgcn_mfma_f32_16x16x32_bf16(Btf[n][k], At[m][k], acc[ai][bj][m][n], 0, 0, 0); \
;     __builtin_amdgcn_s_setprio(0); } while (0)
; #define WAIT_V(n) asm volatile("s_waitcnt vmcnt(" #n ")" ::: "memory")
; #define WAIT_L(n) asm volatile("s_waitcnt lgkmcnt(" #n ")" ::: "memory")
; #define BAR __builtin_amdgcn_s_barrier()
; template <bool OVL, bool PANEL = false, class Epi>
; __device__ __forceinline__ void gemm_phase(const bf16_t* __restrict__ A, long lda, const bf16_t* __restrict__ Bt, long ldb, int nM, int nN, int K,
;                                            const Epi& epi, bf16_t* shm, int w0) {
;     ...
;       LDB(B1, 1, 1); WAIT_V(0); BAR; WAIT_L(0); MMA(0, 1, At, B1); BAR;
	s_waitcnt lgkmcnt(0)
	v_mfma_f32_16x16x32_bf16 v[94:97], v[146:149], v[50:53], v[94:97]
	v_mfma_f32_16x16x32_bf16 v[50:53], v[198:201], v[50:53], v[162:165]
	v_mfma_f32_16x16x32_bf16 v[98:101], v[202:205], v[58:61], v[50:53]
	v_mfma_f32_16x16x32_bf16 v[50:53], v[146:149], v[66:69], v[86:89]
	v_mfma_f32_16x16x32_bf16 v[106:109], v[194:197], v[58:61], v[94:97]
	v_mfma_f32_16x16x32_bf16 v[94:97], v[194:197], v[70:73], v[50:53]
	v_mfma_f32_16x16x32_bf16 v[50:53], v[198:201], v[66:69], v[166:169]
	v_mfma_f32_16x16x32_bf16 v[86:89], v[202:205], v[70:73], v[50:53]
	v_mfma_f32_16x16x32_bf16 v[50:53], v[146:149], v[178:181], v[78:81]
	v_mfma_f32_16x16x32_bf16 v[70:73], v[194:197], v[182:185], v[50:53]
	v_mfma_f32_16x16x32_bf16 v[50:53], v[198:201], v[178:181], v[74:77]
	v_mfma_f32_16x16x32_bf16 v[66:69], v[202:205], v[182:185], v[50:53]
	v_mfma_f32_16x16x32_bf16 v[50:53], v[146:149], v[186:189], v[170:173]
	v_mfma_f32_16x16x32_bf16 v[58:61], v[194:197], v[190:193], v[50:53]
	v_mfma_f32_16x16x32_bf16 v[50:53], v[198:201], v[186:189], v[174:177]
	v_mfma_f32_16x16x32_bf16 v[50:53], v[202:205], v[190:193], v[50:53]

; #define LDA(dst, b, h) for (int m = 0; m < 4; ++m) for (int k = 0; k < 2; ++k) \
;     dst[m][k] = *reinterpret_cast<const bf16x8*>((char*)SA(b, h) + a_thr + (m * 2 + k) * 1024)
; #define MMA(ai, bj, At, Btf) do { __builtin_amdgcn_s_setprio(1); \
;     for (int m = 0; m < 4; ++m) for (int n = 0; n < 2; ++n) for (int k = 0; k < 2; ++k) \
;       acc[ai][bj][m][n] = __builtin_amdgcn_mfma_f32_16x16x32_bf16(Btf[n][k], At[m][k], acc[ai][bj][m][n], 0, 0, 0); \
;     __builtin_amdgcn_s_setprio(0); } while (0)
; #define WAIT_L(n) asm volatile("s_waitcnt lgkmcnt(" #n ")" ::: "memory")
; #define BAR __builtin_amdgcn_s_barrier()
; template <bool OVL, bool PANEL = false, class Epi>
; __device__ __forceinline__ void gemm_phase(const bf16_t* __restrict__ A, long lda, const bf16_t* __restrict__ Bt, long ldb, int nM, int nN, int K,
;                                            const Epi& epi, bf16_t* shm, int w0) {
;     ...
;       LDA(At, 1, 1); BAR; WAIT_L(0); MMA(1, 0, At, B0); MMA(1, 1, At, B1); BAR; }
	s_barrier
	ds_read_b128 v[162:165], v141 offset:49152
	ds_read_b128 v[166:169], v141 offset:50176
	ds_read_b128 v[170:173], v141 offset:51200
	ds_read_b128 v[174:177], v141 offset:52224
	ds_read_b128 v[178:181], v141 offset:53248
	ds_read_b128 v[182:185], v141 offset:54272
	ds_read_b128 v[186:189], v141 offset:55296
	ds_read_b128 v[190:193], v141 offset:56320
	s_barrier
	s_waitcnt lgkmcnt(0)

; #define LDA(dst, b, h) for (int m = 0; m < 4; ++m) for (int k = 0; k < 2; ++k) \
;     dst[m][k] = *reinterpret_cast<const bf16x8*>((char*)SA(b, h) + a_thr + (m * 2 + k) * 1024)
; #define MMA(ai, bj, At, Btf) do { __builtin_amdgcn_s_setprio(1); \
;     for (int m = 0; m < 4; ++m) for (int n = 0; n < 2; ++n) for (int k = 0; k < 2; ++k) \
;       acc[ai][bj][m][n] = __builtin_amdgcn_mfma_f32_16x16x32_bf16(Btf[n][k], At[m][k], acc[ai][bj][m][n], 0, 0, 0); \
;     __builtin_amdgcn_s_setprio(0); } while (0)
; #define WAIT_L(n) asm volatile("s_waitcnt lgkmcnt(" #n ")" ::: "memory")
; #define BAR __builtin_amdgcn_s_barrier()
; template <bool OVL, bool PANEL = false, class Epi>
; __device__ __forceinline__ void gemm_phase(const bf16_t* __restrict__ A, long lda, const bf16_t* __restrict__ Bt, long ldb, int nM, int nN, int K,
;                                            const Epi& epi, bf16_t* shm, int w0) {
;     ...
;       LDA(At, 1, 1); BAR; WAIT_L(0); MMA(1, 0, At, B0); MMA(1, 1, At, B1); BAR; }
	s_waitcnt lgkmcnt(0)
	v_mfma_f32_16x16x32_bf16 v[62:65], v[142:145], v[162:165], v[62:65]
	v_mfma_f32_16x16x32_bf16 v[78:81], v[150:153], v[166:169], v[62:65]
	v_mfma_f32_16x16x32_bf16 v[62:65], v[154:157], v[162:165], v[206:209]
	v_mfma_f32_16x16x32_bf16 v[54:57], v[142:145], v[170:173], v[54:57]
	v_mfma_f32_16x16x32_bf16 v[74:77], v[158:161], v[166:169], v[62:65]
	v_mfma_f32_16x16x32_bf16 v[62:65], v[150:153], v[174:177], v[54:57]
	v_mfma_f32_16x16x32_bf16 v[54:57], v[154:157], v[170:173], v[210:213]
	v_mfma_f32_16x16x32_bf16 v[46:49], v[142:145], v[178:181], v[46:49]
	v_mfma_f32_16x16x32_bf16 v[42:45], v[154:157], v[178:181], v[42:45]
	v_mfma_f32_16x16x32_bf16 v[38:41], v[142:145], v[186:189], v[38:41]
	v_mfma_f32_16x16x32_bf16 v[34:37], v[154:157], v[186:189], v[34:37]
	v_mfma_f32_16x16x32_bf16 v[54:57], v[158:161], v[174:177], v[54:57]
	v_mfma_f32_16x16x32_bf16 v[46:49], v[150:153], v[182:185], v[46:49]
	v_mfma_f32_16x16x32_bf16 v[42:45], v[158:161], v[182:185], v[42:45]
	v_mfma_f32_16x16x32_bf16 v[38:41], v[150:153], v[190:193], v[38:41]
	v_mfma_f32_16x16x32_bf16 v[34:37], v[158:161], v[190:193], v[34:37]


; #define LDA(dst, b, h) for (int m = 0; m < 4; ++m) for (int k = 0; k < 2; ++k) \
;     dst[m][k] = *reinterpret_cast<const bf16x8*>((char*)SA(b, h) + a_thr + (m * 2 + k) * 1024)
; #define MMA(ai, bj, At, Btf) do { __builtin_amdgcn_s_setprio(1); \
;     for (int m = 0; m < 4; ++m) for (int n = 0; n < 2; ++n) for (int k = 0; k < 2; ++k) \
;       acc[ai][bj][m][n] = __builtin_amdgcn_mfma_f32_16x16x32_bf16(Btf[n][k], At[m][k], acc[ai][bj][m][n], 0, 0, 0); \
;     __builtin_amdgcn_s_setprio(0); } while (0)
; #define WAIT_L(n) asm volatile("s_waitcnt lgkmcnt(" #n ")" ::: "memory")
; #define BAR __builtin_amdgcn_s_barrier()
; template <bool OVL, bool PANEL = false, class Epi>
; __device__ __forceinline__ void gemm_phase(const bf16_t* __restrict__ A, long lda, const bf16_t* __restrict__ Bt, long ldb, int nM, int nN, int K,
;                                            const Epi& epi, bf16_t* shm, int w0) {
;     ...
;       LDA(At, 1, 1); BAR; WAIT_L(0); MMA(1, 0, At, B0); MMA(1, 1, At, B1); BAR; }
	v_mfma_f32_16x16x32_bf16 v[30:33], v[146:149], v[162:165], v[30:33]
	v_mfma_f32_16x16x32_bf16 v[26:29], v[198:201], v[162:165], v[26:29]
	v_mfma_f32_16x16x32_bf16 v[22:25], v[146:149], v[170:173], v[22:25]
	v_mfma_f32_16x16x32_bf16 v[18:21], v[198:201], v[170:173], v[18:21]
	v_mfma_f32_16x16x32_bf16 v[14:17], v[146:149], v[178:181], v[14:17]
	v_mfma_f32_16x16x32_bf16 v[10:13], v[198:201], v[178:181], v[10:13]
	v_mfma_f32_16x16x32_bf16 v[6:9], v[146:149], v[186:189], v[6:9]
	v_mfma_f32_16x16x32_bf16 v[2:5], v[198:201], v[186:189], v[2:5]
	v_mfma_f32_16x16x32_bf16 v[30:33], v[194:197], v[166:169], v[30:33]
	v_mfma_f32_16x16x32_bf16 v[26:29], v[202:205], v[166:169], v[26:29]
	v_mfma_f32_16x16x32_bf16 v[22:25], v[194:197], v[174:177], v[22:25]
	v_mfma_f32_16x16x32_bf16 v[18:21], v[202:205], v[174:177], v[18:21]
	v_mfma_f32_16x16x32_bf16 v[14:17], v[194:197], v[182:185], v[14:17]
	v_mfma_f32_16x16x32_bf16 v[10:13], v[202:205], v[182:185], v[10:13]
	v_mfma_f32_16x16x32_bf16 v[6:9], v[194:197], v[190:193], v[6:9]
	v_mfma_f32_16x16x32_bf16 v[2:5], v[202:205], v[190:193], v[2:5]

; #define LDA(dst, b, h) for (int m = 0; m < 4; ++m) for (int k = 0; k < 2; ++k) \
;     dst[m][k] = *reinterpret_cast<const bf16x8*>((char*)SA(b, h) + a_thr + (m * 2 + k) * 1024)
; #define MMA(ai, bj, At, Btf) do { __builtin_amdgcn_s_setprio(1); \
;     for (int m = 0; m < 4; ++m) for (int n = 0; n < 2; ++n) for (int k = 0; k < 2; ++k) \
;       acc[ai][bj][m][n] = __builtin_amdgcn_mfma_f32_16x16x32_bf16(Btf[n][k], At[m][k], acc[ai][bj][m][n], 0, 0, 0); \
;     __builtin_amdgcn_s_setprio(0); } while (0)
; #define WAIT_L(n) asm volatile("s_waitcnt lgkmcnt(" #n ")" ::: "memory")
; #define BAR __builtin_amdgcn_s_barrier()
; template <bool OVL, bool PANEL = false, class Epi>
; __device__ __forceinline__ void gemm_phase(const bf16_t* __restrict__ A, long lda, const bf16_t* __restrict__ Bt, long ldb, int nM, int nN, int K,
;                                            const Epi& epi, bf16_t* shm, int w0) {
;     ...
;       LDA(At, 1, 1); BAR; WAIT_L(0); MMA(1, 0, At, B0); MMA(1, 1, At, B1); BAR; }
;     if (wr == 0) BAR;
	s_barrier
	s_and_saveexec_b64 s[8:9], s[78:79]
	s_cbranch_execz .LBB0_389
	s_barrier

; #define LDA(dst, b, h) for (int m = 0; m < 4; ++m) for (int k = 0; k < 2; ++k) \
;     dst[m][k] = *reinterpret_cast<const bf16x8*>((char*)SA(b, h) + a_thr + (m * 2 + k) * 1024)
; #define LDB(dst, b, h) for (int n = 0; n < 2; ++n) for (int k = 0; k < 2; ++k) \
;     dst[n][k] = *reinterpret_cast<const bf16x8*>((char*)SB(b, h) + b_thr + (n * 2 + k) * 1024)
; #define MMA(ai, bj, At, Btf) do { __builtin_amdgcn_s_setprio(1); \
;     for (int m = 0; m < 4; ++m) for (int n = 0; n < 2; ++n) for (int k = 0; k < 2; ++k) \
;       acc[ai][bj][m][n] = __builtin_amdgcn_mfma_f32_16x16x32_bf16(Btf[n][k], At[m][k], acc[ai][bj][m][n], 0, 0, 0); \
;     __builtin_amdgcn_s_setprio(0); } while (0)
; #define WAIT_V(n) asm volatile("s_waitcnt vmcnt(" #n ")" ::: "memory")
; #define WAIT_L(n) asm volatile("s_waitcnt lgkmcnt(" #n ")" ::: "memory")
; #define BAR __builtin_amdgcn_s_barrier()
; #define SCHED __builtin_amdgcn_sched_barrier(0)
; template <bool OVL, bool PANEL = false, class Epi>
; __device__ __forceinline__ void gemm_phase(const bf16_t* __restrict__ A, long lda, const bf16_t* __restrict__ Bt, long ldb, int nM, int nN, int K,
;                                            const Epi& epi, bf16_t* shm, int w0) {
;     ...
;       LDB(B0, 0, 0); SCHED; LDA(At, 0, 0); STAGE(SA(1, 1), A, lda, aoff, brow + HALF, t + 1);
;       WAIT_L(8); BAR; WAIT_L(0); MMA(0, 0, At, B0); BAR; SCHED;
;       LDB(B1, 0, 1); STAGE(SB(0, 0), Bt, ldb, boff, bcol, t + 2);
;       BAR; WAIT_L(0); MMA(0, 1, At, B1); BAR;
;       LDA(At, 0, 1); STAGE(SA(0, 0), A, lda, aoff, brow, t + 2);
;       BAR; WAIT_L(0); MMA(1, 0, At, B0); BAR; SCHED;
;       STAGE(SB(0, 1), Bt, ldb, boff, bcol + HALF, t + 2);
;       WAIT_V(6); BAR; MMA(1, 1, At, B1); BAR;
.LBB0_410:
	ds_read_b128 v[152:155], v220
	ds_read_b128 v[156:159], v220 offset:1024
	ds_read_b128 v[160:163], v220 offset:2048
	ds_read_b128 v[164:167], v220 offset:3072
	s_add_u32 s12, s8, s10
	s_addc_u32 s13, s9, s11
	ds_read_b128 v[168:171], v143
	ds_read_b128 v[172:175], v143 offset:1024
	ds_read_b128 v[176:179], v143 offset:2048
	ds_read_b128 v[180:183], v143 offset:3072
	ds_read_b128 v[184:187], v143 offset:4096
	ds_read_b128 v[188:191], v143 offset:5120
	ds_read_b128 v[192:195], v143 offset:6144
	ds_read_b128 v[196:199], v143 offset:7168
	s_mov_b32 m0, s16
	s_add_u32 s98, s12, s24
	s_addc_u32 s99, s13, s25
	global_load_lds_dwordx4 v131, s[98:99]
	s_mov_b32 m0, s23
	s_add_u32 s98, s12, s36
	s_addc_u32 s99, s13, s37
	global_load_lds_dwordx4 v131, s[98:99]
	s_waitcnt lgkmcnt(0)
	s_waitcnt vmcnt(10)
	s_barrier
	v_mfma_f32_16x16x32_bf16 v[126:129], v[152:155], v[168:171], v[126:129]
	v_mfma_f32_16x16x32_bf16 v[122:125], v[160:163], v[168:171], v[122:125]
	v_mfma_f32_16x16x32_bf16 v[118:121], v[152:155], v[176:179], v[118:121]
	v_mfma_f32_16x16x32_bf16 v[114:117], v[160:163], v[176:179], v[114:117]
	v_mfma_f32_16x16x32_bf16 v[110:113], v[152:155], v[184:187], v[110:113]
	v_mfma_f32_16x16x32_bf16 v[106:109], v[160:163], v[184:187], v[106:109]
	v_mfma_f32_16x16x32_bf16 v[102:105], v[152:155], v[192:195], v[102:105]
	v_mfma_f32_16x16x32_bf16 v[98:101], v[160:163], v[192:195], v[98:101]
	v_mfma_f32_16x16x32_bf16 v[126:129], v[156:159], v[172:175], v[126:129]
	v_mfma_f32_16x16x32_bf16 v[122:125], v[164:167], v[172:175], v[122:125]
	v_mfma_f32_16x16x32_bf16 v[118:121], v[156:159], v[180:183], v[118:121]
	v_mfma_f32_16x16x32_bf16 v[114:117], v[164:167], v[180:183], v[114:117]
	v_mfma_f32_16x16x32_bf16 v[110:113], v[156:159], v[188:191], v[110:113]
	v_mfma_f32_16x16x32_bf16 v[106:109], v[164:167], v[188:191], v[106:109]
	v_mfma_f32_16x16x32_bf16 v[102:105], v[156:159], v[196:199], v[102:105]
	v_mfma_f32_16x16x32_bf16 v[98:101], v[164:167], v[196:199], v[98:101]
	s_barrier
	s_add_u32 s14, s0, s10
	ds_read_b128 v[200:203], v221
	ds_read_b128 v[204:207], v221 offset:1024
	ds_read_b128 v[208:211], v221 offset:2048
	ds_read_b128 v[212:215], v221 offset:3072
	s_addc_u32 s15, s1, s11
	s_mov_b32 m0, s30
	s_add_u32 s98, s14, s34
	s_addc_u32 s99, s15, s35
	global_load_lds_dwordx4 v131, s[98:99]
	s_mov_b32 m0, s31
	s_add_u32 s98, s14, s64
	s_addc_u32 s99, s15, s65
	global_load_lds_dwordx4 v131, s[98:99]
	s_waitcnt lgkmcnt(0)
	s_waitcnt vmcnt(10)
	s_barrier
	v_mfma_f32_16x16x32_bf16 v[94:97], v[200:203], v[168:171], v[94:97]
	v_mfma_f32_16x16x32_bf16 v[90:93], v[208:211], v[168:171], v[90:93]
	v_mfma_f32_16x16x32_bf16 v[86:89], v[200:203], v[176:179], v[86:89]
	v_mfma_f32_16x16x32_bf16 v[82:85], v[208:211], v[176:179], v[82:85]
	v_mfma_f32_16x16x32_bf16 v[78:81], v[200:203], v[184:187], v[78:81]
	v_mfma_f32_16x16x32_bf16 v[74:77], v[208:211], v[184:187], v[74:77]
	v_mfma_f32_16x16x32_bf16 v[70:73], v[200:203], v[192:195], v[70:73]
	v_mfma_f32_16x16x32_bf16 v[66:69], v[208:211], v[192:195], v[66:69]
	v_mfma_f32_16x16x32_bf16 v[94:97], v[204:207], v[172:175], v[94:97]
	v_mfma_f32_16x16x32_bf16 v[90:93], v[212:215], v[172:175], v[90:93]
	v_mfma_f32_16x16x32_bf16 v[86:89], v[204:207], v[180:183], v[86:89]
	v_mfma_f32_16x16x32_bf16 v[82:85], v[212:215], v[180:183], v[82:85]
	v_mfma_f32_16x16x32_bf16 v[78:81], v[204:207], v[188:191], v[78:81]
	v_mfma_f32_16x16x32_bf16 v[74:77], v[212:215], v[188:191], v[74:77]
	v_mfma_f32_16x16x32_bf16 v[70:73], v[204:207], v[196:199], v[70:73]
	v_mfma_f32_16x16x32_bf16 v[66:69], v[212:215], v[196:199], v[66:69]
	s_barrier
	ds_read_b128 v[168:171], v143 offset:16384
	ds_read_b128 v[172:175], v143 offset:17408
	ds_read_b128 v[176:179], v143 offset:18432
	ds_read_b128 v[180:183], v143 offset:19456
	ds_read_b128 v[184:187], v143 offset:20480
	ds_read_b128 v[188:191], v143 offset:21504
	ds_read_b128 v[192:195], v143 offset:22528
	ds_read_b128 v[196:199], v143 offset:23552
	s_mov_b32 m0, s32
	s_add_u32 s98, s12, s34
	s_addc_u32 s99, s13, s35
	global_load_lds_dwordx4 v131, s[98:99]
	s_mov_b32 m0, s40
	s_add_u32 s98, s12, s64
	s_addc_u32 s99, s13, s65
	global_load_lds_dwordx4 v131, s[98:99]
	s_waitcnt lgkmcnt(0)
	s_barrier
	v_mfma_f32_16x16x32_bf16 v[62:65], v[152:155], v[168:171], v[62:65]
	v_mfma_f32_16x16x32_bf16 v[58:61], v[160:163], v[168:171], v[58:61]
	v_mfma_f32_16x16x32_bf16 v[54:57], v[152:155], v[176:179], v[54:57]
	v_mfma_f32_16x16x32_bf16 v[50:53], v[160:163], v[176:179], v[50:53]
	v_mfma_f32_16x16x32_bf16 v[46:49], v[152:155], v[184:187], v[46:49]
	v_mfma_f32_16x16x32_bf16 v[42:45], v[160:163], v[184:187], v[42:45]
	v_mfma_f32_16x16x32_bf16 v[38:41], v[152:155], v[192:195], v[38:41]
	v_mfma_f32_16x16x32_bf16 v[34:37], v[160:163], v[192:195], v[34:37]
	v_mfma_f32_16x16x32_bf16 v[62:65], v[156:159], v[172:175], v[62:65]
	v_mfma_f32_16x16x32_bf16 v[58:61], v[164:167], v[172:175], v[58:61]
	v_mfma_f32_16x16x32_bf16 v[54:57], v[156:159], v[180:183], v[54:57]
	v_mfma_f32_16x16x32_bf16 v[50:53], v[164:167], v[180:183], v[50:53]
	v_mfma_f32_16x16x32_bf16 v[46:49], v[156:159], v[188:191], v[46:49]
	v_mfma_f32_16x16x32_bf16 v[42:45], v[164:167], v[188:191], v[42:45]
	v_mfma_f32_16x16x32_bf16 v[38:41], v[156:159], v[196:199], v[38:41]
	v_mfma_f32_16x16x32_bf16 v[34:37], v[164:167], v[196:199], v[34:37]
	s_barrier
	s_mov_b32 m0, s41
	s_add_u32 s98, s14, s68
	s_addc_u32 s99, s15, s69
	global_load_lds_dwordx4 v131, s[98:99]
	s_mov_b32 m0, s42
	s_add_u32 s98, s14, s70
	s_addc_u32 s99, s15, s71
	global_load_lds_dwordx4 v131, s[98:99]
	s_waitcnt vmcnt(10)
	s_barrier
; #define LDA(dst, b, h) for (int m = 0; m < 4; ++m) for (int k = 0; k < 2; ++k) \
;     dst[m][k] = *reinterpret_cast<const bf16x8*>((char*)SA(b, h) + a_thr + (m * 2 + k) * 1024)
; #define LDB(dst, b, h) for (int n = 0; n < 2; ++n) for (int k = 0; k < 2; ++k) \
;     dst[n][k] = *reinterpret_cast<const bf16x8*>((char*)SB(b, h) + b_thr + (n * 2 + k) * 1024)
; #define MMA(ai, bj, At, Btf) do { __builtin_amdgcn_s_setprio(1); \
;     for (int m = 0; m < 4; ++m) for (int n = 0; n < 2; ++n) for (int k = 0; k < 2; ++k) \
;       acc[ai][bj][m][n] = __builtin_amdgcn_mfma_f32_16x16x32_bf16(Btf[n][k], At[m][k], acc[ai][bj][m][n], 0, 0, 0); \
;     __builtin_amdgcn_s_setprio(0); } while (0)
; #define WAIT_V(n) asm volatile("s_waitcnt vmcnt(" #n ")" ::: "memory")
; #define WAIT_L(n) asm volatile("s_waitcnt lgkmcnt(" #n ")" ::: "memory")
; #define BAR __builtin_amdgcn_s_barrier()
; #define SCHED __builtin_amdgcn_sched_barrier(0)
; template <bool OVL, bool PANEL = false, class Epi>
; __device__ __forceinline__ void gemm_phase(const bf16_t* __restrict__ A, long lda, const bf16_t* __restrict__ Bt, long ldb, int nM, int nN, int K,
;                                            const Epi& epi, bf16_t* shm, int w0) {
;     ...
;       WAIT_V(6); BAR; MMA(1, 1, At, B1); BAR;
;       LDB(B0, 1, 0); SCHED; LDA(At, 1, 0); STAGE(SA(0, 1), A, lda, aoff, brow + HALF, t + 2);
;       WAIT_L(8); BAR; WAIT_L(0); MMA(0, 0, At, B0); BAR; SCHED;
;       LDB(B1, 1, 1); STAGE(SB(1, 0), Bt, ldb, boff, bcol, t + 3);
;       BAR; WAIT_L(0); MMA(0, 1, At, B1); BAR;
	v_mfma_f32_16x16x32_bf16 v[30:33], v[200:203], v[168:171], v[30:33]
	v_mfma_f32_16x16x32_bf16 v[26:29], v[208:211], v[168:171], v[26:29]
	v_mfma_f32_16x16x32_bf16 v[22:25], v[200:203], v[176:179], v[22:25]
	v_mfma_f32_16x16x32_bf16 v[18:21], v[208:211], v[176:179], v[18:21]
	v_mfma_f32_16x16x32_bf16 v[14:17], v[200:203], v[184:187], v[14:17]
	v_mfma_f32_16x16x32_bf16 v[10:13], v[208:211], v[184:187], v[10:13]
	v_mfma_f32_16x16x32_bf16 v[6:9], v[200:203], v[192:195], v[6:9]
	v_mfma_f32_16x16x32_bf16 v[2:5], v[208:211], v[192:195], v[2:5]
	v_mfma_f32_16x16x32_bf16 v[30:33], v[204:207], v[172:175], v[30:33]
	v_mfma_f32_16x16x32_bf16 v[26:29], v[212:215], v[172:175], v[26:29]
	v_mfma_f32_16x16x32_bf16 v[22:25], v[204:207], v[180:183], v[22:25]
	v_mfma_f32_16x16x32_bf16 v[18:21], v[212:215], v[180:183], v[18:21]
	v_mfma_f32_16x16x32_bf16 v[14:17], v[204:207], v[188:191], v[14:17]
	v_mfma_f32_16x16x32_bf16 v[10:13], v[212:215], v[188:191], v[10:13]
	v_mfma_f32_16x16x32_bf16 v[6:9], v[204:207], v[196:199], v[6:9]
	v_mfma_f32_16x16x32_bf16 v[2:5], v[212:215], v[196:199], v[2:5]
	s_barrier
	ds_read_b128 v[152:155], v222
	ds_read_b128 v[156:159], v222 offset:1024
	ds_read_b128 v[160:163], v222 offset:2048
	ds_read_b128 v[164:167], v222 offset:3072
	ds_read_b128 v[168:171], v143 offset:32768
	ds_read_b128 v[172:175], v143 offset:33792
	ds_read_b128 v[176:179], v143 offset:34816
	ds_read_b128 v[180:183], v143 offset:35840
	ds_read_b128 v[184:187], v143 offset:36864
	ds_read_b128 v[188:191], v143 offset:37888
	ds_read_b128 v[192:195], v143 offset:38912
	ds_read_b128 v[196:199], v143 offset:39936
	s_mov_b32 m0, s43
	s_add_u32 s98, s12, s68
	s_addc_u32 s99, s13, s69
	global_load_lds_dwordx4 v131, s[98:99]
	s_mov_b32 m0, s44
	s_add_u32 s98, s12, s70
	s_addc_u32 s99, s13, s71
	global_load_lds_dwordx4 v131, s[98:99]
	s_waitcnt lgkmcnt(0)
	s_waitcnt vmcnt(10)
	s_barrier
	v_mfma_f32_16x16x32_bf16 v[126:129], v[152:155], v[168:171], v[126:129]
	v_mfma_f32_16x16x32_bf16 v[122:125], v[160:163], v[168:171], v[122:125]
	v_mfma_f32_16x16x32_bf16 v[118:121], v[152:155], v[176:179], v[118:121]
	v_mfma_f32_16x16x32_bf16 v[114:117], v[160:163], v[176:179], v[114:117]
	v_mfma_f32_16x16x32_bf16 v[110:113], v[152:155], v[184:187], v[110:113]
	v_mfma_f32_16x16x32_bf16 v[106:109], v[160:163], v[184:187], v[106:109]
	v_mfma_f32_16x16x32_bf16 v[102:105], v[152:155], v[192:195], v[102:105]
	v_mfma_f32_16x16x32_bf16 v[98:101], v[160:163], v[192:195], v[98:101]
	v_mfma_f32_16x16x32_bf16 v[126:129], v[156:159], v[172:175], v[126:129]
	v_mfma_f32_16x16x32_bf16 v[122:125], v[164:167], v[172:175], v[122:125]
	v_mfma_f32_16x16x32_bf16 v[118:121], v[156:159], v[180:183], v[118:121]
	v_mfma_f32_16x16x32_bf16 v[114:117], v[164:167], v[180:183], v[114:117]
	v_mfma_f32_16x16x32_bf16 v[110:113], v[156:159], v[188:191], v[110:113]
	v_mfma_f32_16x16x32_bf16 v[106:109], v[164:167], v[188:191], v[106:109]
	v_mfma_f32_16x16x32_bf16 v[102:105], v[156:159], v[196:199], v[102:105]
	v_mfma_f32_16x16x32_bf16 v[98:101], v[164:167], v[196:199], v[98:101]
	s_barrier
	ds_read_b128 v[200:203], v223
	ds_read_b128 v[204:207], v223 offset:1024
	ds_read_b128 v[208:211], v223 offset:2048
	ds_read_b128 v[212:215], v223 offset:3072
	s_mov_b32 m0, s45
	s_add_u32 s98, s14, s94
	s_addc_u32 s99, s15, s95
	global_load_lds_dwordx4 v131, s[98:99]
	s_mov_b32 m0, s46
	s_add_u32 s98, s14, s72
	s_addc_u32 s99, s15, s73
	global_load_lds_dwordx4 v131, s[98:99]
	s_waitcnt lgkmcnt(0)
	s_waitcnt vmcnt(10)
	s_barrier
	v_mfma_f32_16x16x32_bf16 v[94:97], v[200:203], v[168:171], v[94:97]
	v_mfma_f32_16x16x32_bf16 v[90:93], v[208:211], v[168:171], v[90:93]
	v_mfma_f32_16x16x32_bf16 v[86:89], v[200:203], v[176:179], v[86:89]
	v_mfma_f32_16x16x32_bf16 v[82:85], v[208:211], v[176:179], v[82:85]
	v_mfma_f32_16x16x32_bf16 v[78:81], v[200:203], v[184:187], v[78:81]
	v_mfma_f32_16x16x32_bf16 v[74:77], v[208:211], v[184:187], v[74:77]
	v_mfma_f32_16x16x32_bf16 v[70:73], v[200:203], v[192:195], v[70:73]
	v_mfma_f32_16x16x32_bf16 v[66:69], v[208:211], v[192:195], v[66:69]
	v_mfma_f32_16x16x32_bf16 v[94:97], v[204:207], v[172:175], v[94:97]
	v_mfma_f32_16x16x32_bf16 v[90:93], v[212:215], v[172:175], v[90:93]
	v_mfma_f32_16x16x32_bf16 v[86:89], v[204:207], v[180:183], v[86:89]
	v_mfma_f32_16x16x32_bf16 v[82:85], v[212:215], v[180:183], v[82:85]
	v_mfma_f32_16x16x32_bf16 v[78:81], v[204:207], v[188:191], v[78:81]
	v_mfma_f32_16x16x32_bf16 v[74:77], v[212:215], v[188:191], v[74:77]
	v_mfma_f32_16x16x32_bf16 v[70:73], v[204:207], v[196:199], v[70:73]
	v_mfma_f32_16x16x32_bf16 v[66:69], v[212:215], v[196:199], v[66:69]
	s_barrier
; #define LDA(dst, b, h) for (int m = 0; m < 4; ++m) for (int k = 0; k < 2; ++k) \
;     dst[m][k] = *reinterpret_cast<const bf16x8*>((char*)SA(b, h) + a_thr + (m * 2 + k) * 1024)
; #define LDB(dst, b, h) for (int n = 0; n < 2; ++n) for (int k = 0; k < 2; ++k) \
;     dst[n][k] = *reinterpret_cast<const bf16x8*>((char*)SB(b, h) + b_thr + (n * 2 + k) * 1024)
; #define MMA(ai, bj, At, Btf) do { __builtin_amdgcn_s_setprio(1); \
;     for (int m = 0; m < 4; ++m) for (int n = 0; n < 2; ++n) for (int k = 0; k < 2; ++k) \
;       acc[ai][bj][m][n] = __builtin_amdgcn_mfma_f32_16x16x32_bf16(Btf[n][k], At[m][k], acc[ai][bj][m][n], 0, 0, 0); \
;     __builtin_amdgcn_s_setprio(0); } while (0)
; #define WAIT_V(n) asm volatile("s_waitcnt vmcnt(" #n ")" ::: "memory")
; #define WAIT_L(n) asm volatile("s_waitcnt lgkmcnt(" #n ")" ::: "memory")
; #define BAR __builtin_amdgcn_s_barrier()
; #define SCHED __builtin_amdgcn_sched_barrier(0)
; template <bool OVL, bool PANEL = false, class Epi>
; __device__ __forceinline__ void gemm_phase(const bf16_t* __restrict__ A, long lda, const bf16_t* __restrict__ Bt, long ldb, int nM, int nN, int K,
;                                            const Epi& epi, bf16_t* shm, int w0) {
;     ...
;       LDA(At, 1, 1); STAGE(SA(1, 0), A, lda, aoff, brow, t + 3);
;       BAR; WAIT_L(0); MMA(1, 0, At, B0); BAR; SCHED;
;       STAGE(SB(1, 1), Bt, ldb, boff, bcol + HALF, t + 3);
;       WAIT_V(6); BAR; MMA(1, 1, At, B1); BAR;
;     }
;     { LDB(B0, 0, 0); LDA(At, 0, 0); STAGE(SA(1, 1), A, lda, aoff, brow + HALF, nt - 1);
	ds_read_b128 v[168:171], v143 offset:49152
	ds_read_b128 v[172:175], v143 offset:50176
	ds_read_b128 v[176:179], v143 offset:51200
	ds_read_b128 v[180:183], v143 offset:52224
	ds_read_b128 v[184:187], v143 offset:53248
	ds_read_b128 v[188:191], v143 offset:54272
	ds_read_b128 v[192:195], v143 offset:55296
	ds_read_b128 v[196:199], v143 offset:56320
	s_mov_b32 m0, s47
	s_add_u32 s98, s12, s94
	s_addc_u32 s99, s13, s95
	global_load_lds_dwordx4 v131, s[98:99]
	s_mov_b32 m0, s48
	s_add_u32 s98, s12, s72
	s_addc_u32 s99, s13, s73
	global_load_lds_dwordx4 v131, s[98:99]
	s_waitcnt lgkmcnt(0)
	s_barrier
	v_mfma_f32_16x16x32_bf16 v[62:65], v[152:155], v[168:171], v[62:65]
	v_mfma_f32_16x16x32_bf16 v[58:61], v[160:163], v[168:171], v[58:61]
	v_mfma_f32_16x16x32_bf16 v[54:57], v[152:155], v[176:179], v[54:57]
	v_mfma_f32_16x16x32_bf16 v[50:53], v[160:163], v[176:179], v[50:53]
	v_mfma_f32_16x16x32_bf16 v[46:49], v[152:155], v[184:187], v[46:49]
	v_mfma_f32_16x16x32_bf16 v[42:45], v[160:163], v[184:187], v[42:45]
	v_mfma_f32_16x16x32_bf16 v[38:41], v[152:155], v[192:195], v[38:41]
	v_mfma_f32_16x16x32_bf16 v[34:37], v[160:163], v[192:195], v[34:37]
	v_mfma_f32_16x16x32_bf16 v[62:65], v[156:159], v[172:175], v[62:65]
	v_mfma_f32_16x16x32_bf16 v[58:61], v[164:167], v[172:175], v[58:61]
	v_mfma_f32_16x16x32_bf16 v[54:57], v[156:159], v[180:183], v[54:57]
	v_mfma_f32_16x16x32_bf16 v[50:53], v[164:167], v[180:183], v[50:53]
	v_mfma_f32_16x16x32_bf16 v[46:49], v[156:159], v[188:191], v[46:49]
	v_mfma_f32_16x16x32_bf16 v[42:45], v[164:167], v[188:191], v[42:45]
	v_mfma_f32_16x16x32_bf16 v[38:41], v[156:159], v[196:199], v[38:41]
	v_mfma_f32_16x16x32_bf16 v[34:37], v[164:167], v[196:199], v[34:37]
	s_barrier
	s_mov_b32 m0, s49
	s_add_u32 s98, s14, s26
	s_addc_u32 s99, s15, s27
	global_load_lds_dwordx4 v131, s[98:99]
	s_mov_b32 m0, s50
	s_add_u32 s98, s14, s28
	s_addc_u32 s99, s15, s29
	global_load_lds_dwordx4 v131, s[98:99]
	s_add_i32 s21, s21, 2
	s_add_u32 s10, s10, 0x100
	s_addc_u32 s11, s11, 0
	s_cmp_lt_u32 s21, 12
	s_waitcnt vmcnt(10)
	s_barrier
	v_mfma_f32_16x16x32_bf16 v[30:33], v[200:203], v[168:171], v[30:33]
	v_mfma_f32_16x16x32_bf16 v[26:29], v[208:211], v[168:171], v[26:29]
	v_mfma_f32_16x16x32_bf16 v[22:25], v[200:203], v[176:179], v[22:25]
	v_mfma_f32_16x16x32_bf16 v[18:21], v[208:211], v[176:179], v[18:21]
	v_mfma_f32_16x16x32_bf16 v[14:17], v[200:203], v[184:187], v[14:17]
	v_mfma_f32_16x16x32_bf16 v[10:13], v[208:211], v[184:187], v[10:13]
	v_mfma_f32_16x16x32_bf16 v[6:9], v[200:203], v[192:195], v[6:9]
	v_mfma_f32_16x16x32_bf16 v[2:5], v[208:211], v[192:195], v[2:5]
	v_mfma_f32_16x16x32_bf16 v[30:33], v[204:207], v[172:175], v[30:33]
	v_mfma_f32_16x16x32_bf16 v[26:29], v[212:215], v[172:175], v[26:29]
	v_mfma_f32_16x16x32_bf16 v[22:25], v[204:207], v[180:183], v[22:25]
	v_mfma_f32_16x16x32_bf16 v[18:21], v[212:215], v[180:183], v[18:21]
	v_mfma_f32_16x16x32_bf16 v[14:17], v[204:207], v[188:191], v[14:17]
	v_mfma_f32_16x16x32_bf16 v[10:13], v[212:215], v[188:191], v[10:13]
	v_mfma_f32_16x16x32_bf16 v[6:9], v[204:207], v[196:199], v[6:9]
	v_mfma_f32_16x16x32_bf16 v[2:5], v[212:215], v[196:199], v[2:5]
	s_barrier
	s_cbranch_scc1 .LBB0_410
	s_waitcnt vmcnt(6)
	v_add_u32_e32 v212, 16, v140
	v_add_u32_e32 v0, 0x10000, v212
	ds_read_b128 v[144:147], v0
	ds_read_b128 v[152:155], v0 offset:1024
	ds_read_b128 v[156:159], v0 offset:2048
	ds_read_b128 v[160:163], v0 offset:3072
	ds_read_b128 v[164:167], v143
	ds_read_b128 v[168:171], v143 offset:1024
	ds_read_b128 v[172:175], v143 offset:2048
	ds_read_b128 v[176:179], v143 offset:3072
	ds_read_b128 v[180:183], v143 offset:4096
	ds_read_b128 v[184:187], v143 offset:5120
	ds_read_b128 v[188:191], v143 offset:6144
	ds_read_b128 v[192:195], v143 offset:7168
	v_mov_b32_e32 v0, v131
	s_mov_b64 s[0:1], 0x40780
	v_lshl_add_u64 v[148:149], s[8:9], 0, v[0:1]
	v_lshl_add_u64 v[196:197], v[148:149], 0, s[0:1]
	v_readfirstlane_b32 s0, v150
	s_mov_b32 m0, s0
	s_mov_b64 s[0:1], 0x60780
	v_lshl_add_u64 v[148:149], v[148:149], 0, s[0:1]
	v_readfirstlane_b32 s0, v151
	global_load_lds_dwordx4 v[196:197], off
	s_mov_b32 m0, s0
	s_nop 0
	global_load_lds_dwordx4 v[148:149], off
	s_barrier
	s_waitcnt lgkmcnt(0)

; #define MMA(ai, bj, At, Btf) do { __builtin_amdgcn_s_setprio(1); \
;     for (int m = 0; m < 4; ++m) for (int n = 0; n < 2; ++n) for (int k = 0; k < 2; ++k) \
;       acc[ai][bj][m][n] = __builtin_amdgcn_mfma_f32_16x16x32_bf16(Btf[n][k], At[m][k], acc[ai][bj][m][n], 0, 0, 0); \
;     __builtin_amdgcn_s_setprio(0); } while (0)
; #define WAIT_L(n) asm volatile("s_waitcnt lgkmcnt(" #n ")" ::: "memory")
; #define BAR __builtin_amdgcn_s_barrier()
; template <bool OVL, bool PANEL = false, class Epi>
; __device__ __forceinline__ void gemm_phase(const bf16_t* __restrict__ A, long lda, const bf16_t* __restrict__ Bt, long ldb, int nM, int nN, int K,
;                                            const Epi& epi, bf16_t* shm, int w0) {
;     ...
;       BAR; WAIT_L(0); MMA(0, 0, At, B0); BAR;
	s_waitcnt lgkmcnt(0)
	v_mfma_f32_16x16x32_bf16 v[126:129], v[144:147], v[164:167], v[126:129]
	v_mfma_f32_16x16x32_bf16 v[122:125], v[156:159], v[164:167], v[122:125]
	v_mfma_f32_16x16x32_bf16 v[118:121], v[144:147], v[172:175], v[118:121]
	v_mfma_f32_16x16x32_bf16 v[114:117], v[156:159], v[172:175], v[114:117]
	v_mfma_f32_16x16x32_bf16 v[110:113], v[144:147], v[180:183], v[110:113]
	v_mfma_f32_16x16x32_bf16 v[106:109], v[156:159], v[180:183], v[106:109]
	v_mfma_f32_16x16x32_bf16 v[102:105], v[144:147], v[188:191], v[102:105]
	v_mfma_f32_16x16x32_bf16 v[126:129], v[152:155], v[168:171], v[126:129]
	v_mfma_f32_16x16x32_bf16 v[122:125], v[160:163], v[168:171], v[122:125]
	v_mfma_f32_16x16x32_bf16 v[118:121], v[152:155], v[176:179], v[118:121]
	v_mfma_f32_16x16x32_bf16 v[114:117], v[160:163], v[176:179], v[114:117]
	v_mfma_f32_16x16x32_bf16 v[110:113], v[152:155], v[184:187], v[110:113]
	v_mfma_f32_16x16x32_bf16 v[106:109], v[160:163], v[184:187], v[106:109]
	v_mfma_f32_16x16x32_bf16 v[102:105], v[152:155], v[192:195], v[102:105]
	v_mfma_f32_16x16x32_bf16 v[98:101], v[156:159], v[188:191], v[98:101]
	v_mfma_f32_16x16x32_bf16 v[148:151], v[160:163], v[192:195], v[98:101]

; #define LDB(dst, b, h) for (int n = 0; n < 2; ++n) for (int k = 0; k < 2; ++k) \
;     dst[n][k] = *reinterpret_cast<const bf16x8*>((char*)SB(b, h) + b_thr + (n * 2 + k) * 1024)
; #define MMA(ai, bj, At, Btf) do { __builtin_amdgcn_s_setprio(1); \
;     for (int m = 0; m < 4; ++m) for (int n = 0; n < 2; ++n) for (int k = 0; k < 2; ++k) \
;       acc[ai][bj][m][n] = __builtin_amdgcn_mfma_f32_16x16x32_bf16(Btf[n][k], At[m][k], acc[ai][bj][m][n], 0, 0, 0); \
;     __builtin_amdgcn_s_setprio(0); } while (0)
; #define WAIT_L(n) asm volatile("s_waitcnt lgkmcnt(" #n ")" ::: "memory")
; #define BAR __builtin_amdgcn_s_barrier()
; template <bool OVL, bool PANEL = false, class Epi>
; __device__ __forceinline__ void gemm_phase(const bf16_t* __restrict__ A, long lda, const bf16_t* __restrict__ Bt, long ldb, int nM, int nN, int K,
;                                            const Epi& epi, bf16_t* shm, int w0) {
;     ...
;       LDB(B1, 0, 1); BAR; WAIT_L(0); MMA(0, 1, At, B1); BAR;
	v_add_u32_e32 v0, 0x14000, v212
	s_barrier
	s_nop 3
	ds_read_b128 v[98:101], v0
	ds_read_b128 v[196:199], v0 offset:1024
	ds_read_b128 v[200:203], v0 offset:2048
	ds_read_b128 v[204:207], v0 offset:3072
	s_barrier
	s_waitcnt lgkmcnt(0)

; #define LDB(dst, b, h) for (int n = 0; n < 2; ++n) for (int k = 0; k < 2; ++k) \
;     dst[n][k] = *reinterpret_cast<const bf16x8*>((char*)SB(b, h) + b_thr + (n * 2 + k) * 1024)
; #define MMA(ai, bj, At, Btf) do { __builtin_amdgcn_s_setprio(1); \
;     for (int m = 0; m < 4; ++m) for (int n = 0; n < 2; ++n) for (int k = 0; k < 2; ++k) \
;       acc[ai][bj][m][n] = __builtin_amdgcn_mfma_f32_16x16x32_bf16(Btf[n][k], At[m][k], acc[ai][bj][m][n], 0, 0, 0); \
;     __builtin_amdgcn_s_setprio(0); } while (0)
; #define WAIT_L(n) asm volatile("s_waitcnt lgkmcnt(" #n ")" ::: "memory")
; #define BAR __builtin_amdgcn_s_barrier()
; template <bool OVL, bool PANEL = false, class Epi>
; __device__ __forceinline__ void gemm_phase(const bf16_t* __restrict__ A, long lda, const bf16_t* __restrict__ Bt, long ldb, int nM, int nN, int K,
;                                            const Epi& epi, bf16_t* shm, int w0) {
;     ...
;       LDB(B1, 0, 1); BAR; WAIT_L(0); MMA(0, 1, At, B1); BAR;
	s_waitcnt lgkmcnt(0)
	v_mfma_f32_16x16x32_bf16 v[94:97], v[98:101], v[164:167], v[94:97]
	v_mfma_f32_16x16x32_bf16 v[86:89], v[98:101], v[172:175], v[86:89]
	v_mfma_f32_16x16x32_bf16 v[82:85], v[200:203], v[172:175], v[82:85]
	v_mfma_f32_16x16x32_bf16 v[78:81], v[98:101], v[180:183], v[78:81]
	v_mfma_f32_16x16x32_bf16 v[74:77], v[200:203], v[180:183], v[74:77]
	v_mfma_f32_16x16x32_bf16 v[94:97], v[196:199], v[168:171], v[94:97]
	v_mfma_f32_16x16x32_bf16 v[90:93], v[200:203], v[164:167], v[90:93]
	v_mfma_f32_16x16x32_bf16 v[86:89], v[196:199], v[176:179], v[86:89]
	v_mfma_f32_16x16x32_bf16 v[82:85], v[204:207], v[176:179], v[82:85]
	v_mfma_f32_16x16x32_bf16 v[78:81], v[196:199], v[184:187], v[78:81]
	v_mfma_f32_16x16x32_bf16 v[74:77], v[204:207], v[184:187], v[74:77]
	v_mfma_f32_16x16x32_bf16 v[70:73], v[98:101], v[188:191], v[70:73]
	v_mfma_f32_16x16x32_bf16 v[66:69], v[200:203], v[188:191], v[66:69]
	v_mfma_f32_16x16x32_bf16 v[164:167], v[204:207], v[168:171], v[90:93]
	v_mfma_f32_16x16x32_bf16 v[168:171], v[196:199], v[192:195], v[70:73]
	v_mfma_f32_16x16x32_bf16 v[172:175], v[204:207], v[192:195], v[66:69]

; #define LDA(dst, b, h) for (int m = 0; m < 4; ++m) for (int k = 0; k < 2; ++k) \
;     dst[m][k] = *reinterpret_cast<const bf16x8*>((char*)SA(b, h) + a_thr + (m * 2 + k) * 1024)
; #define MMA(ai, bj, At, Btf) do { __builtin_amdgcn_s_setprio(1); \
;     for (int m = 0; m < 4; ++m) for (int n = 0; n < 2; ++n) for (int k = 0; k < 2; ++k) \
;       acc[ai][bj][m][n] = __builtin_amdgcn_mfma_f32_16x16x32_bf16(Btf[n][k], At[m][k], acc[ai][bj][m][n], 0, 0, 0); \
;     __builtin_amdgcn_s_setprio(0); } while (0)
; #define WAIT_V(n) asm volatile("s_waitcnt vmcnt(" #n ")" ::: "memory")
; #define WAIT_L(n) asm volatile("s_waitcnt lgkmcnt(" #n ")" ::: "memory")
; #define BAR __builtin_amdgcn_s_barrier()
; template <bool OVL, bool PANEL = false, class Epi>
; __device__ __forceinline__ void gemm_phase(const bf16_t* __restrict__ A, long lda, const bf16_t* __restrict__ Bt, long ldb, int nM, int nN, int K,
;                                            const Epi& epi, bf16_t* shm, int w0) {
;     ...
;       LDA(At, 0, 1); WAIT_V(4); BAR; WAIT_L(0); MMA(1, 0, At, B0); MMA(1, 1, At, B1); BAR; }
	s_barrier
	s_nop 2
	ds_read_b128 v[66:69], v143 offset:16384
	ds_read_b128 v[70:73], v143 offset:17408
	ds_read_b128 v[90:93], v143 offset:18432
	ds_read_b128 v[176:179], v143 offset:19456
	ds_read_b128 v[180:183], v143 offset:20480
	ds_read_b128 v[184:187], v143 offset:21504
	ds_read_b128 v[188:191], v143 offset:22528
	ds_read_b128 v[192:195], v143 offset:23552
	s_waitcnt vmcnt(4)
	s_barrier
	s_waitcnt lgkmcnt(0)

; #define LDA(dst, b, h) for (int m = 0; m < 4; ++m) for (int k = 0; k < 2; ++k) \
;     dst[m][k] = *reinterpret_cast<const bf16x8*>((char*)SA(b, h) + a_thr + (m * 2 + k) * 1024)
; #define MMA(ai, bj, At, Btf) do { __builtin_amdgcn_s_setprio(1); \
;     for (int m = 0; m < 4; ++m) for (int n = 0; n < 2; ++n) for (int k = 0; k < 2; ++k) \
;       acc[ai][bj][m][n] = __builtin_amdgcn_mfma_f32_16x16x32_bf16(Btf[n][k], At[m][k], acc[ai][bj][m][n], 0, 0, 0); \
;     __builtin_amdgcn_s_setprio(0); } while (0)
; #define WAIT_V(n) asm volatile("s_waitcnt vmcnt(" #n ")" ::: "memory")
; #define WAIT_L(n) asm volatile("s_waitcnt lgkmcnt(" #n ")" ::: "memory")
; #define BAR __builtin_amdgcn_s_barrier()
; template <bool OVL, bool PANEL = false, class Epi>
; __device__ __forceinline__ void gemm_phase(const bf16_t* __restrict__ A, long lda, const bf16_t* __restrict__ Bt, long ldb, int nM, int nN, int K,
;                                            const Epi& epi, bf16_t* shm, int w0) {
;     ...
;       LDA(At, 0, 1); WAIT_V(4); BAR; WAIT_L(0); MMA(1, 0, At, B0); MMA(1, 1, At, B1); BAR; }
	s_waitcnt lgkmcnt(0)
	v_mfma_f32_16x16x32_bf16 v[62:65], v[144:147], v[66:69], v[62:65]
	v_mfma_f32_16x16x32_bf16 v[54:57], v[144:147], v[90:93], v[54:57]
	v_mfma_f32_16x16x32_bf16 v[50:53], v[156:159], v[90:93], v[50:53]
	v_mfma_f32_16x16x32_bf16 v[46:49], v[144:147], v[180:183], v[46:49]
	v_mfma_f32_16x16x32_bf16 v[42:45], v[156:159], v[180:183], v[42:45]
	v_mfma_f32_16x16x32_bf16 v[38:41], v[144:147], v[188:191], v[38:41]
	v_mfma_f32_16x16x32_bf16 v[34:37], v[156:159], v[188:191], v[34:37]
	v_mfma_f32_16x16x32_bf16 v[62:65], v[152:155], v[70:73], v[62:65]
	v_mfma_f32_16x16x32_bf16 v[58:61], v[156:159], v[66:69], v[58:61]
	v_mfma_f32_16x16x32_bf16 v[54:57], v[152:155], v[176:179], v[54:57]
	v_mfma_f32_16x16x32_bf16 v[50:53], v[160:163], v[176:179], v[50:53]
	v_mfma_f32_16x16x32_bf16 v[46:49], v[152:155], v[184:187], v[46:49]
	v_mfma_f32_16x16x32_bf16 v[42:45], v[160:163], v[184:187], v[42:45]
	v_mfma_f32_16x16x32_bf16 v[38:41], v[152:155], v[192:195], v[38:41]
	v_mfma_f32_16x16x32_bf16 v[34:37], v[160:163], v[192:195], v[34:37]
	v_mfma_f32_16x16x32_bf16 v[208:211], v[160:163], v[70:73], v[58:61]


; #define LDA(dst, b, h) for (int m = 0; m < 4; ++m) for (int k = 0; k < 2; ++k) \
;     dst[m][k] = *reinterpret_cast<const bf16x8*>((char*)SA(b, h) + a_thr + (m * 2 + k) * 1024)
; #define MMA(ai, bj, At, Btf) do { __builtin_amdgcn_s_setprio(1); \
;     for (int m = 0; m < 4; ++m) for (int n = 0; n < 2; ++n) for (int k = 0; k < 2; ++k) \
;       acc[ai][bj][m][n] = __builtin_amdgcn_mfma_f32_16x16x32_bf16(Btf[n][k], At[m][k], acc[ai][bj][m][n], 0, 0, 0); \
;     __builtin_amdgcn_s_setprio(0); } while (0)
; #define WAIT_V(n) asm volatile("s_waitcnt vmcnt(" #n ")" ::: "memory")
; #define WAIT_L(n) asm volatile("s_waitcnt lgkmcnt(" #n ")" ::: "memory")
; #define BAR __builtin_amdgcn_s_barrier()
; template <bool OVL, bool PANEL = false, class Epi>
; __device__ __forceinline__ void gemm_phase(const bf16_t* __restrict__ A, long lda, const bf16_t* __restrict__ Bt, long ldb, int nM, int nN, int K,
;                                            const Epi& epi, bf16_t* shm, int w0) {
;     ...
;       LDA(At, 0, 1); WAIT_V(4); BAR; WAIT_L(0); MMA(1, 0, At, B0); MMA(1, 1, At, B1); BAR; }
	v_mfma_f32_16x16x32_bf16 v[30:33], v[98:101], v[66:69], v[30:33]
	v_mfma_f32_16x16x32_bf16 v[26:29], v[200:203], v[66:69], v[26:29]
	v_mfma_f32_16x16x32_bf16 v[22:25], v[98:101], v[90:93], v[22:25]
	v_mfma_f32_16x16x32_bf16 v[18:21], v[200:203], v[90:93], v[18:21]
	v_mfma_f32_16x16x32_bf16 v[14:17], v[98:101], v[180:183], v[14:17]
	v_mfma_f32_16x16x32_bf16 v[10:13], v[200:203], v[180:183], v[10:13]
	v_mfma_f32_16x16x32_bf16 v[6:9], v[98:101], v[188:191], v[6:9]
	v_mfma_f32_16x16x32_bf16 v[2:5], v[200:203], v[188:191], v[2:5]
	v_mfma_f32_16x16x32_bf16 v[30:33], v[196:199], v[70:73], v[30:33]
	v_mfma_f32_16x16x32_bf16 v[26:29], v[204:207], v[70:73], v[26:29]
	v_mfma_f32_16x16x32_bf16 v[22:25], v[196:199], v[176:179], v[22:25]
	v_mfma_f32_16x16x32_bf16 v[18:21], v[204:207], v[176:179], v[18:21]
	v_mfma_f32_16x16x32_bf16 v[14:17], v[196:199], v[184:187], v[14:17]
	v_mfma_f32_16x16x32_bf16 v[10:13], v[204:207], v[184:187], v[10:13]
	v_mfma_f32_16x16x32_bf16 v[6:9], v[196:199], v[192:195], v[6:9]
	v_mfma_f32_16x16x32_bf16 v[2:5], v[204:207], v[192:195], v[2:5]

; #define LDA(dst, b, h) for (int m = 0; m < 4; ++m) for (int k = 0; k < 2; ++k) \
;     dst[m][k] = *reinterpret_cast<const bf16x8*>((char*)SA(b, h) + a_thr + (m * 2 + k) * 1024)
; #define LDB(dst, b, h) for (int n = 0; n < 2; ++n) for (int k = 0; k < 2; ++k) \
;     dst[n][k] = *reinterpret_cast<const bf16x8*>((char*)SB(b, h) + b_thr + (n * 2 + k) * 1024)
; #define MMA(ai, bj, At, Btf) do { __builtin_amdgcn_s_setprio(1); \
;     for (int m = 0; m < 4; ++m) for (int n = 0; n < 2; ++n) for (int k = 0; k < 2; ++k) \
;       acc[ai][bj][m][n] = __builtin_amdgcn_mfma_f32_16x16x32_bf16(Btf[n][k], At[m][k], acc[ai][bj][m][n], 0, 0, 0); \
;     __builtin_amdgcn_s_setprio(0); } while (0)
; #define WAIT_V(n) asm volatile("s_waitcnt vmcnt(" #n ")" ::: "memory")
; #define WAIT_L(n) asm volatile("s_waitcnt lgkmcnt(" #n ")" ::: "memory")
; #define BAR __builtin_amdgcn_s_barrier()
; template <bool OVL, bool PANEL = false, class Epi>
; __device__ __forceinline__ void gemm_phase(const bf16_t* __restrict__ A, long lda, const bf16_t* __restrict__ Bt, long ldb, int nM, int nN, int K,
;                                            const Epi& epi, bf16_t* shm, int w0) {
;     ...
;     { LDB(B0, 1, 0); LDA(At, 1, 0); WAIT_V(2); BAR; WAIT_L(0); MMA(0, 0, At, B0); BAR;
	v_add_u32_e32 v0, 0x18000, v212
	s_barrier
	ds_read_b128 v[144:147], v0
	ds_read_b128 v[152:155], v0 offset:1024
	ds_read_b128 v[156:159], v0 offset:2048
	ds_read_b128 v[160:163], v0 offset:3072
	ds_read_b128 v[58:61], v143 offset:32768
	ds_read_b128 v[66:69], v143 offset:33792
	ds_read_b128 v[70:73], v143 offset:34816
	ds_read_b128 v[176:179], v143 offset:35840
	ds_read_b128 v[180:183], v143 offset:36864
	ds_read_b128 v[184:187], v143 offset:37888
	ds_read_b128 v[188:191], v143 offset:38912
	ds_read_b128 v[192:195], v143 offset:39936
	s_waitcnt vmcnt(2)
	s_barrier
	s_waitcnt lgkmcnt(0)

; #define LDA(dst, b, h) for (int m = 0; m < 4; ++m) for (int k = 0; k < 2; ++k) \
;     dst[m][k] = *reinterpret_cast<const bf16x8*>((char*)SA(b, h) + a_thr + (m * 2 + k) * 1024)
; #define LDB(dst, b, h) for (int n = 0; n < 2; ++n) for (int k = 0; k < 2; ++k) \
;     dst[n][k] = *reinterpret_cast<const bf16x8*>((char*)SB(b, h) + b_thr + (n * 2 + k) * 1024)
; #define MMA(ai, bj, At, Btf) do { __builtin_amdgcn_s_setprio(1); \
;     for (int m = 0; m < 4; ++m) for (int n = 0; n < 2; ++n) for (int k = 0; k < 2; ++k) \
;       acc[ai][bj][m][n] = __builtin_amdgcn_mfma_f32_16x16x32_bf16(Btf[n][k], At[m][k], acc[ai][bj][m][n], 0, 0, 0); \
;     __builtin_amdgcn_s_setprio(0); } while (0)
; #define WAIT_V(n) asm volatile("s_waitcnt vmcnt(" #n ")" ::: "memory")
; #define WAIT_L(n) asm volatile("s_waitcnt lgkmcnt(" #n ")" ::: "memory")
; #define BAR __builtin_amdgcn_s_barrier()
; template <bool OVL, bool PANEL = false, class Epi>
; __device__ __forceinline__ void gemm_phase(const bf16_t* __restrict__ A, long lda, const bf16_t* __restrict__ Bt, long ldb, int nM, int nN, int K,
;                                            const Epi& epi, bf16_t* shm, int w0) {
;     ...
;     { LDB(B0, 1, 0); LDA(At, 1, 0); WAIT_V(2); BAR; WAIT_L(0); MMA(0, 0, At, B0); BAR;
	s_waitcnt lgkmcnt(0)
	v_mfma_f32_16x16x32_bf16 v[90:93], v[144:147], v[58:61], v[126:129]
	v_mfma_f32_16x16x32_bf16 v[126:129], v[152:155], v[66:69], v[90:93]
	v_mfma_f32_16x16x32_bf16 v[90:93], v[156:159], v[58:61], v[122:125]
	v_mfma_f32_16x16x32_bf16 v[122:125], v[160:163], v[66:69], v[90:93]
	v_mfma_f32_16x16x32_bf16 v[90:93], v[144:147], v[70:73], v[118:121]
	v_mfma_f32_16x16x32_bf16 v[118:121], v[152:155], v[176:179], v[90:93]
	v_mfma_f32_16x16x32_bf16 v[90:93], v[156:159], v[70:73], v[114:117]
	v_mfma_f32_16x16x32_bf16 v[114:117], v[160:163], v[176:179], v[90:93]
	v_mfma_f32_16x16x32_bf16 v[90:93], v[144:147], v[180:183], v[110:113]
	v_mfma_f32_16x16x32_bf16 v[110:113], v[152:155], v[184:187], v[90:93]
	v_mfma_f32_16x16x32_bf16 v[90:93], v[156:159], v[180:183], v[106:109]
	v_mfma_f32_16x16x32_bf16 v[106:109], v[160:163], v[184:187], v[90:93]
	v_mfma_f32_16x16x32_bf16 v[90:93], v[144:147], v[188:191], v[102:105]
	v_mfma_f32_16x16x32_bf16 v[98:101], v[152:155], v[192:195], v[90:93]
	v_mfma_f32_16x16x32_bf16 v[90:93], v[156:159], v[188:191], v[148:151]
	v_mfma_f32_16x16x32_bf16 v[90:93], v[160:163], v[192:195], v[90:93]

; #define LDB(dst, b, h) for (int n = 0; n < 2; ++n) for (int k = 0; k < 2; ++k) \
;     dst[n][k] = *reinterpret_cast<const bf16x8*>((char*)SB(b, h) + b_thr + (n * 2 + k) * 1024)
; #define MMA(ai, bj, At, Btf) do { __builtin_amdgcn_s_setprio(1); \
;     for (int m = 0; m < 4; ++m) for (int n = 0; n < 2; ++n) for (int k = 0; k < 2; ++k) \
;       acc[ai][bj][m][n] = __builtin_amdgcn_mfma_f32_16x16x32_bf16(Btf[n][k], At[m][k], acc[ai][bj][m][n], 0, 0, 0); \
;     __builtin_amdgcn_s_setprio(0); } while (0)
; #define WAIT_V(n) asm volatile("s_waitcnt vmcnt(" #n ")" ::: "memory")
; #define WAIT_L(n) asm volatile("s_waitcnt lgkmcnt(" #n ")" ::: "memory")
; #define BAR __builtin_amdgcn_s_barrier()
; template <bool OVL, bool PANEL = false, class Epi>
; __device__ __forceinline__ void gemm_phase(const bf16_t* __restrict__ A, long lda, const bf16_t* __restrict__ Bt, long ldb, int nM, int nN, int K,
;                                            const Epi& epi, bf16_t* shm, int w0) {
;     ...
;       LDB(B1, 1, 1); WAIT_V(0); BAR; WAIT_L(0); MMA(0, 1, At, B1); BAR;
	v_add_u32_e32 v0, 0x1c000, v212
	s_barrier
	ds_read_b128 v[148:151], v0
	ds_read_b128 v[196:199], v0 offset:1024
	ds_read_b128 v[200:203], v0 offset:2048
	ds_read_b128 v[204:207], v0 offset:3072
	s_waitcnt vmcnt(0)
	s_barrier
	s_waitcnt lgkmcnt(0)

; #define LDB(dst, b, h) for (int n = 0; n < 2; ++n) for (int k = 0; k < 2; ++k) \
;     dst[n][k] = *reinterpret_cast<const bf16x8*>((char*)SB(b, h) + b_thr + (n * 2 + k) * 1024)
; #define MMA(ai, bj, At, Btf) do { __builtin_amdgcn_s_setprio(1); \
;     for (int m = 0; m < 4; ++m) for (int n = 0; n < 2; ++n) for (int k = 0; k < 2; ++k) \
;       acc[ai][bj][m][n] = __builtin_amdgcn_mfma_f32_16x16x32_bf16(Btf[n][k], At[m][k], acc[ai][bj][m][n], 0, 0, 0); \
;     __builtin_amdgcn_s_setprio(0); } while (0)
; #define WAIT_V(n) asm volatile("s_waitcnt vmcnt(" #n ")" ::: "memory")
; #define WAIT_L(n) asm volatile("s_waitcnt lgkmcnt(" #n ")" ::: "memory")
; #define BAR __builtin_amdgcn_s_barrier()
; template <bool OVL, bool PANEL = false, class Epi>
; __device__ __forceinline__ void gemm_phase(const bf16_t* __restrict__ A, long lda, const bf16_t* __restrict__ Bt, long ldb, int nM, int nN, int K,
;                                            const Epi& epi, bf16_t* shm, int w0) {
;     ...
;       LDB(B1, 1, 1); WAIT_V(0); BAR; WAIT_L(0); MMA(0, 1, At, B1); BAR;
	s_waitcnt lgkmcnt(0)
	v_mfma_f32_16x16x32_bf16 v[94:97], v[148:151], v[58:61], v[94:97]
	v_mfma_f32_16x16x32_bf16 v[58:61], v[200:203], v[58:61], v[164:167]
	v_mfma_f32_16x16x32_bf16 v[102:105], v[196:199], v[66:69], v[94:97]
	v_mfma_f32_16x16x32_bf16 v[94:97], v[204:207], v[66:69], v[58:61]
	v_mfma_f32_16x16x32_bf16 v[58:61], v[148:151], v[70:73], v[86:89]
	v_mfma_f32_16x16x32_bf16 v[86:89], v[196:199], v[176:179], v[58:61]
	v_mfma_f32_16x16x32_bf16 v[58:61], v[200:203], v[70:73], v[82:85]
	v_mfma_f32_16x16x32_bf16 v[82:85], v[204:207], v[176:179], v[58:61]
	v_mfma_f32_16x16x32_bf16 v[58:61], v[148:151], v[180:183], v[78:81]
	v_mfma_f32_16x16x32_bf16 v[78:81], v[196:199], v[184:187], v[58:61]
	v_mfma_f32_16x16x32_bf16 v[58:61], v[200:203], v[180:183], v[74:77]
	v_mfma_f32_16x16x32_bf16 v[70:73], v[204:207], v[184:187], v[58:61]
	v_mfma_f32_16x16x32_bf16 v[58:61], v[148:151], v[188:191], v[168:171]
	v_mfma_f32_16x16x32_bf16 v[66:69], v[196:199], v[192:195], v[58:61]
	v_mfma_f32_16x16x32_bf16 v[58:61], v[200:203], v[188:191], v[172:175]
	v_mfma_f32_16x16x32_bf16 v[58:61], v[204:207], v[192:195], v[58:61]

; #define LDA(dst, b, h) for (int m = 0; m < 4; ++m) for (int k = 0; k < 2; ++k) \
;     dst[m][k] = *reinterpret_cast<const bf16x8*>((char*)SA(b, h) + a_thr + (m * 2 + k) * 1024)
; #define MMA(ai, bj, At, Btf) do { __builtin_amdgcn_s_setprio(1); \
;     for (int m = 0; m < 4; ++m) for (int n = 0; n < 2; ++n) for (int k = 0; k < 2; ++k) \
;       acc[ai][bj][m][n] = __builtin_amdgcn_mfma_f32_16x16x32_bf16(Btf[n][k], At[m][k], acc[ai][bj][m][n], 0, 0, 0); \
;     __builtin_amdgcn_s_setprio(0); } while (0)
; #define WAIT_L(n) asm volatile("s_waitcnt lgkmcnt(" #n ")" ::: "memory")
; #define BAR __builtin_amdgcn_s_barrier()
; template <bool OVL, bool PANEL = false, class Epi>
; __device__ __forceinline__ void gemm_phase(const bf16_t* __restrict__ A, long lda, const bf16_t* __restrict__ Bt, long ldb, int nM, int nN, int K,
;                                            const Epi& epi, bf16_t* shm, int w0) {
;     ...
;       LDA(At, 1, 1); BAR; WAIT_L(0); MMA(1, 0, At, B0); MMA(1, 1, At, B1); BAR; }
	s_barrier
	ds_read_b128 v[164:167], v143 offset:49152
	ds_read_b128 v[168:171], v143 offset:50176
	ds_read_b128 v[172:175], v143 offset:51200
	ds_read_b128 v[176:179], v143 offset:52224
	ds_read_b128 v[180:183], v143 offset:53248
	ds_read_b128 v[184:187], v143 offset:54272
	ds_read_b128 v[188:191], v143 offset:55296
	ds_read_b128 v[192:195], v143 offset:56320
	s_barrier
	s_waitcnt lgkmcnt(0)

; #define LDA(dst, b, h) for (int m = 0; m < 4; ++m) for (int k = 0; k < 2; ++k) \
;     dst[m][k] = *reinterpret_cast<const bf16x8*>((char*)SA(b, h) + a_thr + (m * 2 + k) * 1024)
; #define MMA(ai, bj, At, Btf) do { __builtin_amdgcn_s_setprio(1); \
;     for (int m = 0; m < 4; ++m) for (int n = 0; n < 2; ++n) for (int k = 0; k < 2; ++k) \
;       acc[ai][bj][m][n] = __builtin_amdgcn_mfma_f32_16x16x32_bf16(Btf[n][k], At[m][k], acc[ai][bj][m][n], 0, 0, 0); \
;     __builtin_amdgcn_s_setprio(0); } while (0)
; #define WAIT_L(n) asm volatile("s_waitcnt lgkmcnt(" #n ")" ::: "memory")
; #define BAR __builtin_amdgcn_s_barrier()
; template <bool OVL, bool PANEL = false, class Epi>
; __device__ __forceinline__ void gemm_phase(const bf16_t* __restrict__ A, long lda, const bf16_t* __restrict__ Bt, long ldb, int nM, int nN, int K,
;                                            const Epi& epi, bf16_t* shm, int w0) {
;     ...
;       LDA(At, 1, 1); BAR; WAIT_L(0); MMA(1, 0, At, B0); MMA(1, 1, At, B1); BAR; }
	s_waitcnt lgkmcnt(0)
	v_mfma_f32_16x16x32_bf16 v[62:65], v[144:147], v[164:167], v[62:65]
	v_mfma_f32_16x16x32_bf16 v[74:77], v[152:155], v[168:171], v[62:65]
	v_mfma_f32_16x16x32_bf16 v[62:65], v[156:159], v[164:167], v[208:211]
	v_mfma_f32_16x16x32_bf16 v[54:57], v[144:147], v[172:175], v[54:57]
	v_mfma_f32_16x16x32_bf16 v[50:53], v[156:159], v[172:175], v[50:53]
	v_mfma_f32_16x16x32_bf16 v[46:49], v[144:147], v[180:183], v[46:49]
	v_mfma_f32_16x16x32_bf16 v[42:45], v[156:159], v[180:183], v[42:45]
	v_mfma_f32_16x16x32_bf16 v[38:41], v[144:147], v[188:191], v[38:41]
	v_mfma_f32_16x16x32_bf16 v[34:37], v[156:159], v[188:191], v[34:37]
	v_mfma_f32_16x16x32_bf16 v[62:65], v[160:163], v[168:171], v[62:65]
	v_mfma_f32_16x16x32_bf16 v[54:57], v[152:155], v[176:179], v[54:57]
	v_mfma_f32_16x16x32_bf16 v[50:53], v[160:163], v[176:179], v[50:53]
	v_mfma_f32_16x16x32_bf16 v[46:49], v[152:155], v[184:187], v[46:49]
	v_mfma_f32_16x16x32_bf16 v[42:45], v[160:163], v[184:187], v[42:45]
	v_mfma_f32_16x16x32_bf16 v[38:41], v[152:155], v[192:195], v[38:41]
	v_mfma_f32_16x16x32_bf16 v[34:37], v[160:163], v[192:195], v[34:37]


; #define LDA(dst, b, h) for (int m = 0; m < 4; ++m) for (int k = 0; k < 2; ++k) \
;     dst[m][k] = *reinterpret_cast<const bf16x8*>((char*)SA(b, h) + a_thr + (m * 2 + k) * 1024)
; #define MMA(ai, bj, At, Btf) do { __builtin_amdgcn_s_setprio(1); \
;     for (int m = 0; m < 4; ++m) for (int n = 0; n < 2; ++n) for (int k = 0; k < 2; ++k) \
;       acc[ai][bj][m][n] = __builtin_amdgcn_mfma_f32_16x16x32_bf16(Btf[n][k], At[m][k], acc[ai][bj][m][n], 0, 0, 0); \
;     __builtin_amdgcn_s_setprio(0); } while (0)
; #define WAIT_L(n) asm volatile("s_waitcnt lgkmcnt(" #n ")" ::: "memory")
; #define BAR __builtin_amdgcn_s_barrier()
; template <bool OVL, bool PANEL = false, class Epi>
; __device__ __forceinline__ void gemm_phase(const bf16_t* __restrict__ A, long lda, const bf16_t* __restrict__ Bt, long ldb, int nM, int nN, int K,
;                                            const Epi& epi, bf16_t* shm, int w0) {
;     ...
;       LDA(At, 1, 1); BAR; WAIT_L(0); MMA(1, 0, At, B0); MMA(1, 1, At, B1); BAR; }
	v_mfma_f32_16x16x32_bf16 v[30:33], v[148:151], v[164:167], v[30:33]
	v_mfma_f32_16x16x32_bf16 v[26:29], v[200:203], v[164:167], v[26:29]
	v_mfma_f32_16x16x32_bf16 v[22:25], v[148:151], v[172:175], v[22:25]
	v_mfma_f32_16x16x32_bf16 v[18:21], v[200:203], v[172:175], v[18:21]
	v_mfma_f32_16x16x32_bf16 v[14:17], v[148:151], v[180:183], v[14:17]
	v_mfma_f32_16x16x32_bf16 v[10:13], v[200:203], v[180:183], v[10:13]
	v_mfma_f32_16x16x32_bf16 v[6:9], v[148:151], v[188:191], v[6:9]
	v_mfma_f32_16x16x32_bf16 v[2:5], v[200:203], v[188:191], v[2:5]
	v_mfma_f32_16x16x32_bf16 v[30:33], v[196:199], v[168:171], v[30:33]
	v_mfma_f32_16x16x32_bf16 v[26:29], v[204:207], v[168:171], v[26:29]
	v_mfma_f32_16x16x32_bf16 v[22:25], v[196:199], v[176:179], v[22:25]
	v_mfma_f32_16x16x32_bf16 v[18:21], v[204:207], v[176:179], v[18:21]
	v_mfma_f32_16x16x32_bf16 v[14:17], v[196:199], v[184:187], v[14:17]
	v_mfma_f32_16x16x32_bf16 v[10:13], v[204:207], v[184:187], v[10:13]
	v_mfma_f32_16x16x32_bf16 v[6:9], v[196:199], v[192:195], v[6:9]
	v_mfma_f32_16x16x32_bf16 v[2:5], v[204:207], v[192:195], v[2:5]

; #define LDA(dst, b, h) for (int m = 0; m < 4; ++m) for (int k = 0; k < 2; ++k) \
;     dst[m][k] = *reinterpret_cast<const bf16x8*>((char*)SA(b, h) + a_thr + (m * 2 + k) * 1024)
; #define MMA(ai, bj, At, Btf) do { __builtin_amdgcn_s_setprio(1); \
;     for (int m = 0; m < 4; ++m) for (int n = 0; n < 2; ++n) for (int k = 0; k < 2; ++k) \
;       acc[ai][bj][m][n] = __builtin_amdgcn_mfma_f32_16x16x32_bf16(Btf[n][k], At[m][k], acc[ai][bj][m][n], 0, 0, 0); \
;     __builtin_amdgcn_s_setprio(0); } while (0)
; #define WAIT_L(n) asm volatile("s_waitcnt lgkmcnt(" #n ")" ::: "memory")
; #define BAR __builtin_amdgcn_s_barrier()
; template <bool OVL, bool PANEL = false, class Epi>
; __device__ __forceinline__ void gemm_phase(const bf16_t* __restrict__ A, long lda, const bf16_t* __restrict__ Bt, long ldb, int nM, int nN, int K,
;                                            const Epi& epi, bf16_t* shm, int w0) {
;     ...
;       LDA(At, 1, 1); BAR; WAIT_L(0); MMA(1, 0, At, B0); MMA(1, 1, At, B1); BAR; }
;     if (wr == 0) BAR;
	s_barrier
	s_and_saveexec_b64 s[0:1], s[6:7]
	s_cbranch_execz .LBB0_413
	s_barrier

; #define LDA(dst, b, h) for (int m = 0; m < 4; ++m) for (int k = 0; k < 2; ++k) \
;     dst[m][k] = *reinterpret_cast<const bf16x8*>((char*)SA(b, h) + a_thr + (m * 2 + k) * 1024)
; #define LDB(dst, b, h) for (int n = 0; n < 2; ++n) for (int k = 0; k < 2; ++k) \
;     dst[n][k] = *reinterpret_cast<const bf16x8*>((char*)SB(b, h) + b_thr + (n * 2 + k) * 1024)
; #define MMA(ai, bj, At, Btf) do { __builtin_amdgcn_s_setprio(1); \
;     for (int m = 0; m < 4; ++m) for (int n = 0; n < 2; ++n) for (int k = 0; k < 2; ++k) \
;       acc[ai][bj][m][n] = __builtin_amdgcn_mfma_f32_16x16x32_bf16(Btf[n][k], At[m][k], acc[ai][bj][m][n], 0, 0, 0); \
;     __builtin_amdgcn_s_setprio(0); } while (0)
; #define WAIT_V(n) asm volatile("s_waitcnt vmcnt(" #n ")" ::: "memory")
; #define WAIT_L(n) asm volatile("s_waitcnt lgkmcnt(" #n ")" ::: "memory")
; #define BAR __builtin_amdgcn_s_barrier()
; #define SCHED __builtin_amdgcn_sched_barrier(0)
; template <bool OVL, bool PANEL = false, class Epi>
; __device__ __forceinline__ void gemm_phase(const bf16_t* __restrict__ A, long lda, const bf16_t* __restrict__ Bt, long ldb, int nM, int nN, int K,
;                                            const Epi& epi, bf16_t* shm, int w0) {
;     ...
;       LDB(B0, 0, 0); SCHED; LDA(At, 0, 0); STAGE(SA(1, 1), A, lda, aoff, brow + HALF, t + 1);
;       WAIT_L(8); BAR; WAIT_L(0); MMA(0, 0, At, B0); BAR; SCHED;
;       LDB(B1, 0, 1); STAGE(SB(0, 0), Bt, ldb, boff, bcol, t + 2);
;       BAR; WAIT_L(0); MMA(0, 1, At, B1); BAR;
;       LDA(At, 0, 1); STAGE(SA(0, 0), A, lda, aoff, brow, t + 2);
;       BAR; WAIT_L(0); MMA(1, 0, At, B0); BAR; SCHED;
;       STAGE(SB(0, 1), Bt, ldb, boff, bcol + HALF, t + 2);
;       WAIT_V(6); BAR; MMA(1, 1, At, B1); BAR;
.LBB0_472:
	ds_read_b128 v[138:141], v206
	ds_read_b128 v[142:145], v206 offset:1024
	ds_read_b128 v[146:149], v206 offset:2048
	ds_read_b128 v[150:153], v206 offset:3072
	s_add_u32 vcc_lo, s8, s80
	s_addc_u32 vcc_hi, s9, s81
	ds_read_b128 v[154:157], v241
	ds_read_b128 v[158:161], v241 offset:1024
	ds_read_b128 v[162:165], v241 offset:2048
	ds_read_b128 v[166:169], v241 offset:3072
	ds_read_b128 v[170:173], v241 offset:4096
	ds_read_b128 v[174:177], v241 offset:5120
	ds_read_b128 v[178:181], v241 offset:6144
	ds_read_b128 v[182:185], v241 offset:7168
	s_mov_b32 m0, s16
	s_add_u32 s98, vcc_lo, s12
	s_addc_u32 s99, vcc_hi, s13
	global_load_lds_dwordx4 v221, s[98:99]
	s_mov_b32 m0, s32
	s_add_u32 s98, vcc_lo, s36
	s_addc_u32 s99, vcc_hi, s37
	global_load_lds_dwordx4 v221, s[98:99]
	s_waitcnt lgkmcnt(0)
	s_waitcnt vmcnt(10)
	s_barrier
	v_mfma_f32_16x16x32_bf16 v[126:129], v[138:141], v[154:157], v[126:129]
	v_mfma_f32_16x16x32_bf16 v[122:125], v[146:149], v[154:157], v[122:125]
	v_mfma_f32_16x16x32_bf16 v[118:121], v[138:141], v[162:165], v[118:121]
	v_mfma_f32_16x16x32_bf16 v[114:117], v[146:149], v[162:165], v[114:117]
	v_mfma_f32_16x16x32_bf16 v[110:113], v[138:141], v[170:173], v[110:113]
	v_mfma_f32_16x16x32_bf16 v[106:109], v[146:149], v[170:173], v[106:109]
	v_mfma_f32_16x16x32_bf16 v[102:105], v[138:141], v[178:181], v[102:105]
	v_mfma_f32_16x16x32_bf16 v[98:101], v[146:149], v[178:181], v[98:101]
	v_mfma_f32_16x16x32_bf16 v[126:129], v[142:145], v[158:161], v[126:129]
	v_mfma_f32_16x16x32_bf16 v[122:125], v[150:153], v[158:161], v[122:125]
	v_mfma_f32_16x16x32_bf16 v[118:121], v[142:145], v[166:169], v[118:121]
	v_mfma_f32_16x16x32_bf16 v[114:117], v[150:153], v[166:169], v[114:117]
	v_mfma_f32_16x16x32_bf16 v[110:113], v[142:145], v[174:177], v[110:113]
	v_mfma_f32_16x16x32_bf16 v[106:109], v[150:153], v[174:177], v[106:109]
	v_mfma_f32_16x16x32_bf16 v[102:105], v[142:145], v[182:185], v[102:105]
	v_mfma_f32_16x16x32_bf16 v[98:101], v[150:153], v[182:185], v[98:101]
	s_barrier
	s_add_u32 s0, s6, s80
	ds_read_b128 v[186:189], v207
	ds_read_b128 v[190:193], v207 offset:1024
	ds_read_b128 v[194:197], v207 offset:2048
	ds_read_b128 v[198:201], v207 offset:3072
	s_addc_u32 s1, s7, s81
	s_mov_b32 m0, s44
	s_add_u32 s98, s0, s34
	s_addc_u32 s99, s1, s35
	global_load_lds_dwordx4 v221, s[98:99]
	s_mov_b32 m0, s45
	s_add_u32 s98, s0, s64
	s_addc_u32 s99, s1, s65
	global_load_lds_dwordx4 v221, s[98:99]
	s_waitcnt lgkmcnt(0)
	s_waitcnt vmcnt(10)
	s_barrier
	v_mfma_f32_16x16x32_bf16 v[94:97], v[186:189], v[154:157], v[94:97]
	v_mfma_f32_16x16x32_bf16 v[90:93], v[194:197], v[154:157], v[90:93]
	v_mfma_f32_16x16x32_bf16 v[86:89], v[186:189], v[162:165], v[86:89]
	v_mfma_f32_16x16x32_bf16 v[82:85], v[194:197], v[162:165], v[82:85]
	v_mfma_f32_16x16x32_bf16 v[78:81], v[186:189], v[170:173], v[78:81]
	v_mfma_f32_16x16x32_bf16 v[74:77], v[194:197], v[170:173], v[74:77]
	v_mfma_f32_16x16x32_bf16 v[70:73], v[186:189], v[178:181], v[70:73]
	v_mfma_f32_16x16x32_bf16 v[66:69], v[194:197], v[178:181], v[66:69]
	v_mfma_f32_16x16x32_bf16 v[94:97], v[190:193], v[158:161], v[94:97]
	v_mfma_f32_16x16x32_bf16 v[90:93], v[198:201], v[158:161], v[90:93]
	v_mfma_f32_16x16x32_bf16 v[86:89], v[190:193], v[166:169], v[86:89]
	v_mfma_f32_16x16x32_bf16 v[82:85], v[198:201], v[166:169], v[82:85]
	v_mfma_f32_16x16x32_bf16 v[78:81], v[190:193], v[174:177], v[78:81]
	v_mfma_f32_16x16x32_bf16 v[74:77], v[198:201], v[174:177], v[74:77]
	v_mfma_f32_16x16x32_bf16 v[70:73], v[190:193], v[182:185], v[70:73]
	v_mfma_f32_16x16x32_bf16 v[66:69], v[198:201], v[182:185], v[66:69]
	s_barrier
	ds_read_b128 v[154:157], v241 offset:16384
	ds_read_b128 v[158:161], v241 offset:17408
	ds_read_b128 v[162:165], v241 offset:18432
	ds_read_b128 v[166:169], v241 offset:19456
	ds_read_b128 v[170:173], v241 offset:20480
	ds_read_b128 v[174:177], v241 offset:21504
	ds_read_b128 v[178:181], v241 offset:22528
	ds_read_b128 v[182:185], v241 offset:23552
	s_mov_b32 m0, s46
	s_add_u32 s98, vcc_lo, s34
	s_addc_u32 s99, vcc_hi, s35
	global_load_lds_dwordx4 v221, s[98:99]
	s_mov_b32 m0, s47
	s_add_u32 s98, vcc_lo, s64
	s_addc_u32 s99, vcc_hi, s65
	global_load_lds_dwordx4 v221, s[98:99]
	s_waitcnt lgkmcnt(0)
	s_barrier
	v_mfma_f32_16x16x32_bf16 v[62:65], v[138:141], v[154:157], v[62:65]
	v_mfma_f32_16x16x32_bf16 v[58:61], v[146:149], v[154:157], v[58:61]
	v_mfma_f32_16x16x32_bf16 v[54:57], v[138:141], v[162:165], v[54:57]
	v_mfma_f32_16x16x32_bf16 v[50:53], v[146:149], v[162:165], v[50:53]
	v_mfma_f32_16x16x32_bf16 v[46:49], v[138:141], v[170:173], v[46:49]
	v_mfma_f32_16x16x32_bf16 v[42:45], v[146:149], v[170:173], v[42:45]
	v_mfma_f32_16x16x32_bf16 v[38:41], v[138:141], v[178:181], v[38:41]
	v_mfma_f32_16x16x32_bf16 v[34:37], v[146:149], v[178:181], v[34:37]
	v_mfma_f32_16x16x32_bf16 v[62:65], v[142:145], v[158:161], v[62:65]
	v_mfma_f32_16x16x32_bf16 v[58:61], v[150:153], v[158:161], v[58:61]
	v_mfma_f32_16x16x32_bf16 v[54:57], v[142:145], v[166:169], v[54:57]
	v_mfma_f32_16x16x32_bf16 v[50:53], v[150:153], v[166:169], v[50:53]
	v_mfma_f32_16x16x32_bf16 v[46:49], v[142:145], v[174:177], v[46:49]
	v_mfma_f32_16x16x32_bf16 v[42:45], v[150:153], v[174:177], v[42:45]
	v_mfma_f32_16x16x32_bf16 v[38:41], v[142:145], v[182:185], v[38:41]
	v_mfma_f32_16x16x32_bf16 v[34:37], v[150:153], v[182:185], v[34:37]
	s_barrier
	s_mov_b32 m0, s48
	s_add_u32 s98, s0, s68
	s_addc_u32 s99, s1, s69
	global_load_lds_dwordx4 v221, s[98:99]
	s_mov_b32 m0, s49
	s_add_u32 s98, s0, s70
	s_addc_u32 s99, s1, s71
	global_load_lds_dwordx4 v221, s[98:99]
	s_waitcnt vmcnt(10)
	s_barrier
; #define LDA(dst, b, h) for (int m = 0; m < 4; ++m) for (int k = 0; k < 2; ++k) \
;     dst[m][k] = *reinterpret_cast<const bf16x8*>((char*)SA(b, h) + a_thr + (m * 2 + k) * 1024)
; #define LDB(dst, b, h) for (int n = 0; n < 2; ++n) for (int k = 0; k < 2; ++k) \
;     dst[n][k] = *reinterpret_cast<const bf16x8*>((char*)SB(b, h) + b_thr + (n * 2 + k) * 1024)
; #define MMA(ai, bj, At, Btf) do { __builtin_amdgcn_s_setprio(1); \
;     for (int m = 0; m < 4; ++m) for (int n = 0; n < 2; ++n) for (int k = 0; k < 2; ++k) \
;       acc[ai][bj][m][n] = __builtin_amdgcn_mfma_f32_16x16x32_bf16(Btf[n][k], At[m][k], acc[ai][bj][m][n], 0, 0, 0); \
;     __builtin_amdgcn_s_setprio(0); } while (0)
; #define WAIT_V(n) asm volatile("s_waitcnt vmcnt(" #n ")" ::: "memory")
; #define WAIT_L(n) asm volatile("s_waitcnt lgkmcnt(" #n ")" ::: "memory")
; #define BAR __builtin_amdgcn_s_barrier()
; #define SCHED __builtin_amdgcn_sched_barrier(0)
; template <bool OVL, bool PANEL = false, class Epi>
; __device__ __forceinline__ void gemm_phase(const bf16_t* __restrict__ A, long lda, const bf16_t* __restrict__ Bt, long ldb, int nM, int nN, int K,
;                                            const Epi& epi, bf16_t* shm, int w0) {
;     ...
;       WAIT_V(6); BAR; MMA(1, 1, At, B1); BAR;
;       LDB(B0, 1, 0); SCHED; LDA(At, 1, 0); STAGE(SA(0, 1), A, lda, aoff, brow + HALF, t + 2);
;       WAIT_L(8); BAR; WAIT_L(0); MMA(0, 0, At, B0); BAR; SCHED;
;       LDB(B1, 1, 1); STAGE(SB(1, 0), Bt, ldb, boff, bcol, t + 3);
;       BAR; WAIT_L(0); MMA(0, 1, At, B1); BAR;
	v_mfma_f32_16x16x32_bf16 v[30:33], v[186:189], v[154:157], v[30:33]
	v_mfma_f32_16x16x32_bf16 v[26:29], v[194:197], v[154:157], v[26:29]
	v_mfma_f32_16x16x32_bf16 v[22:25], v[186:189], v[162:165], v[22:25]
	v_mfma_f32_16x16x32_bf16 v[18:21], v[194:197], v[162:165], v[18:21]
	v_mfma_f32_16x16x32_bf16 v[14:17], v[186:189], v[170:173], v[14:17]
	v_mfma_f32_16x16x32_bf16 v[10:13], v[194:197], v[170:173], v[10:13]
	v_mfma_f32_16x16x32_bf16 v[6:9], v[186:189], v[178:181], v[6:9]
	v_mfma_f32_16x16x32_bf16 v[2:5], v[194:197], v[178:181], v[2:5]
	v_mfma_f32_16x16x32_bf16 v[30:33], v[190:193], v[158:161], v[30:33]
	v_mfma_f32_16x16x32_bf16 v[26:29], v[198:201], v[158:161], v[26:29]
	v_mfma_f32_16x16x32_bf16 v[22:25], v[190:193], v[166:169], v[22:25]
	v_mfma_f32_16x16x32_bf16 v[18:21], v[198:201], v[166:169], v[18:21]
	v_mfma_f32_16x16x32_bf16 v[14:17], v[190:193], v[174:177], v[14:17]
	v_mfma_f32_16x16x32_bf16 v[10:13], v[198:201], v[174:177], v[10:13]
	v_mfma_f32_16x16x32_bf16 v[6:9], v[190:193], v[182:185], v[6:9]
	v_mfma_f32_16x16x32_bf16 v[2:5], v[198:201], v[182:185], v[2:5]
	s_barrier
	ds_read_b128 v[138:141], v208
	ds_read_b128 v[142:145], v208 offset:1024
	ds_read_b128 v[146:149], v208 offset:2048
	ds_read_b128 v[150:153], v208 offset:3072
	ds_read_b128 v[154:157], v241 offset:32768
	ds_read_b128 v[158:161], v241 offset:33792
	ds_read_b128 v[162:165], v241 offset:34816
	ds_read_b128 v[166:169], v241 offset:35840
	ds_read_b128 v[170:173], v241 offset:36864
	ds_read_b128 v[174:177], v241 offset:37888
	ds_read_b128 v[178:181], v241 offset:38912
	ds_read_b128 v[182:185], v241 offset:39936
	s_mov_b32 m0, s50
	s_add_u32 s98, vcc_lo, s68
	s_addc_u32 s99, vcc_hi, s69
	global_load_lds_dwordx4 v221, s[98:99]
	s_mov_b32 m0, s51
	s_add_u32 s98, vcc_lo, s70
	s_addc_u32 s99, vcc_hi, s71
	global_load_lds_dwordx4 v221, s[98:99]
	s_waitcnt lgkmcnt(0)
	s_waitcnt vmcnt(10)
	s_barrier
	v_mfma_f32_16x16x32_bf16 v[126:129], v[138:141], v[154:157], v[126:129]
	v_mfma_f32_16x16x32_bf16 v[122:125], v[146:149], v[154:157], v[122:125]
	v_mfma_f32_16x16x32_bf16 v[118:121], v[138:141], v[162:165], v[118:121]
	v_mfma_f32_16x16x32_bf16 v[114:117], v[146:149], v[162:165], v[114:117]
	v_mfma_f32_16x16x32_bf16 v[110:113], v[138:141], v[170:173], v[110:113]
	v_mfma_f32_16x16x32_bf16 v[106:109], v[146:149], v[170:173], v[106:109]
	v_mfma_f32_16x16x32_bf16 v[102:105], v[138:141], v[178:181], v[102:105]
	v_mfma_f32_16x16x32_bf16 v[98:101], v[146:149], v[178:181], v[98:101]
	v_mfma_f32_16x16x32_bf16 v[126:129], v[142:145], v[158:161], v[126:129]
	v_mfma_f32_16x16x32_bf16 v[122:125], v[150:153], v[158:161], v[122:125]
	v_mfma_f32_16x16x32_bf16 v[118:121], v[142:145], v[166:169], v[118:121]
	v_mfma_f32_16x16x32_bf16 v[114:117], v[150:153], v[166:169], v[114:117]
	v_mfma_f32_16x16x32_bf16 v[110:113], v[142:145], v[174:177], v[110:113]
	v_mfma_f32_16x16x32_bf16 v[106:109], v[150:153], v[174:177], v[106:109]
	v_mfma_f32_16x16x32_bf16 v[102:105], v[142:145], v[182:185], v[102:105]
	v_mfma_f32_16x16x32_bf16 v[98:101], v[150:153], v[182:185], v[98:101]
	s_barrier
	ds_read_b128 v[186:189], v209
	ds_read_b128 v[190:193], v209 offset:1024
	ds_read_b128 v[194:197], v209 offset:2048
	ds_read_b128 v[198:201], v209 offset:3072
	s_mov_b32 m0, s52
	s_add_u32 s98, s0, s94
	s_addc_u32 s99, s1, s95
	global_load_lds_dwordx4 v221, s[98:99]
	s_mov_b32 m0, s53
	s_add_u32 s98, s0, s72
	s_addc_u32 s99, s1, s73
	global_load_lds_dwordx4 v221, s[98:99]
	s_waitcnt lgkmcnt(0)
	s_waitcnt vmcnt(10)
	s_barrier
	v_mfma_f32_16x16x32_bf16 v[94:97], v[186:189], v[154:157], v[94:97]
	v_mfma_f32_16x16x32_bf16 v[90:93], v[194:197], v[154:157], v[90:93]
	v_mfma_f32_16x16x32_bf16 v[86:89], v[186:189], v[162:165], v[86:89]
	v_mfma_f32_16x16x32_bf16 v[82:85], v[194:197], v[162:165], v[82:85]
	v_mfma_f32_16x16x32_bf16 v[78:81], v[186:189], v[170:173], v[78:81]
	v_mfma_f32_16x16x32_bf16 v[74:77], v[194:197], v[170:173], v[74:77]
	v_mfma_f32_16x16x32_bf16 v[70:73], v[186:189], v[178:181], v[70:73]
	v_mfma_f32_16x16x32_bf16 v[66:69], v[194:197], v[178:181], v[66:69]
	v_mfma_f32_16x16x32_bf16 v[94:97], v[190:193], v[158:161], v[94:97]
	v_mfma_f32_16x16x32_bf16 v[90:93], v[198:201], v[158:161], v[90:93]
	v_mfma_f32_16x16x32_bf16 v[86:89], v[190:193], v[166:169], v[86:89]
	v_mfma_f32_16x16x32_bf16 v[82:85], v[198:201], v[166:169], v[82:85]
	v_mfma_f32_16x16x32_bf16 v[78:81], v[190:193], v[174:177], v[78:81]
	v_mfma_f32_16x16x32_bf16 v[74:77], v[198:201], v[174:177], v[74:77]
	v_mfma_f32_16x16x32_bf16 v[70:73], v[190:193], v[182:185], v[70:73]
	v_mfma_f32_16x16x32_bf16 v[66:69], v[198:201], v[182:185], v[66:69]
	s_barrier
; #define LDA(dst, b, h) for (int m = 0; m < 4; ++m) for (int k = 0; k < 2; ++k) \
;     dst[m][k] = *reinterpret_cast<const bf16x8*>((char*)SA(b, h) + a_thr + (m * 2 + k) * 1024)
; #define LDB(dst, b, h) for (int n = 0; n < 2; ++n) for (int k = 0; k < 2; ++k) \
;     dst[n][k] = *reinterpret_cast<const bf16x8*>((char*)SB(b, h) + b_thr + (n * 2 + k) * 1024)
; #define MMA(ai, bj, At, Btf) do { __builtin_amdgcn_s_setprio(1); \
;     for (int m = 0; m < 4; ++m) for (int n = 0; n < 2; ++n) for (int k = 0; k < 2; ++k) \
;       acc[ai][bj][m][n] = __builtin_amdgcn_mfma_f32_16x16x32_bf16(Btf[n][k], At[m][k], acc[ai][bj][m][n], 0, 0, 0); \
;     __builtin_amdgcn_s_setprio(0); } while (0)
; #define WAIT_V(n) asm volatile("s_waitcnt vmcnt(" #n ")" ::: "memory")
; #define WAIT_L(n) asm volatile("s_waitcnt lgkmcnt(" #n ")" ::: "memory")
; #define BAR __builtin_amdgcn_s_barrier()
; #define SCHED __builtin_amdgcn_sched_barrier(0)
; template <bool OVL, bool PANEL = false, class Epi>
; __device__ __forceinline__ void gemm_phase(const bf16_t* __restrict__ A, long lda, const bf16_t* __restrict__ Bt, long ldb, int nM, int nN, int K,
;                                            const Epi& epi, bf16_t* shm, int w0) {
;     ...
;       LDA(At, 1, 1); STAGE(SA(1, 0), A, lda, aoff, brow, t + 3);
;       BAR; WAIT_L(0); MMA(1, 0, At, B0); BAR; SCHED;
;       STAGE(SB(1, 1), Bt, ldb, boff, bcol + HALF, t + 3);
;       WAIT_V(6); BAR; MMA(1, 1, At, B1); BAR;
;     }
;     { LDB(B0, 0, 0); LDA(At, 0, 0); STAGE(SA(1, 1), A, lda, aoff, brow + HALF, nt - 1);
	ds_read_b128 v[154:157], v241 offset:49152
	ds_read_b128 v[158:161], v241 offset:50176
	ds_read_b128 v[162:165], v241 offset:51200
	ds_read_b128 v[166:169], v241 offset:52224
	ds_read_b128 v[170:173], v241 offset:53248
	ds_read_b128 v[174:177], v241 offset:54272
	ds_read_b128 v[178:181], v241 offset:55296
	ds_read_b128 v[182:185], v241 offset:56320
	s_mov_b32 m0, s54
	s_add_u32 s98, vcc_lo, s94
	s_addc_u32 s99, vcc_hi, s95
	global_load_lds_dwordx4 v221, s[98:99]
	s_mov_b32 m0, s55
	s_add_u32 s98, vcc_lo, s72
	s_addc_u32 s99, vcc_hi, s73
	global_load_lds_dwordx4 v221, s[98:99]
	s_waitcnt lgkmcnt(0)
	s_barrier
	v_mfma_f32_16x16x32_bf16 v[62:65], v[138:141], v[154:157], v[62:65]
	v_mfma_f32_16x16x32_bf16 v[58:61], v[146:149], v[154:157], v[58:61]
	v_mfma_f32_16x16x32_bf16 v[54:57], v[138:141], v[162:165], v[54:57]
	v_mfma_f32_16x16x32_bf16 v[50:53], v[146:149], v[162:165], v[50:53]
	v_mfma_f32_16x16x32_bf16 v[46:49], v[138:141], v[170:173], v[46:49]
	v_mfma_f32_16x16x32_bf16 v[42:45], v[146:149], v[170:173], v[42:45]
	v_mfma_f32_16x16x32_bf16 v[38:41], v[138:141], v[178:181], v[38:41]
	v_mfma_f32_16x16x32_bf16 v[34:37], v[146:149], v[178:181], v[34:37]
	v_mfma_f32_16x16x32_bf16 v[62:65], v[142:145], v[158:161], v[62:65]
	v_mfma_f32_16x16x32_bf16 v[58:61], v[150:153], v[158:161], v[58:61]
	v_mfma_f32_16x16x32_bf16 v[54:57], v[142:145], v[166:169], v[54:57]
	v_mfma_f32_16x16x32_bf16 v[50:53], v[150:153], v[166:169], v[50:53]
	v_mfma_f32_16x16x32_bf16 v[46:49], v[142:145], v[174:177], v[46:49]
	v_mfma_f32_16x16x32_bf16 v[42:45], v[150:153], v[174:177], v[42:45]
	v_mfma_f32_16x16x32_bf16 v[38:41], v[142:145], v[182:185], v[38:41]
	v_mfma_f32_16x16x32_bf16 v[34:37], v[150:153], v[182:185], v[34:37]
	s_barrier
	s_mov_b32 m0, s56
	s_add_u32 s98, s0, s14
	s_addc_u32 s99, s1, s15
	global_load_lds_dwordx4 v221, s[98:99]
	s_mov_b32 m0, s57
	s_add_u32 s98, s0, s18
	s_addc_u32 s99, s1, s19
	global_load_lds_dwordx4 v221, s[98:99]
	s_add_i32 s2, s2, 2
	s_add_u32 s80, s80, 0x100
	s_addc_u32 s81, s81, 0
	s_cmp_gt_u32 s2, 11
	s_waitcnt vmcnt(10)
	s_barrier
	v_mfma_f32_16x16x32_bf16 v[30:33], v[186:189], v[154:157], v[30:33]
	v_mfma_f32_16x16x32_bf16 v[26:29], v[194:197], v[154:157], v[26:29]
	v_mfma_f32_16x16x32_bf16 v[22:25], v[186:189], v[162:165], v[22:25]
	v_mfma_f32_16x16x32_bf16 v[18:21], v[194:197], v[162:165], v[18:21]
	v_mfma_f32_16x16x32_bf16 v[14:17], v[186:189], v[170:173], v[14:17]
	v_mfma_f32_16x16x32_bf16 v[10:13], v[194:197], v[170:173], v[10:13]
	v_mfma_f32_16x16x32_bf16 v[6:9], v[186:189], v[178:181], v[6:9]
	v_mfma_f32_16x16x32_bf16 v[2:5], v[194:197], v[178:181], v[2:5]
	v_mfma_f32_16x16x32_bf16 v[30:33], v[190:193], v[158:161], v[30:33]
	v_mfma_f32_16x16x32_bf16 v[26:29], v[198:201], v[158:161], v[26:29]
	v_mfma_f32_16x16x32_bf16 v[22:25], v[190:193], v[166:169], v[22:25]
	v_mfma_f32_16x16x32_bf16 v[18:21], v[198:201], v[166:169], v[18:21]
	v_mfma_f32_16x16x32_bf16 v[14:17], v[190:193], v[174:177], v[14:17]
	v_mfma_f32_16x16x32_bf16 v[10:13], v[198:201], v[174:177], v[10:13]
	v_mfma_f32_16x16x32_bf16 v[6:9], v[190:193], v[182:185], v[6:9]
	v_mfma_f32_16x16x32_bf16 v[2:5], v[198:201], v[182:185], v[2:5]
	s_barrier
	s_cbranch_scc0 .LBB0_472
	s_waitcnt vmcnt(6)
	s_or_b32 s0, s82, 0x80
	s_ashr_i32 s1, s0, 31
	v_readlane_b32 s44, v252, 20
	s_lshl_b64 s[0:1], s[0:1], 11
	v_readlane_b32 s50, v252, 26
	v_add_u32_e32 v206, 16, v240
	v_readlane_b32 s51, v252, 27
	s_add_u32 s0, s50, s0
	v_add_u32_e32 v0, 0x10000, v206
	s_addc_u32 s1, s51, s1
	ds_read_b128 v[130:133], v0
	ds_read_b128 v[138:141], v0 offset:1024
	ds_read_b128 v[142:145], v0 offset:2048
	ds_read_b128 v[146:149], v0 offset:3072
	ds_read_b128 v[150:153], v241
	ds_read_b128 v[154:157], v241 offset:1024
	ds_read_b128 v[158:161], v241 offset:2048
	ds_read_b128 v[162:165], v241 offset:3072
	ds_read_b128 v[166:169], v241 offset:4096
	ds_read_b128 v[170:173], v241 offset:5120
	ds_read_b128 v[174:177], v241 offset:6144
	ds_read_b128 v[178:181], v241 offset:7168
	v_mov_b32_e32 v0, v221
	v_readlane_b32 s45, v252, 21
	v_lshl_add_u64 v[134:135], s[0:1], 0, v[0:1]
	s_mov_b64 s[0:1], 0x780
	v_lshl_add_u64 v[182:183], v[134:135], 0, s[0:1]
	v_readfirstlane_b32 s0, v136
	s_mov_b32 m0, s0
	s_mov_b64 s[0:1], 0x20780
	v_lshl_add_u64 v[134:135], v[134:135], 0, s[0:1]
	v_readfirstlane_b32 s0, v137
	global_load_lds_dwordx4 v[182:183], off
	s_mov_b32 m0, s0
	v_readlane_b32 s46, v252, 22
	global_load_lds_dwordx4 v[134:135], off
	s_barrier
	s_waitcnt lgkmcnt(0)
	v_readlane_b32 s47, v252, 23
	v_readlane_b32 s48, v252, 24
	v_readlane_b32 s49, v252, 25
	v_readlane_b32 s52, v252, 28
	v_readlane_b32 s53, v252, 29
	v_readlane_b32 s54, v252, 30
	v_readlane_b32 s55, v252, 31
	v_readlane_b32 s56, v252, 32
	v_readlane_b32 s57, v252, 33
	v_readlane_b32 s58, v252, 34
	v_readlane_b32 s59, v252, 35

; #define MMA(ai, bj, At, Btf) do { __builtin_amdgcn_s_setprio(1); \
;     for (int m = 0; m < 4; ++m) for (int n = 0; n < 2; ++n) for (int k = 0; k < 2; ++k) \
;       acc[ai][bj][m][n] = __builtin_amdgcn_mfma_f32_16x16x32_bf16(Btf[n][k], At[m][k], acc[ai][bj][m][n], 0, 0, 0); \
;     __builtin_amdgcn_s_setprio(0); } while (0)
; #define WAIT_L(n) asm volatile("s_waitcnt lgkmcnt(" #n ")" ::: "memory")
; #define BAR __builtin_amdgcn_s_barrier()
; template <bool OVL, bool PANEL = false, class Epi>
; __device__ __forceinline__ void gemm_phase(const bf16_t* __restrict__ A, long lda, const bf16_t* __restrict__ Bt, long ldb, int nM, int nN, int K,
;                                            const Epi& epi, bf16_t* shm, int w0) {
;     ...
;       BAR; WAIT_L(0); MMA(0, 0, At, B0); BAR;
	s_waitcnt lgkmcnt(0)
	v_mfma_f32_16x16x32_bf16 v[126:129], v[130:133], v[150:153], v[126:129]
	v_mfma_f32_16x16x32_bf16 v[122:125], v[142:145], v[150:153], v[122:125]
	v_mfma_f32_16x16x32_bf16 v[118:121], v[130:133], v[158:161], v[118:121]
	v_mfma_f32_16x16x32_bf16 v[114:117], v[142:145], v[158:161], v[114:117]
	v_mfma_f32_16x16x32_bf16 v[106:109], v[142:145], v[166:169], v[106:109]
	v_mfma_f32_16x16x32_bf16 v[102:105], v[130:133], v[174:177], v[102:105]
	v_mfma_f32_16x16x32_bf16 v[98:101], v[142:145], v[174:177], v[98:101]
	v_mfma_f32_16x16x32_bf16 v[126:129], v[138:141], v[154:157], v[126:129]
	v_mfma_f32_16x16x32_bf16 v[122:125], v[146:149], v[154:157], v[122:125]
	v_mfma_f32_16x16x32_bf16 v[118:121], v[138:141], v[162:165], v[118:121]
	v_mfma_f32_16x16x32_bf16 v[114:117], v[146:149], v[162:165], v[114:117]
	v_mfma_f32_16x16x32_bf16 v[110:113], v[130:133], v[166:169], v[110:113]
	v_mfma_f32_16x16x32_bf16 v[106:109], v[146:149], v[170:173], v[106:109]
	v_mfma_f32_16x16x32_bf16 v[102:105], v[138:141], v[178:181], v[102:105]
	v_mfma_f32_16x16x32_bf16 v[98:101], v[146:149], v[178:181], v[98:101]
	v_mfma_f32_16x16x32_bf16 v[134:137], v[138:141], v[170:173], v[110:113]

; #define LDB(dst, b, h) for (int n = 0; n < 2; ++n) for (int k = 0; k < 2; ++k) \
;     dst[n][k] = *reinterpret_cast<const bf16x8*>((char*)SB(b, h) + b_thr + (n * 2 + k) * 1024)
; #define MMA(ai, bj, At, Btf) do { __builtin_amdgcn_s_setprio(1); \
;     for (int m = 0; m < 4; ++m) for (int n = 0; n < 2; ++n) for (int k = 0; k < 2; ++k) \
;       acc[ai][bj][m][n] = __builtin_amdgcn_mfma_f32_16x16x32_bf16(Btf[n][k], At[m][k], acc[ai][bj][m][n], 0, 0, 0); \
;     __builtin_amdgcn_s_setprio(0); } while (0)
; #define WAIT_L(n) asm volatile("s_waitcnt lgkmcnt(" #n ")" ::: "memory")
; #define BAR __builtin_amdgcn_s_barrier()
; template <bool OVL, bool PANEL = false, class Epi>
; __device__ __forceinline__ void gemm_phase(const bf16_t* __restrict__ A, long lda, const bf16_t* __restrict__ Bt, long ldb, int nM, int nN, int K,
;                                            const Epi& epi, bf16_t* shm, int w0) {
;     ...
;       LDB(B1, 0, 1); BAR; WAIT_L(0); MMA(0, 1, At, B1); BAR;
	v_add_u32_e32 v0, 0x14000, v206
	s_barrier
	s_nop 0
	ds_read_b128 v[110:113], v0
	ds_read_b128 v[182:185], v0 offset:1024
	ds_read_b128 v[186:189], v0 offset:2048
	ds_read_b128 v[190:193], v0 offset:3072
	s_barrier
	s_waitcnt lgkmcnt(0)

; #define LDB(dst, b, h) for (int n = 0; n < 2; ++n) for (int k = 0; k < 2; ++k) \
;     dst[n][k] = *reinterpret_cast<const bf16x8*>((char*)SB(b, h) + b_thr + (n * 2 + k) * 1024)
; #define MMA(ai, bj, At, Btf) do { __builtin_amdgcn_s_setprio(1); \
;     for (int m = 0; m < 4; ++m) for (int n = 0; n < 2; ++n) for (int k = 0; k < 2; ++k) \
;       acc[ai][bj][m][n] = __builtin_amdgcn_mfma_f32_16x16x32_bf16(Btf[n][k], At[m][k], acc[ai][bj][m][n], 0, 0, 0); \
;     __builtin_amdgcn_s_setprio(0); } while (0)
; #define WAIT_L(n) asm volatile("s_waitcnt lgkmcnt(" #n ")" ::: "memory")
; #define BAR __builtin_amdgcn_s_barrier()
; template <bool OVL, bool PANEL = false, class Epi>
; __device__ __forceinline__ void gemm_phase(const bf16_t* __restrict__ A, long lda, const bf16_t* __restrict__ Bt, long ldb, int nM, int nN, int K,
;                                            const Epi& epi, bf16_t* shm, int w0) {
;     ...
;       LDB(B1, 0, 1); BAR; WAIT_L(0); MMA(0, 1, At, B1); BAR;
	s_waitcnt lgkmcnt(0)
	v_mfma_f32_16x16x32_bf16 v[90:93], v[186:189], v[150:153], v[90:93]
	v_mfma_f32_16x16x32_bf16 v[74:77], v[186:189], v[166:169], v[74:77]
	v_mfma_f32_16x16x32_bf16 v[70:73], v[110:113], v[174:177], v[70:73]
	v_mfma_f32_16x16x32_bf16 v[66:69], v[186:189], v[174:177], v[66:69]
	v_mfma_f32_16x16x32_bf16 v[94:97], v[110:113], v[150:153], v[94:97]
	v_mfma_f32_16x16x32_bf16 v[90:93], v[190:193], v[154:157], v[90:93]
	v_mfma_f32_16x16x32_bf16 v[86:89], v[110:113], v[158:161], v[86:89]
	v_mfma_f32_16x16x32_bf16 v[82:85], v[186:189], v[158:161], v[82:85]
	v_mfma_f32_16x16x32_bf16 v[78:81], v[110:113], v[166:169], v[78:81]
	v_mfma_f32_16x16x32_bf16 v[74:77], v[190:193], v[170:173], v[74:77]
	v_mfma_f32_16x16x32_bf16 v[70:73], v[182:185], v[178:181], v[70:73]
	v_mfma_f32_16x16x32_bf16 v[66:69], v[190:193], v[178:181], v[66:69]
	v_mfma_f32_16x16x32_bf16 v[194:197], v[182:185], v[154:157], v[94:97]
	v_mfma_f32_16x16x32_bf16 v[150:153], v[182:185], v[162:165], v[86:89]
	v_mfma_f32_16x16x32_bf16 v[154:157], v[190:193], v[162:165], v[82:85]
	v_mfma_f32_16x16x32_bf16 v[158:161], v[182:185], v[170:173], v[78:81]

; #define LDA(dst, b, h) for (int m = 0; m < 4; ++m) for (int k = 0; k < 2; ++k) \
;     dst[m][k] = *reinterpret_cast<const bf16x8*>((char*)SA(b, h) + a_thr + (m * 2 + k) * 1024)
; #define MMA(ai, bj, At, Btf) do { __builtin_amdgcn_s_setprio(1); \
;     for (int m = 0; m < 4; ++m) for (int n = 0; n < 2; ++n) for (int k = 0; k < 2; ++k) \
;       acc[ai][bj][m][n] = __builtin_amdgcn_mfma_f32_16x16x32_bf16(Btf[n][k], At[m][k], acc[ai][bj][m][n], 0, 0, 0); \
;     __builtin_amdgcn_s_setprio(0); } while (0)
; #define WAIT_V(n) asm volatile("s_waitcnt vmcnt(" #n ")" ::: "memory")
; #define WAIT_L(n) asm volatile("s_waitcnt lgkmcnt(" #n ")" ::: "memory")
; #define BAR __builtin_amdgcn_s_barrier()
; template <bool OVL, bool PANEL = false, class Epi>
; __device__ __forceinline__ void gemm_phase(const bf16_t* __restrict__ A, long lda, const bf16_t* __restrict__ Bt, long ldb, int nM, int nN, int K,
;                                            const Epi& epi, bf16_t* shm, int w0) {
;     ...
;       LDA(At, 0, 1); WAIT_V(4); BAR; WAIT_L(0); MMA(1, 0, At, B0); MMA(1, 1, At, B1); BAR; }
	s_barrier
	s_nop 0
	ds_read_b128 v[78:81], v241 offset:16384
	ds_read_b128 v[82:85], v241 offset:17408
	ds_read_b128 v[86:89], v241 offset:18432
	ds_read_b128 v[94:97], v241 offset:19456
	ds_read_b128 v[162:165], v241 offset:20480
	ds_read_b128 v[166:169], v241 offset:21504
	ds_read_b128 v[170:173], v241 offset:22528
	ds_read_b128 v[174:177], v241 offset:23552
	s_waitcnt vmcnt(4)
	s_barrier
	s_waitcnt lgkmcnt(0)

; #define LDA(dst, b, h) for (int m = 0; m < 4; ++m) for (int k = 0; k < 2; ++k) \
;     dst[m][k] = *reinterpret_cast<const bf16x8*>((char*)SA(b, h) + a_thr + (m * 2 + k) * 1024)
; #define MMA(ai, bj, At, Btf) do { __builtin_amdgcn_s_setprio(1); \
;     for (int m = 0; m < 4; ++m) for (int n = 0; n < 2; ++n) for (int k = 0; k < 2; ++k) \
;       acc[ai][bj][m][n] = __builtin_amdgcn_mfma_f32_16x16x32_bf16(Btf[n][k], At[m][k], acc[ai][bj][m][n], 0, 0, 0); \
;     __builtin_amdgcn_s_setprio(0); } while (0)
; #define WAIT_V(n) asm volatile("s_waitcnt vmcnt(" #n ")" ::: "memory")
; #define WAIT_L(n) asm volatile("s_waitcnt lgkmcnt(" #n ")" ::: "memory")
; #define BAR __builtin_amdgcn_s_barrier()
; template <bool OVL, bool PANEL = false, class Epi>
; __device__ __forceinline__ void gemm_phase(const bf16_t* __restrict__ A, long lda, const bf16_t* __restrict__ Bt, long ldb, int nM, int nN, int K,
;                                            const Epi& epi, bf16_t* shm, int w0) {
;     ...
;       LDA(At, 0, 1); WAIT_V(4); BAR; WAIT_L(0); MMA(1, 0, At, B0); MMA(1, 1, At, B1); BAR; }
	s_waitcnt lgkmcnt(0)
	v_mfma_f32_16x16x32_bf16 v[62:65], v[130:133], v[78:81], v[62:65]
	v_mfma_f32_16x16x32_bf16 v[58:61], v[142:145], v[78:81], v[58:61]
	v_mfma_f32_16x16x32_bf16 v[54:57], v[130:133], v[86:89], v[54:57]
	v_mfma_f32_16x16x32_bf16 v[50:53], v[142:145], v[86:89], v[50:53]
	v_mfma_f32_16x16x32_bf16 v[46:49], v[130:133], v[162:165], v[46:49]
	v_mfma_f32_16x16x32_bf16 v[42:45], v[142:145], v[162:165], v[42:45]
	v_mfma_f32_16x16x32_bf16 v[34:37], v[142:145], v[170:173], v[34:37]
	v_mfma_f32_16x16x32_bf16 v[62:65], v[138:141], v[82:85], v[62:65]
	v_mfma_f32_16x16x32_bf16 v[58:61], v[146:149], v[82:85], v[58:61]
	v_mfma_f32_16x16x32_bf16 v[54:57], v[138:141], v[94:97], v[54:57]
	v_mfma_f32_16x16x32_bf16 v[50:53], v[146:149], v[94:97], v[50:53]
	v_mfma_f32_16x16x32_bf16 v[46:49], v[138:141], v[166:169], v[46:49]
	v_mfma_f32_16x16x32_bf16 v[42:45], v[146:149], v[166:169], v[42:45]
	v_mfma_f32_16x16x32_bf16 v[38:41], v[130:133], v[170:173], v[38:41]
	v_mfma_f32_16x16x32_bf16 v[34:37], v[146:149], v[174:177], v[34:37]
	v_mfma_f32_16x16x32_bf16 v[130:133], v[138:141], v[174:177], v[38:41]


; #define LDA(dst, b, h) for (int m = 0; m < 4; ++m) for (int k = 0; k < 2; ++k) \
;     dst[m][k] = *reinterpret_cast<const bf16x8*>((char*)SA(b, h) + a_thr + (m * 2 + k) * 1024)
; #define MMA(ai, bj, At, Btf) do { __builtin_amdgcn_s_setprio(1); \
;     for (int m = 0; m < 4; ++m) for (int n = 0; n < 2; ++n) for (int k = 0; k < 2; ++k) \
;       acc[ai][bj][m][n] = __builtin_amdgcn_mfma_f32_16x16x32_bf16(Btf[n][k], At[m][k], acc[ai][bj][m][n], 0, 0, 0); \
;     __builtin_amdgcn_s_setprio(0); } while (0)
; #define WAIT_V(n) asm volatile("s_waitcnt vmcnt(" #n ")" ::: "memory")
; #define WAIT_L(n) asm volatile("s_waitcnt lgkmcnt(" #n ")" ::: "memory")
; #define BAR __builtin_amdgcn_s_barrier()
; template <bool OVL, bool PANEL = false, class Epi>
; __device__ __forceinline__ void gemm_phase(const bf16_t* __restrict__ A, long lda, const bf16_t* __restrict__ Bt, long ldb, int nM, int nN, int K,
;                                            const Epi& epi, bf16_t* shm, int w0) {
;     ...
;       LDA(At, 0, 1); WAIT_V(4); BAR; WAIT_L(0); MMA(1, 0, At, B0); MMA(1, 1, At, B1); BAR; }
	v_mfma_f32_16x16x32_bf16 v[30:33], v[110:113], v[78:81], v[30:33]
	v_mfma_f32_16x16x32_bf16 v[26:29], v[186:189], v[78:81], v[26:29]
	v_mfma_f32_16x16x32_bf16 v[22:25], v[110:113], v[86:89], v[22:25]
	v_mfma_f32_16x16x32_bf16 v[18:21], v[186:189], v[86:89], v[18:21]
	v_mfma_f32_16x16x32_bf16 v[14:17], v[110:113], v[162:165], v[14:17]
	v_mfma_f32_16x16x32_bf16 v[10:13], v[186:189], v[162:165], v[10:13]
	v_mfma_f32_16x16x32_bf16 v[6:9], v[110:113], v[170:173], v[6:9]
	v_mfma_f32_16x16x32_bf16 v[2:5], v[186:189], v[170:173], v[2:5]
	v_mfma_f32_16x16x32_bf16 v[138:141], v[182:185], v[82:85], v[30:33]
	v_mfma_f32_16x16x32_bf16 v[142:145], v[190:193], v[82:85], v[26:29]
	v_mfma_f32_16x16x32_bf16 v[146:149], v[182:185], v[94:97], v[22:25]
	v_mfma_f32_16x16x32_bf16 v[178:181], v[190:193], v[94:97], v[18:21]
	v_mfma_f32_16x16x32_bf16 v[198:201], v[182:185], v[166:169], v[14:17]
	v_mfma_f32_16x16x32_bf16 v[162:165], v[190:193], v[166:169], v[10:13]
	v_mfma_f32_16x16x32_bf16 v[166:169], v[182:185], v[174:177], v[6:9]
	v_mfma_f32_16x16x32_bf16 v[170:173], v[190:193], v[174:177], v[2:5]

; #define LDA(dst, b, h) for (int m = 0; m < 4; ++m) for (int k = 0; k < 2; ++k) \
;     dst[m][k] = *reinterpret_cast<const bf16x8*>((char*)SA(b, h) + a_thr + (m * 2 + k) * 1024)
; #define LDB(dst, b, h) for (int n = 0; n < 2; ++n) for (int k = 0; k < 2; ++k) \
;     dst[n][k] = *reinterpret_cast<const bf16x8*>((char*)SB(b, h) + b_thr + (n * 2 + k) * 1024)
; #define MMA(ai, bj, At, Btf) do { __builtin_amdgcn_s_setprio(1); \
;     for (int m = 0; m < 4; ++m) for (int n = 0; n < 2; ++n) for (int k = 0; k < 2; ++k) \
;       acc[ai][bj][m][n] = __builtin_amdgcn_mfma_f32_16x16x32_bf16(Btf[n][k], At[m][k], acc[ai][bj][m][n], 0, 0, 0); \
;     __builtin_amdgcn_s_setprio(0); } while (0)
; #define WAIT_V(n) asm volatile("s_waitcnt vmcnt(" #n ")" ::: "memory")
; #define WAIT_L(n) asm volatile("s_waitcnt lgkmcnt(" #n ")" ::: "memory")
; #define BAR __builtin_amdgcn_s_barrier()
; template <bool OVL, bool PANEL = false, class Epi>
; __device__ __forceinline__ void gemm_phase(const bf16_t* __restrict__ A, long lda, const bf16_t* __restrict__ Bt, long ldb, int nM, int nN, int K,
;                                            const Epi& epi, bf16_t* shm, int w0) {
;     ...
;     { LDB(B0, 1, 0); LDA(At, 1, 0); WAIT_V(2); BAR; WAIT_L(0); MMA(0, 0, At, B0); BAR;
	v_add_u32_e32 v0, 0x18000, v206
	s_barrier
	ds_read_b128 v[174:177], v0
	ds_read_b128 v[182:185], v0 offset:1024
	ds_read_b128 v[186:189], v0 offset:2048
	ds_read_b128 v[190:193], v0 offset:3072
	ds_read_b128 v[6:9], v241 offset:32768
	ds_read_b128 v[14:17], v241 offset:33792
	ds_read_b128 v[18:21], v241 offset:34816
	ds_read_b128 v[22:25], v241 offset:35840
	ds_read_b128 v[26:29], v241 offset:36864
	ds_read_b128 v[30:33], v241 offset:37888
	ds_read_b128 v[38:41], v241 offset:38912
	ds_read_b128 v[202:205], v241 offset:39936
	s_waitcnt vmcnt(2)
	s_barrier
	s_waitcnt lgkmcnt(0)

; #define LDA(dst, b, h) for (int m = 0; m < 4; ++m) for (int k = 0; k < 2; ++k) \
;     dst[m][k] = *reinterpret_cast<const bf16x8*>((char*)SA(b, h) + a_thr + (m * 2 + k) * 1024)
; #define LDB(dst, b, h) for (int n = 0; n < 2; ++n) for (int k = 0; k < 2; ++k) \
;     dst[n][k] = *reinterpret_cast<const bf16x8*>((char*)SB(b, h) + b_thr + (n * 2 + k) * 1024)
; #define MMA(ai, bj, At, Btf) do { __builtin_amdgcn_s_setprio(1); \
;     for (int m = 0; m < 4; ++m) for (int n = 0; n < 2; ++n) for (int k = 0; k < 2; ++k) \
;       acc[ai][bj][m][n] = __builtin_amdgcn_mfma_f32_16x16x32_bf16(Btf[n][k], At[m][k], acc[ai][bj][m][n], 0, 0, 0); \
;     __builtin_amdgcn_s_setprio(0); } while (0)
; #define WAIT_V(n) asm volatile("s_waitcnt vmcnt(" #n ")" ::: "memory")
; #define WAIT_L(n) asm volatile("s_waitcnt lgkmcnt(" #n ")" ::: "memory")
; #define BAR __builtin_amdgcn_s_barrier()
; template <bool OVL, bool PANEL = false, class Epi>
; __device__ __forceinline__ void gemm_phase(const bf16_t* __restrict__ A, long lda, const bf16_t* __restrict__ Bt, long ldb, int nM, int nN, int K,
;                                            const Epi& epi, bf16_t* shm, int w0) {
;     ...
;     { LDB(B0, 1, 0); LDA(At, 1, 0); WAIT_V(2); BAR; WAIT_L(0); MMA(0, 0, At, B0); BAR;
	s_waitcnt lgkmcnt(0)
	v_mfma_f32_16x16x32_bf16 v[2:5], v[174:177], v[6:9], v[126:129]
	v_mfma_f32_16x16x32_bf16 v[126:129], v[182:185], v[14:17], v[2:5]
	v_mfma_f32_16x16x32_bf16 v[2:5], v[186:189], v[6:9], v[122:125]
	v_mfma_f32_16x16x32_bf16 v[82:85], v[190:193], v[14:17], v[2:5]
	v_mfma_f32_16x16x32_bf16 v[2:5], v[174:177], v[18:21], v[118:121]
	v_mfma_f32_16x16x32_bf16 v[110:113], v[182:185], v[22:25], v[2:5]
	v_mfma_f32_16x16x32_bf16 v[2:5], v[186:189], v[18:21], v[114:117]
	v_mfma_f32_16x16x32_bf16 v[86:89], v[190:193], v[22:25], v[2:5]
	v_mfma_f32_16x16x32_bf16 v[2:5], v[174:177], v[26:29], v[134:137]
	v_mfma_f32_16x16x32_bf16 v[94:97], v[182:185], v[30:33], v[2:5]
	v_mfma_f32_16x16x32_bf16 v[2:5], v[186:189], v[26:29], v[106:109]
	v_mfma_f32_16x16x32_bf16 v[78:81], v[190:193], v[30:33], v[2:5]
	v_mfma_f32_16x16x32_bf16 v[2:5], v[174:177], v[38:41], v[102:105]
	v_mfma_f32_16x16x32_bf16 v[10:13], v[186:189], v[38:41], v[98:101]
	v_mfma_f32_16x16x32_bf16 v[2:5], v[182:185], v[202:205], v[2:5]
	v_mfma_f32_16x16x32_bf16 v[10:13], v[190:193], v[202:205], v[10:13]

; #define LDB(dst, b, h) for (int n = 0; n < 2; ++n) for (int k = 0; k < 2; ++k) \
;     dst[n][k] = *reinterpret_cast<const bf16x8*>((char*)SB(b, h) + b_thr + (n * 2 + k) * 1024)
; #define MMA(ai, bj, At, Btf) do { __builtin_amdgcn_s_setprio(1); \
;     for (int m = 0; m < 4; ++m) for (int n = 0; n < 2; ++n) for (int k = 0; k < 2; ++k) \
;       acc[ai][bj][m][n] = __builtin_amdgcn_mfma_f32_16x16x32_bf16(Btf[n][k], At[m][k], acc[ai][bj][m][n], 0, 0, 0); \
;     __builtin_amdgcn_s_setprio(0); } while (0)
; #define WAIT_V(n) asm volatile("s_waitcnt vmcnt(" #n ")" ::: "memory")
; #define WAIT_L(n) asm volatile("s_waitcnt lgkmcnt(" #n ")" ::: "memory")
; #define BAR __builtin_amdgcn_s_barrier()
; template <bool OVL, bool PANEL = false, class Epi>
; __device__ __forceinline__ void gemm_phase(const bf16_t* __restrict__ A, long lda, const bf16_t* __restrict__ Bt, long ldb, int nM, int nN, int K,
;                                            const Epi& epi, bf16_t* shm, int w0) {
;     ...
;       LDB(B1, 1, 1); WAIT_V(0); BAR; WAIT_L(0); MMA(0, 1, At, B1); BAR;
	v_add_u32_e32 v0, 0x1c000, v206
	s_barrier
	ds_read_b128 v[122:125], v0
	ds_read_b128 v[134:137], v0 offset:1024
	ds_read_b128 v[206:209], v0 offset:2048
	ds_read_b128 v[210:213], v0 offset:3072
	s_waitcnt vmcnt(0)
	s_barrier
	s_waitcnt lgkmcnt(0)

; #define LDB(dst, b, h) for (int n = 0; n < 2; ++n) for (int k = 0; k < 2; ++k) \
;     dst[n][k] = *reinterpret_cast<const bf16x8*>((char*)SB(b, h) + b_thr + (n * 2 + k) * 1024)
; #define MMA(ai, bj, At, Btf) do { __builtin_amdgcn_s_setprio(1); \
;     for (int m = 0; m < 4; ++m) for (int n = 0; n < 2; ++n) for (int k = 0; k < 2; ++k) \
;       acc[ai][bj][m][n] = __builtin_amdgcn_mfma_f32_16x16x32_bf16(Btf[n][k], At[m][k], acc[ai][bj][m][n], 0, 0, 0); \
;     __builtin_amdgcn_s_setprio(0); } while (0)
; #define WAIT_V(n) asm volatile("s_waitcnt vmcnt(" #n ")" ::: "memory")
; #define WAIT_L(n) asm volatile("s_waitcnt lgkmcnt(" #n ")" ::: "memory")
; #define BAR __builtin_amdgcn_s_barrier()
; template <bool OVL, bool PANEL = false, class Epi>
; __device__ __forceinline__ void gemm_phase(const bf16_t* __restrict__ A, long lda, const bf16_t* __restrict__ Bt, long ldb, int nM, int nN, int K,
;                                            const Epi& epi, bf16_t* shm, int w0) {
;     ...
;       LDB(B1, 1, 1); WAIT_V(0); BAR; WAIT_L(0); MMA(0, 1, At, B1); BAR;
	s_waitcnt lgkmcnt(0)
	v_mfma_f32_16x16x32_bf16 v[98:101], v[122:125], v[6:9], v[194:197]
	v_mfma_f32_16x16x32_bf16 v[6:9], v[206:209], v[6:9], v[90:93]
	v_mfma_f32_16x16x32_bf16 v[114:117], v[210:213], v[14:17], v[6:9]
	v_mfma_f32_16x16x32_bf16 v[6:9], v[122:125], v[18:21], v[150:153]
	v_mfma_f32_16x16x32_bf16 v[102:105], v[134:137], v[22:25], v[6:9]
	v_mfma_f32_16x16x32_bf16 v[6:9], v[206:209], v[18:21], v[154:157]
	v_mfma_f32_16x16x32_bf16 v[118:121], v[210:213], v[22:25], v[6:9]
	v_mfma_f32_16x16x32_bf16 v[6:9], v[122:125], v[26:29], v[158:161]
	v_mfma_f32_16x16x32_bf16 v[90:93], v[134:137], v[30:33], v[6:9]
	v_mfma_f32_16x16x32_bf16 v[6:9], v[206:209], v[26:29], v[74:77]
	v_mfma_f32_16x16x32_bf16 v[106:109], v[210:213], v[30:33], v[6:9]
	v_mfma_f32_16x16x32_bf16 v[6:9], v[122:125], v[38:41], v[70:73]
	v_mfma_f32_16x16x32_bf16 v[22:25], v[134:137], v[202:205], v[6:9]
	v_mfma_f32_16x16x32_bf16 v[6:9], v[206:209], v[38:41], v[66:69]
	v_mfma_f32_16x16x32_bf16 v[98:101], v[134:137], v[14:17], v[98:101]
	v_mfma_f32_16x16x32_bf16 v[38:41], v[210:213], v[202:205], v[6:9]

; #define LDA(dst, b, h) for (int m = 0; m < 4; ++m) for (int k = 0; k < 2; ++k) \
;     dst[m][k] = *reinterpret_cast<const bf16x8*>((char*)SA(b, h) + a_thr + (m * 2 + k) * 1024)
; #define MMA(ai, bj, At, Btf) do { __builtin_amdgcn_s_setprio(1); \
;     for (int m = 0; m < 4; ++m) for (int n = 0; n < 2; ++n) for (int k = 0; k < 2; ++k) \
;       acc[ai][bj][m][n] = __builtin_amdgcn_mfma_f32_16x16x32_bf16(Btf[n][k], At[m][k], acc[ai][bj][m][n], 0, 0, 0); \
;     __builtin_amdgcn_s_setprio(0); } while (0)
; #define WAIT_L(n) asm volatile("s_waitcnt lgkmcnt(" #n ")" ::: "memory")
; #define BAR __builtin_amdgcn_s_barrier()
; template <bool OVL, bool PANEL = false, class Epi>
; __device__ __forceinline__ void gemm_phase(const bf16_t* __restrict__ A, long lda, const bf16_t* __restrict__ Bt, long ldb, int nM, int nN, int K,
;                                            const Epi& epi, bf16_t* shm, int w0) {
;     ...
;       LDA(At, 1, 1); BAR; WAIT_L(0); MMA(1, 0, At, B0); MMA(1, 1, At, B1); BAR; }
	s_barrier
	ds_read_b128 v[70:73], v241 offset:49152
	ds_read_b128 v[74:77], v241 offset:50176
	ds_read_b128 v[150:153], v241 offset:51200
	ds_read_b128 v[154:157], v241 offset:52224
	ds_read_b128 v[158:161], v241 offset:53248
	ds_read_b128 v[194:197], v241 offset:54272
	ds_read_b128 v[202:205], v241 offset:55296
	ds_read_b128 v[214:217], v241 offset:56320
	s_barrier
	s_waitcnt lgkmcnt(0)

; #define LDA(dst, b, h) for (int m = 0; m < 4; ++m) for (int k = 0; k < 2; ++k) \
;     dst[m][k] = *reinterpret_cast<const bf16x8*>((char*)SA(b, h) + a_thr + (m * 2 + k) * 1024)
; #define MMA(ai, bj, At, Btf) do { __builtin_amdgcn_s_setprio(1); \
;     for (int m = 0; m < 4; ++m) for (int n = 0; n < 2; ++n) for (int k = 0; k < 2; ++k) \
;       acc[ai][bj][m][n] = __builtin_amdgcn_mfma_f32_16x16x32_bf16(Btf[n][k], At[m][k], acc[ai][bj][m][n], 0, 0, 0); \
;     __builtin_amdgcn_s_setprio(0); } while (0)
; #define WAIT_L(n) asm volatile("s_waitcnt lgkmcnt(" #n ")" ::: "memory")
; #define BAR __builtin_amdgcn_s_barrier()
; template <bool OVL, bool PANEL = false, class Epi>
; __device__ __forceinline__ void gemm_phase(const bf16_t* __restrict__ A, long lda, const bf16_t* __restrict__ Bt, long ldb, int nM, int nN, int K,
;                                            const Epi& epi, bf16_t* shm, int w0) {
;     ...
;       LDA(At, 1, 1); BAR; WAIT_L(0); MMA(1, 0, At, B0); MMA(1, 1, At, B1); BAR; }
	s_waitcnt lgkmcnt(0)
	v_mfma_f32_16x16x32_bf16 v[14:17], v[186:189], v[70:73], v[58:61]
	v_mfma_f32_16x16x32_bf16 v[42:45], v[186:189], v[158:161], v[42:45]
	v_mfma_f32_16x16x32_bf16 v[6:9], v[174:177], v[70:73], v[62:65]
	v_mfma_f32_16x16x32_bf16 v[18:21], v[190:193], v[74:77], v[14:17]
	v_mfma_f32_16x16x32_bf16 v[14:17], v[174:177], v[150:153], v[54:57]
	v_mfma_f32_16x16x32_bf16 v[26:29], v[186:189], v[150:153], v[50:53]
	v_mfma_f32_16x16x32_bf16 v[30:33], v[174:177], v[158:161], v[46:49]
	v_mfma_f32_16x16x32_bf16 v[46:49], v[190:193], v[194:197], v[42:45]
	v_mfma_f32_16x16x32_bf16 v[42:45], v[174:177], v[202:205], v[130:133]
	v_mfma_f32_16x16x32_bf16 v[34:37], v[186:189], v[202:205], v[34:37]
	v_mfma_f32_16x16x32_bf16 v[6:9], v[182:185], v[74:77], v[6:9]
	v_mfma_f32_16x16x32_bf16 v[14:17], v[182:185], v[154:157], v[14:17]
	v_mfma_f32_16x16x32_bf16 v[26:29], v[190:193], v[154:157], v[26:29]
	v_mfma_f32_16x16x32_bf16 v[30:33], v[182:185], v[194:197], v[30:33]
	v_mfma_f32_16x16x32_bf16 v[54:57], v[182:185], v[214:217], v[42:45]
	v_mfma_f32_16x16x32_bf16 v[66:69], v[190:193], v[214:217], v[34:37]


; #define LDA(dst, b, h) for (int m = 0; m < 4; ++m) for (int k = 0; k < 2; ++k) \
;     dst[m][k] = *reinterpret_cast<const bf16x8*>((char*)SA(b, h) + a_thr + (m * 2 + k) * 1024)
; #define MMA(ai, bj, At, Btf) do { __builtin_amdgcn_s_setprio(1); \
;     for (int m = 0; m < 4; ++m) for (int n = 0; n < 2; ++n) for (int k = 0; k < 2; ++k) \
;       acc[ai][bj][m][n] = __builtin_amdgcn_mfma_f32_16x16x32_bf16(Btf[n][k], At[m][k], acc[ai][bj][m][n], 0, 0, 0); \
;     __builtin_amdgcn_s_setprio(0); } while (0)
; #define WAIT_L(n) asm volatile("s_waitcnt lgkmcnt(" #n ")" ::: "memory")
; #define BAR __builtin_amdgcn_s_barrier()
; template <bool OVL, bool PANEL = false, class Epi>
; __device__ __forceinline__ void gemm_phase(const bf16_t* __restrict__ A, long lda, const bf16_t* __restrict__ Bt, long ldb, int nM, int nN, int K,
;                                            const Epi& epi, bf16_t* shm, int w0) {
;     ...
;       LDA(At, 1, 1); BAR; WAIT_L(0); MMA(1, 0, At, B0); MMA(1, 1, At, B1); BAR; }
	v_mfma_f32_16x16x32_bf16 v[34:37], v[122:125], v[70:73], v[138:141]
	v_mfma_f32_16x16x32_bf16 v[42:45], v[206:209], v[70:73], v[142:145]
	v_mfma_f32_16x16x32_bf16 v[34:37], v[134:137], v[74:77], v[34:37]
	v_mfma_f32_16x16x32_bf16 v[50:53], v[210:213], v[74:77], v[42:45]
	v_mfma_f32_16x16x32_bf16 v[42:45], v[122:125], v[150:153], v[146:149]
	v_mfma_f32_16x16x32_bf16 v[58:61], v[206:209], v[150:153], v[178:181]
	v_mfma_f32_16x16x32_bf16 v[62:65], v[122:125], v[158:161], v[198:201]
	v_mfma_f32_16x16x32_bf16 v[70:73], v[206:209], v[158:161], v[162:165]
	v_mfma_f32_16x16x32_bf16 v[74:77], v[122:125], v[202:205], v[166:169]
	v_mfma_f32_16x16x32_bf16 v[122:125], v[206:209], v[202:205], v[170:173]
	v_mfma_f32_16x16x32_bf16 v[42:45], v[134:137], v[154:157], v[42:45]
	v_mfma_f32_16x16x32_bf16 v[58:61], v[210:213], v[154:157], v[58:61]
	v_mfma_f32_16x16x32_bf16 v[62:65], v[134:137], v[194:197], v[62:65]
	v_mfma_f32_16x16x32_bf16 v[70:73], v[210:213], v[194:197], v[70:73]
	v_mfma_f32_16x16x32_bf16 v[74:77], v[134:137], v[214:217], v[74:77]
	v_mfma_f32_16x16x32_bf16 v[122:125], v[210:213], v[214:217], v[122:125]

; #define LDA(dst, b, h) for (int m = 0; m < 4; ++m) for (int k = 0; k < 2; ++k) \
;     dst[m][k] = *reinterpret_cast<const bf16x8*>((char*)SA(b, h) + a_thr + (m * 2 + k) * 1024)
; #define MMA(ai, bj, At, Btf) do { __builtin_amdgcn_s_setprio(1); \
;     for (int m = 0; m < 4; ++m) for (int n = 0; n < 2; ++n) for (int k = 0; k < 2; ++k) \
;       acc[ai][bj][m][n] = __builtin_amdgcn_mfma_f32_16x16x32_bf16(Btf[n][k], At[m][k], acc[ai][bj][m][n], 0, 0, 0); \
;     __builtin_amdgcn_s_setprio(0); } while (0)
; #define WAIT_L(n) asm volatile("s_waitcnt lgkmcnt(" #n ")" ::: "memory")
; #define BAR __builtin_amdgcn_s_barrier()
; template <bool OVL, bool PANEL = false, class Epi>
; __device__ __forceinline__ void gemm_phase(const bf16_t* __restrict__ A, long lda, const bf16_t* __restrict__ Bt, long ldb, int nM, int nN, int K,
;                                            const Epi& epi, bf16_t* shm, int w0) {
;     ...
;       LDA(At, 1, 1); BAR; WAIT_L(0); MMA(1, 0, At, B0); MMA(1, 1, At, B1); BAR; }
;     if (wr == 0) BAR;
	s_barrier
	s_and_saveexec_b64 s[0:1], s[90:91]
	s_cbranch_execz .LBB0_475
	s_barrier

; #define LDA(dst, b, h) for (int m = 0; m < 4; ++m) for (int k = 0; k < 2; ++k) \
;     dst[m][k] = *reinterpret_cast<const bf16x8*>((char*)SA(b, h) + a_thr + (m * 2 + k) * 1024)
; #define LDB(dst, b, h) for (int n = 0; n < 2; ++n) for (int k = 0; k < 2; ++k) \
;     dst[n][k] = *reinterpret_cast<const bf16x8*>((char*)SB(b, h) + b_thr + (n * 2 + k) * 1024)
; #define MMA(ai, bj, At, Btf) do { __builtin_amdgcn_s_setprio(1); \
;     for (int m = 0; m < 4; ++m) for (int n = 0; n < 2; ++n) for (int k = 0; k < 2; ++k) \
;       acc[ai][bj][m][n] = __builtin_amdgcn_mfma_f32_16x16x32_bf16(Btf[n][k], At[m][k], acc[ai][bj][m][n], 0, 0, 0); \
;     __builtin_amdgcn_s_setprio(0); } while (0)
; #define WAIT_V(n) asm volatile("s_waitcnt vmcnt(" #n ")" ::: "memory")
; #define WAIT_L(n) asm volatile("s_waitcnt lgkmcnt(" #n ")" ::: "memory")
; #define BAR __builtin_amdgcn_s_barrier()
; #define SCHED __builtin_amdgcn_sched_barrier(0)
; template <bool OVL, bool PANEL = false, class Epi>
; __device__ __forceinline__ void gemm_phase(const bf16_t* __restrict__ A, long lda, const bf16_t* __restrict__ Bt, long ldb, int nM, int nN, int K,
;                                            const Epi& epi, bf16_t* shm, int w0) {
;     ...
;       LDB(B0, 0, 0); SCHED; LDA(At, 0, 0); STAGE(SA(1, 1), A, lda, aoff, brow + HALF, t + 1);
;       WAIT_L(8); BAR; WAIT_L(0); MMA(0, 0, At, B0); BAR; SCHED;
;       LDB(B1, 0, 1); STAGE(SB(0, 0), Bt, ldb, boff, bcol, t + 2);
;       BAR; WAIT_L(0); MMA(0, 1, At, B1); BAR;
;       LDA(At, 0, 1); STAGE(SA(0, 0), A, lda, aoff, brow, t + 2);
;       BAR; WAIT_L(0); MMA(1, 0, At, B0); BAR; SCHED;
;       STAGE(SB(0, 1), Bt, ldb, boff, bcol + HALF, t + 2);
;       WAIT_V(6); BAR; MMA(1, 1, At, B1); BAR;
.LBB0_1053:
	ds_read_b128 v[152:155], v184
	ds_read_b128 v[156:159], v184 offset:1024
	ds_read_b128 v[160:163], v184 offset:2048
	ds_read_b128 v[164:167], v184 offset:3072
	s_add_u32 s40, s10, s14
	s_addc_u32 s41, s11, s15
	ds_read_b128 v[168:171], v147
	ds_read_b128 v[172:175], v147 offset:1024
	ds_read_b128 v[176:179], v147 offset:2048
	ds_read_b128 v[194:197], v147 offset:3072
	ds_read_b128 v[198:201], v147 offset:4096
	ds_read_b128 v[202:205], v147 offset:5120
	ds_read_b128 v[206:209], v147 offset:6144
	ds_read_b128 v[210:213], v147 offset:7168
	s_mov_b32 m0, s22
	s_add_u32 s98, s40, s16
	s_addc_u32 s99, s41, s17
	global_load_lds_dwordx4 v135, s[98:99]
	s_mov_b32 m0, s23
	s_add_u32 s98, s40, s36
	s_addc_u32 s99, s41, s37
	global_load_lds_dwordx4 v135, s[98:99]
	s_waitcnt lgkmcnt(0)
	s_waitcnt vmcnt(10)
	s_barrier
	v_mfma_f32_16x16x32_bf16 v[126:129], v[152:155], v[168:171], v[126:129]
	v_mfma_f32_16x16x32_bf16 v[122:125], v[160:163], v[168:171], v[122:125]
	v_mfma_f32_16x16x32_bf16 v[118:121], v[152:155], v[176:179], v[118:121]
	v_mfma_f32_16x16x32_bf16 v[114:117], v[160:163], v[176:179], v[114:117]
	v_mfma_f32_16x16x32_bf16 v[110:113], v[152:155], v[198:201], v[110:113]
	v_mfma_f32_16x16x32_bf16 v[106:109], v[160:163], v[198:201], v[106:109]
	v_mfma_f32_16x16x32_bf16 v[102:105], v[152:155], v[206:209], v[102:105]
	v_mfma_f32_16x16x32_bf16 v[98:101], v[160:163], v[206:209], v[98:101]
	v_mfma_f32_16x16x32_bf16 v[126:129], v[156:159], v[172:175], v[126:129]
	v_mfma_f32_16x16x32_bf16 v[122:125], v[164:167], v[172:175], v[122:125]
	v_mfma_f32_16x16x32_bf16 v[118:121], v[156:159], v[194:197], v[118:121]
	v_mfma_f32_16x16x32_bf16 v[114:117], v[164:167], v[194:197], v[114:117]
	v_mfma_f32_16x16x32_bf16 v[110:113], v[156:159], v[202:205], v[110:113]
	v_mfma_f32_16x16x32_bf16 v[106:109], v[164:167], v[202:205], v[106:109]
	v_mfma_f32_16x16x32_bf16 v[102:105], v[156:159], v[210:213], v[102:105]
	v_mfma_f32_16x16x32_bf16 v[98:101], v[164:167], v[210:213], v[98:101]
	s_barrier
	s_add_u32 s42, s8, s14
	ds_read_b128 v[214:217], v185
	ds_read_b128 v[218:221], v185 offset:1024
	ds_read_b128 v[234:237], v185 offset:2048
	ds_read_b128 v[238:241], v185 offset:3072
	s_addc_u32 s43, s9, s15
	s_mov_b32 m0, s24
	s_add_u32 s98, s42, s34
	s_addc_u32 s99, s43, s35
	global_load_lds_dwordx4 v135, s[98:99]
	s_mov_b32 m0, s25
	s_add_u32 s98, s42, s64
	s_addc_u32 s99, s43, s65
	global_load_lds_dwordx4 v135, s[98:99]
	s_waitcnt lgkmcnt(0)
	s_waitcnt vmcnt(10)
	s_barrier
	v_mfma_f32_16x16x32_bf16 v[94:97], v[214:217], v[168:171], v[94:97]
	v_mfma_f32_16x16x32_bf16 v[90:93], v[234:237], v[168:171], v[90:93]
	v_mfma_f32_16x16x32_bf16 v[86:89], v[214:217], v[176:179], v[86:89]
	v_mfma_f32_16x16x32_bf16 v[82:85], v[234:237], v[176:179], v[82:85]
	v_mfma_f32_16x16x32_bf16 v[78:81], v[214:217], v[198:201], v[78:81]
	v_mfma_f32_16x16x32_bf16 v[74:77], v[234:237], v[198:201], v[74:77]
	v_mfma_f32_16x16x32_bf16 v[70:73], v[214:217], v[206:209], v[70:73]
	v_mfma_f32_16x16x32_bf16 v[66:69], v[234:237], v[206:209], v[66:69]
	v_mfma_f32_16x16x32_bf16 v[94:97], v[218:221], v[172:175], v[94:97]
	v_mfma_f32_16x16x32_bf16 v[90:93], v[238:241], v[172:175], v[90:93]
	v_mfma_f32_16x16x32_bf16 v[86:89], v[218:221], v[194:197], v[86:89]
	v_mfma_f32_16x16x32_bf16 v[82:85], v[238:241], v[194:197], v[82:85]
	v_mfma_f32_16x16x32_bf16 v[78:81], v[218:221], v[202:205], v[78:81]
	v_mfma_f32_16x16x32_bf16 v[74:77], v[238:241], v[202:205], v[74:77]
	v_mfma_f32_16x16x32_bf16 v[70:73], v[218:221], v[210:213], v[70:73]
	v_mfma_f32_16x16x32_bf16 v[66:69], v[238:241], v[210:213], v[66:69]
	s_barrier
	ds_read_b128 v[168:171], v147 offset:16384
	ds_read_b128 v[172:175], v147 offset:17408
	ds_read_b128 v[176:179], v147 offset:18432
	ds_read_b128 v[194:197], v147 offset:19456
	ds_read_b128 v[198:201], v147 offset:20480
	ds_read_b128 v[202:205], v147 offset:21504
	ds_read_b128 v[206:209], v147 offset:22528
	ds_read_b128 v[210:213], v147 offset:23552
	s_mov_b32 m0, s26
	s_add_u32 s98, s40, s34
	s_addc_u32 s99, s41, s35
	global_load_lds_dwordx4 v135, s[98:99]
	s_mov_b32 m0, s27
	s_add_u32 s98, s40, s64
	s_addc_u32 s99, s41, s65
	global_load_lds_dwordx4 v135, s[98:99]
	s_waitcnt lgkmcnt(0)
	s_barrier
	v_mfma_f32_16x16x32_bf16 v[62:65], v[152:155], v[168:171], v[62:65]
	v_mfma_f32_16x16x32_bf16 v[58:61], v[160:163], v[168:171], v[58:61]
	v_mfma_f32_16x16x32_bf16 v[54:57], v[152:155], v[176:179], v[54:57]
	v_mfma_f32_16x16x32_bf16 v[50:53], v[160:163], v[176:179], v[50:53]
	v_mfma_f32_16x16x32_bf16 v[46:49], v[152:155], v[198:201], v[46:49]
	v_mfma_f32_16x16x32_bf16 v[42:45], v[160:163], v[198:201], v[42:45]
	v_mfma_f32_16x16x32_bf16 v[38:41], v[152:155], v[206:209], v[38:41]
	v_mfma_f32_16x16x32_bf16 v[34:37], v[160:163], v[206:209], v[34:37]
	v_mfma_f32_16x16x32_bf16 v[62:65], v[156:159], v[172:175], v[62:65]
	v_mfma_f32_16x16x32_bf16 v[58:61], v[164:167], v[172:175], v[58:61]
	v_mfma_f32_16x16x32_bf16 v[54:57], v[156:159], v[194:197], v[54:57]
	v_mfma_f32_16x16x32_bf16 v[50:53], v[164:167], v[194:197], v[50:53]
	v_mfma_f32_16x16x32_bf16 v[46:49], v[156:159], v[202:205], v[46:49]
	v_mfma_f32_16x16x32_bf16 v[42:45], v[164:167], v[202:205], v[42:45]
	v_mfma_f32_16x16x32_bf16 v[38:41], v[156:159], v[210:213], v[38:41]
	v_mfma_f32_16x16x32_bf16 v[34:37], v[164:167], v[210:213], v[34:37]
	s_barrier
	s_mov_b32 m0, s28
	s_add_u32 s98, s42, s68
	s_addc_u32 s99, s43, s69
	global_load_lds_dwordx4 v135, s[98:99]
	s_mov_b32 m0, s29
	s_add_u32 s98, s42, s70
	s_addc_u32 s99, s43, s71
	global_load_lds_dwordx4 v135, s[98:99]
	s_waitcnt vmcnt(10)
	s_barrier
; #define LDA(dst, b, h) for (int m = 0; m < 4; ++m) for (int k = 0; k < 2; ++k) \
;     dst[m][k] = *reinterpret_cast<const bf16x8*>((char*)SA(b, h) + a_thr + (m * 2 + k) * 1024)
; #define LDB(dst, b, h) for (int n = 0; n < 2; ++n) for (int k = 0; k < 2; ++k) \
;     dst[n][k] = *reinterpret_cast<const bf16x8*>((char*)SB(b, h) + b_thr + (n * 2 + k) * 1024)
; #define MMA(ai, bj, At, Btf) do { __builtin_amdgcn_s_setprio(1); \
;     for (int m = 0; m < 4; ++m) for (int n = 0; n < 2; ++n) for (int k = 0; k < 2; ++k) \
;       acc[ai][bj][m][n] = __builtin_amdgcn_mfma_f32_16x16x32_bf16(Btf[n][k], At[m][k], acc[ai][bj][m][n], 0, 0, 0); \
;     __builtin_amdgcn_s_setprio(0); } while (0)
; #define WAIT_V(n) asm volatile("s_waitcnt vmcnt(" #n ")" ::: "memory")
; #define WAIT_L(n) asm volatile("s_waitcnt lgkmcnt(" #n ")" ::: "memory")
; #define BAR __builtin_amdgcn_s_barrier()
; #define SCHED __builtin_amdgcn_sched_barrier(0)
; template <bool OVL, bool PANEL = false, class Epi>
; __device__ __forceinline__ void gemm_phase(const bf16_t* __restrict__ A, long lda, const bf16_t* __restrict__ Bt, long ldb, int nM, int nN, int K,
;                                            const Epi& epi, bf16_t* shm, int w0) {
;     ...
;       WAIT_V(6); BAR; MMA(1, 1, At, B1); BAR;
;       LDB(B0, 1, 0); SCHED; LDA(At, 1, 0); STAGE(SA(0, 1), A, lda, aoff, brow + HALF, t + 2);
;       WAIT_L(8); BAR; WAIT_L(0); MMA(0, 0, At, B0); BAR; SCHED;
;       LDB(B1, 1, 1); STAGE(SB(1, 0), Bt, ldb, boff, bcol, t + 3);
;       BAR; WAIT_L(0); MMA(0, 1, At, B1); BAR;
	v_mfma_f32_16x16x32_bf16 v[30:33], v[214:217], v[168:171], v[30:33]
	v_mfma_f32_16x16x32_bf16 v[26:29], v[234:237], v[168:171], v[26:29]
	v_mfma_f32_16x16x32_bf16 v[22:25], v[214:217], v[176:179], v[22:25]
	v_mfma_f32_16x16x32_bf16 v[18:21], v[234:237], v[176:179], v[18:21]
	v_mfma_f32_16x16x32_bf16 v[14:17], v[214:217], v[198:201], v[14:17]
	v_mfma_f32_16x16x32_bf16 v[10:13], v[234:237], v[198:201], v[10:13]
	v_mfma_f32_16x16x32_bf16 v[6:9], v[214:217], v[206:209], v[6:9]
	v_mfma_f32_16x16x32_bf16 v[2:5], v[234:237], v[206:209], v[2:5]
	v_mfma_f32_16x16x32_bf16 v[30:33], v[218:221], v[172:175], v[30:33]
	v_mfma_f32_16x16x32_bf16 v[26:29], v[238:241], v[172:175], v[26:29]
	v_mfma_f32_16x16x32_bf16 v[22:25], v[218:221], v[194:197], v[22:25]
	v_mfma_f32_16x16x32_bf16 v[18:21], v[238:241], v[194:197], v[18:21]
	v_mfma_f32_16x16x32_bf16 v[14:17], v[218:221], v[202:205], v[14:17]
	v_mfma_f32_16x16x32_bf16 v[10:13], v[238:241], v[202:205], v[10:13]
	v_mfma_f32_16x16x32_bf16 v[6:9], v[218:221], v[210:213], v[6:9]
	v_mfma_f32_16x16x32_bf16 v[2:5], v[238:241], v[210:213], v[2:5]
	s_barrier
	ds_read_b128 v[152:155], v186
	ds_read_b128 v[156:159], v186 offset:1024
	ds_read_b128 v[160:163], v186 offset:2048
	ds_read_b128 v[164:167], v186 offset:3072
	ds_read_b128 v[168:171], v147 offset:32768
	ds_read_b128 v[172:175], v147 offset:33792
	ds_read_b128 v[176:179], v147 offset:34816
	ds_read_b128 v[194:197], v147 offset:35840
	ds_read_b128 v[198:201], v147 offset:36864
	ds_read_b128 v[202:205], v147 offset:37888
	ds_read_b128 v[206:209], v147 offset:38912
	ds_read_b128 v[210:213], v147 offset:39936
	s_mov_b32 m0, s30
	s_add_u32 s98, s40, s68
	s_addc_u32 s99, s41, s69
	global_load_lds_dwordx4 v135, s[98:99]
	s_mov_b32 m0, s31
	s_add_u32 s98, s40, s70
	s_addc_u32 s99, s41, s71
	global_load_lds_dwordx4 v135, s[98:99]
	s_waitcnt lgkmcnt(0)
	s_waitcnt vmcnt(10)
	s_barrier
	v_mfma_f32_16x16x32_bf16 v[126:129], v[152:155], v[168:171], v[126:129]
	v_mfma_f32_16x16x32_bf16 v[122:125], v[160:163], v[168:171], v[122:125]
	v_mfma_f32_16x16x32_bf16 v[118:121], v[152:155], v[176:179], v[118:121]
	v_mfma_f32_16x16x32_bf16 v[114:117], v[160:163], v[176:179], v[114:117]
	v_mfma_f32_16x16x32_bf16 v[110:113], v[152:155], v[198:201], v[110:113]
	v_mfma_f32_16x16x32_bf16 v[106:109], v[160:163], v[198:201], v[106:109]
	v_mfma_f32_16x16x32_bf16 v[102:105], v[152:155], v[206:209], v[102:105]
	v_mfma_f32_16x16x32_bf16 v[98:101], v[160:163], v[206:209], v[98:101]
	v_mfma_f32_16x16x32_bf16 v[126:129], v[156:159], v[172:175], v[126:129]
	v_mfma_f32_16x16x32_bf16 v[122:125], v[164:167], v[172:175], v[122:125]
	v_mfma_f32_16x16x32_bf16 v[118:121], v[156:159], v[194:197], v[118:121]
	v_mfma_f32_16x16x32_bf16 v[114:117], v[164:167], v[194:197], v[114:117]
	v_mfma_f32_16x16x32_bf16 v[110:113], v[156:159], v[202:205], v[110:113]
	v_mfma_f32_16x16x32_bf16 v[106:109], v[164:167], v[202:205], v[106:109]
	v_mfma_f32_16x16x32_bf16 v[102:105], v[156:159], v[210:213], v[102:105]
	v_mfma_f32_16x16x32_bf16 v[98:101], v[164:167], v[210:213], v[98:101]
	s_barrier
	ds_read_b128 v[214:217], v187
	ds_read_b128 v[218:221], v187 offset:1024
	ds_read_b128 v[234:237], v187 offset:2048
	ds_read_b128 v[238:241], v187 offset:3072
	s_mov_b32 m0, s32
	s_add_u32 s98, s42, s94
	s_addc_u32 s99, s43, s95
	global_load_lds_dwordx4 v135, s[98:99]
	s_mov_b32 m0, s44
	s_add_u32 s98, s42, s72
	s_addc_u32 s99, s43, s73
	global_load_lds_dwordx4 v135, s[98:99]
	s_waitcnt lgkmcnt(0)
	s_waitcnt vmcnt(10)
	s_barrier
	v_mfma_f32_16x16x32_bf16 v[94:97], v[214:217], v[168:171], v[94:97]
	v_mfma_f32_16x16x32_bf16 v[90:93], v[234:237], v[168:171], v[90:93]
	v_mfma_f32_16x16x32_bf16 v[86:89], v[214:217], v[176:179], v[86:89]
	v_mfma_f32_16x16x32_bf16 v[82:85], v[234:237], v[176:179], v[82:85]
	v_mfma_f32_16x16x32_bf16 v[78:81], v[214:217], v[198:201], v[78:81]
	v_mfma_f32_16x16x32_bf16 v[74:77], v[234:237], v[198:201], v[74:77]
	v_mfma_f32_16x16x32_bf16 v[70:73], v[214:217], v[206:209], v[70:73]
	v_mfma_f32_16x16x32_bf16 v[66:69], v[234:237], v[206:209], v[66:69]
	v_mfma_f32_16x16x32_bf16 v[94:97], v[218:221], v[172:175], v[94:97]
	v_mfma_f32_16x16x32_bf16 v[90:93], v[238:241], v[172:175], v[90:93]
	v_mfma_f32_16x16x32_bf16 v[86:89], v[218:221], v[194:197], v[86:89]
	v_mfma_f32_16x16x32_bf16 v[82:85], v[238:241], v[194:197], v[82:85]
	v_mfma_f32_16x16x32_bf16 v[78:81], v[218:221], v[202:205], v[78:81]
	v_mfma_f32_16x16x32_bf16 v[74:77], v[238:241], v[202:205], v[74:77]
	v_mfma_f32_16x16x32_bf16 v[70:73], v[218:221], v[210:213], v[70:73]
	v_mfma_f32_16x16x32_bf16 v[66:69], v[238:241], v[210:213], v[66:69]
	s_barrier
; #define LDA(dst, b, h) for (int m = 0; m < 4; ++m) for (int k = 0; k < 2; ++k) \
;     dst[m][k] = *reinterpret_cast<const bf16x8*>((char*)SA(b, h) + a_thr + (m * 2 + k) * 1024)
; #define LDB(dst, b, h) for (int n = 0; n < 2; ++n) for (int k = 0; k < 2; ++k) \
;     dst[n][k] = *reinterpret_cast<const bf16x8*>((char*)SB(b, h) + b_thr + (n * 2 + k) * 1024)
; #define MMA(ai, bj, At, Btf) do { __builtin_amdgcn_s_setprio(1); \
;     for (int m = 0; m < 4; ++m) for (int n = 0; n < 2; ++n) for (int k = 0; k < 2; ++k) \
;       acc[ai][bj][m][n] = __builtin_amdgcn_mfma_f32_16x16x32_bf16(Btf[n][k], At[m][k], acc[ai][bj][m][n], 0, 0, 0); \
;     __builtin_amdgcn_s_setprio(0); } while (0)
; #define WAIT_V(n) asm volatile("s_waitcnt vmcnt(" #n ")" ::: "memory")
; #define WAIT_L(n) asm volatile("s_waitcnt lgkmcnt(" #n ")" ::: "memory")
; #define BAR __builtin_amdgcn_s_barrier()
; #define SCHED __builtin_amdgcn_sched_barrier(0)
; template <bool OVL, bool PANEL = false, class Epi>
; __device__ __forceinline__ void gemm_phase(const bf16_t* __restrict__ A, long lda, const bf16_t* __restrict__ Bt, long ldb, int nM, int nN, int K,
;                                            const Epi& epi, bf16_t* shm, int w0) {
;     ...
;       LDA(At, 1, 1); STAGE(SA(1, 0), A, lda, aoff, brow, t + 3);
;       BAR; WAIT_L(0); MMA(1, 0, At, B0); BAR; SCHED;
;       STAGE(SB(1, 1), Bt, ldb, boff, bcol + HALF, t + 3);
;       WAIT_V(6); BAR; MMA(1, 1, At, B1); BAR;
;     }
;     { LDB(B0, 0, 0); LDA(At, 0, 0); STAGE(SA(1, 1), A, lda, aoff, brow + HALF, nt - 1);
	ds_read_b128 v[168:171], v147 offset:49152
	ds_read_b128 v[172:175], v147 offset:50176
	ds_read_b128 v[176:179], v147 offset:51200
	ds_read_b128 v[194:197], v147 offset:52224
	ds_read_b128 v[198:201], v147 offset:53248
	ds_read_b128 v[202:205], v147 offset:54272
	ds_read_b128 v[206:209], v147 offset:55296
	ds_read_b128 v[210:213], v147 offset:56320
	s_mov_b32 m0, s45
	s_add_u32 s98, s40, s94
	s_addc_u32 s99, s41, s95
	global_load_lds_dwordx4 v135, s[98:99]
	s_mov_b32 m0, s46
	s_add_u32 s98, s40, s72
	s_addc_u32 s99, s41, s73
	global_load_lds_dwordx4 v135, s[98:99]
	s_waitcnt lgkmcnt(0)
	s_barrier
	v_mfma_f32_16x16x32_bf16 v[62:65], v[152:155], v[168:171], v[62:65]
	v_mfma_f32_16x16x32_bf16 v[58:61], v[160:163], v[168:171], v[58:61]
	v_mfma_f32_16x16x32_bf16 v[54:57], v[152:155], v[176:179], v[54:57]
	v_mfma_f32_16x16x32_bf16 v[50:53], v[160:163], v[176:179], v[50:53]
	v_mfma_f32_16x16x32_bf16 v[46:49], v[152:155], v[198:201], v[46:49]
	v_mfma_f32_16x16x32_bf16 v[42:45], v[160:163], v[198:201], v[42:45]
	v_mfma_f32_16x16x32_bf16 v[38:41], v[152:155], v[206:209], v[38:41]
	v_mfma_f32_16x16x32_bf16 v[34:37], v[160:163], v[206:209], v[34:37]
	v_mfma_f32_16x16x32_bf16 v[62:65], v[156:159], v[172:175], v[62:65]
	v_mfma_f32_16x16x32_bf16 v[58:61], v[164:167], v[172:175], v[58:61]
	v_mfma_f32_16x16x32_bf16 v[54:57], v[156:159], v[194:197], v[54:57]
	v_mfma_f32_16x16x32_bf16 v[50:53], v[164:167], v[194:197], v[50:53]
	v_mfma_f32_16x16x32_bf16 v[46:49], v[156:159], v[202:205], v[46:49]
	v_mfma_f32_16x16x32_bf16 v[42:45], v[164:167], v[202:205], v[42:45]
	v_mfma_f32_16x16x32_bf16 v[38:41], v[156:159], v[210:213], v[38:41]
	v_mfma_f32_16x16x32_bf16 v[34:37], v[164:167], v[210:213], v[34:37]
	s_barrier
	s_mov_b32 m0, s47
	s_add_u32 s98, s42, s18
	s_addc_u32 s99, s43, s19
	global_load_lds_dwordx4 v135, s[98:99]
	s_mov_b32 m0, s48
	s_add_u32 s98, s42, s20
	s_addc_u32 s99, s43, s21
	global_load_lds_dwordx4 v135, s[98:99]
	s_add_i32 s1, s1, 2
	s_add_u32 s14, s14, 0x100
	s_addc_u32 s15, s15, 0
	s_cmp_lt_u32 s1, 12
	s_waitcnt vmcnt(10)
	s_barrier
	v_mfma_f32_16x16x32_bf16 v[30:33], v[214:217], v[168:171], v[30:33]
	v_mfma_f32_16x16x32_bf16 v[26:29], v[234:237], v[168:171], v[26:29]
	v_mfma_f32_16x16x32_bf16 v[22:25], v[214:217], v[176:179], v[22:25]
	v_mfma_f32_16x16x32_bf16 v[18:21], v[234:237], v[176:179], v[18:21]
	v_mfma_f32_16x16x32_bf16 v[14:17], v[214:217], v[198:201], v[14:17]
	v_mfma_f32_16x16x32_bf16 v[10:13], v[234:237], v[198:201], v[10:13]
	v_mfma_f32_16x16x32_bf16 v[6:9], v[214:217], v[206:209], v[6:9]
	v_mfma_f32_16x16x32_bf16 v[2:5], v[234:237], v[206:209], v[2:5]
	v_mfma_f32_16x16x32_bf16 v[30:33], v[218:221], v[172:175], v[30:33]
	v_mfma_f32_16x16x32_bf16 v[26:29], v[238:241], v[172:175], v[26:29]
	v_mfma_f32_16x16x32_bf16 v[22:25], v[218:221], v[194:197], v[22:25]
	v_mfma_f32_16x16x32_bf16 v[18:21], v[238:241], v[194:197], v[18:21]
	v_mfma_f32_16x16x32_bf16 v[14:17], v[218:221], v[202:205], v[14:17]
	v_mfma_f32_16x16x32_bf16 v[10:13], v[238:241], v[202:205], v[10:13]
	v_mfma_f32_16x16x32_bf16 v[6:9], v[218:221], v[210:213], v[6:9]
	v_mfma_f32_16x16x32_bf16 v[2:5], v[238:241], v[210:213], v[2:5]
	s_barrier
	s_cbranch_scc1 .LBB0_1053
	s_waitcnt vmcnt(6)
	s_or_b32 s8, s0, 0x80
	s_ashr_i32 s9, s8, 31
	v_readlane_b32 s40, v252, 20
	s_lshl_b64 s[8:9], s[8:9], 11
	v_readlane_b32 s46, v252, 26
	v_add_u32_e32 v182, 16, v144
	v_readlane_b32 s47, v252, 27
	s_add_u32 s8, s46, s8
	v_add_u32_e32 v0, 0x10000, v182
	s_addc_u32 s9, s47, s9
	ds_read_b128 v[130:133], v0
	ds_read_b128 v[152:155], v0 offset:1024
	ds_read_b128 v[156:159], v0 offset:2048
	ds_read_b128 v[160:163], v0 offset:3072
	ds_read_b128 v[164:167], v147
	ds_read_b128 v[168:171], v147 offset:1024
	ds_read_b128 v[172:175], v147 offset:2048
	ds_read_b128 v[176:179], v147 offset:3072
	ds_read_b128 v[194:197], v147 offset:4096
	ds_read_b128 v[198:201], v147 offset:5120
	ds_read_b128 v[202:205], v147 offset:6144
	ds_read_b128 v[206:209], v147 offset:7168
	v_mov_b32_e32 v0, v135
	v_readfirstlane_b32 s1, v150
	v_lshl_add_u64 v[148:149], s[8:9], 0, v[0:1]
	s_mov_b64 s[8:9], 0x780
	v_lshl_add_u64 v[180:181], v[148:149], 0, s[8:9]
	s_mov_b32 m0, s1
	s_mov_b64 s[8:9], 0x20780
	v_readfirstlane_b32 s1, v151
	global_load_lds_dwordx4 v[180:181], off
	v_lshl_add_u64 v[148:149], v[148:149], 0, s[8:9]
	s_mov_b32 m0, s1
	v_readlane_b32 s41, v252, 21
	global_load_lds_dwordx4 v[148:149], off
	s_barrier
	s_waitcnt lgkmcnt(0)
	v_readlane_b32 s42, v252, 22
	v_readlane_b32 s43, v252, 23
	v_readlane_b32 s44, v252, 24
	v_readlane_b32 s45, v252, 25
	v_readlane_b32 s48, v252, 28
	v_readlane_b32 s49, v252, 29
	v_readlane_b32 s50, v252, 30
	v_readlane_b32 s51, v252, 31
	v_readlane_b32 s52, v252, 32
	v_readlane_b32 s53, v252, 33
	v_readlane_b32 s54, v252, 34
	v_readlane_b32 s55, v252, 35

; #define MMA(ai, bj, At, Btf) do { __builtin_amdgcn_s_setprio(1); \
;     for (int m = 0; m < 4; ++m) for (int n = 0; n < 2; ++n) for (int k = 0; k < 2; ++k) \
;       acc[ai][bj][m][n] = __builtin_amdgcn_mfma_f32_16x16x32_bf16(Btf[n][k], At[m][k], acc[ai][bj][m][n], 0, 0, 0); \
;     __builtin_amdgcn_s_setprio(0); } while (0)
; #define WAIT_L(n) asm volatile("s_waitcnt lgkmcnt(" #n ")" ::: "memory")
; #define BAR __builtin_amdgcn_s_barrier()
; template <bool OVL, bool PANEL = false, class Epi>
; __device__ __forceinline__ void gemm_phase(const bf16_t* __restrict__ A, long lda, const bf16_t* __restrict__ Bt, long ldb, int nM, int nN, int K,
;                                            const Epi& epi, bf16_t* shm, int w0) {
;     ...
;       BAR; WAIT_L(0); MMA(0, 0, At, B0); BAR;
	s_waitcnt lgkmcnt(0)
	v_mfma_f32_16x16x32_bf16 v[126:129], v[130:133], v[164:167], v[126:129]
	v_mfma_f32_16x16x32_bf16 v[122:125], v[156:159], v[164:167], v[122:125]
	v_mfma_f32_16x16x32_bf16 v[118:121], v[130:133], v[172:175], v[118:121]
	v_mfma_f32_16x16x32_bf16 v[114:117], v[156:159], v[172:175], v[114:117]
	v_mfma_f32_16x16x32_bf16 v[110:113], v[130:133], v[194:197], v[110:113]
	v_mfma_f32_16x16x32_bf16 v[106:109], v[156:159], v[194:197], v[106:109]
	v_mfma_f32_16x16x32_bf16 v[102:105], v[130:133], v[202:205], v[102:105]
	v_mfma_f32_16x16x32_bf16 v[98:101], v[156:159], v[202:205], v[98:101]
	v_mfma_f32_16x16x32_bf16 v[126:129], v[152:155], v[168:171], v[126:129]
	v_mfma_f32_16x16x32_bf16 v[122:125], v[160:163], v[168:171], v[122:125]
	v_mfma_f32_16x16x32_bf16 v[118:121], v[152:155], v[176:179], v[118:121]
	v_mfma_f32_16x16x32_bf16 v[114:117], v[160:163], v[176:179], v[114:117]
	v_mfma_f32_16x16x32_bf16 v[110:113], v[152:155], v[198:201], v[110:113]
	v_mfma_f32_16x16x32_bf16 v[106:109], v[160:163], v[198:201], v[106:109]
	v_mfma_f32_16x16x32_bf16 v[102:105], v[152:155], v[206:209], v[102:105]
	v_mfma_f32_16x16x32_bf16 v[98:101], v[160:163], v[206:209], v[98:101]

; #define LDB(dst, b, h) for (int n = 0; n < 2; ++n) for (int k = 0; k < 2; ++k) \
;     dst[n][k] = *reinterpret_cast<const bf16x8*>((char*)SB(b, h) + b_thr + (n * 2 + k) * 1024)
; #define MMA(ai, bj, At, Btf) do { __builtin_amdgcn_s_setprio(1); \
;     for (int m = 0; m < 4; ++m) for (int n = 0; n < 2; ++n) for (int k = 0; k < 2; ++k) \
;       acc[ai][bj][m][n] = __builtin_amdgcn_mfma_f32_16x16x32_bf16(Btf[n][k], At[m][k], acc[ai][bj][m][n], 0, 0, 0); \
;     __builtin_amdgcn_s_setprio(0); } while (0)
; #define WAIT_L(n) asm volatile("s_waitcnt lgkmcnt(" #n ")" ::: "memory")
; #define BAR __builtin_amdgcn_s_barrier()
; template <bool OVL, bool PANEL = false, class Epi>
; __device__ __forceinline__ void gemm_phase(const bf16_t* __restrict__ A, long lda, const bf16_t* __restrict__ Bt, long ldb, int nM, int nN, int K,
;                                            const Epi& epi, bf16_t* shm, int w0) {
;     ...
;       LDB(B1, 0, 1); BAR; WAIT_L(0); MMA(0, 1, At, B1); BAR;
	v_add_u32_e32 v0, 0x14000, v182
	s_barrier
	ds_read_b128 v[148:151], v0
	ds_read_b128 v[210:213], v0 offset:1024
	ds_read_b128 v[214:217], v0 offset:2048
	ds_read_b128 v[218:221], v0 offset:3072
	s_barrier
	s_waitcnt lgkmcnt(0)

; #define LDB(dst, b, h) for (int n = 0; n < 2; ++n) for (int k = 0; k < 2; ++k) \
;     dst[n][k] = *reinterpret_cast<const bf16x8*>((char*)SB(b, h) + b_thr + (n * 2 + k) * 1024)
; #define MMA(ai, bj, At, Btf) do { __builtin_amdgcn_s_setprio(1); \
;     for (int m = 0; m < 4; ++m) for (int n = 0; n < 2; ++n) for (int k = 0; k < 2; ++k) \
;       acc[ai][bj][m][n] = __builtin_amdgcn_mfma_f32_16x16x32_bf16(Btf[n][k], At[m][k], acc[ai][bj][m][n], 0, 0, 0); \
;     __builtin_amdgcn_s_setprio(0); } while (0)
; #define WAIT_L(n) asm volatile("s_waitcnt lgkmcnt(" #n ")" ::: "memory")
; #define BAR __builtin_amdgcn_s_barrier()
; template <bool OVL, bool PANEL = false, class Epi>
; __device__ __forceinline__ void gemm_phase(const bf16_t* __restrict__ A, long lda, const bf16_t* __restrict__ Bt, long ldb, int nM, int nN, int K,
;                                            const Epi& epi, bf16_t* shm, int w0) {
;     ...
;       LDB(B1, 0, 1); BAR; WAIT_L(0); MMA(0, 1, At, B1); BAR;
	s_waitcnt lgkmcnt(0)
	v_mfma_f32_16x16x32_bf16 v[94:97], v[148:151], v[164:167], v[94:97]
	v_mfma_f32_16x16x32_bf16 v[90:93], v[214:217], v[164:167], v[90:93]
	v_mfma_f32_16x16x32_bf16 v[86:89], v[148:151], v[172:175], v[86:89]
	v_mfma_f32_16x16x32_bf16 v[82:85], v[214:217], v[172:175], v[82:85]
	v_mfma_f32_16x16x32_bf16 v[78:81], v[148:151], v[194:197], v[78:81]
	v_mfma_f32_16x16x32_bf16 v[74:77], v[214:217], v[194:197], v[74:77]
	v_mfma_f32_16x16x32_bf16 v[70:73], v[148:151], v[202:205], v[70:73]
	v_mfma_f32_16x16x32_bf16 v[66:69], v[214:217], v[202:205], v[66:69]
	v_mfma_f32_16x16x32_bf16 v[94:97], v[210:213], v[168:171], v[94:97]
	v_mfma_f32_16x16x32_bf16 v[90:93], v[218:221], v[168:171], v[90:93]
	v_mfma_f32_16x16x32_bf16 v[86:89], v[210:213], v[176:179], v[86:89]
	v_mfma_f32_16x16x32_bf16 v[82:85], v[218:221], v[176:179], v[82:85]
	v_mfma_f32_16x16x32_bf16 v[78:81], v[210:213], v[198:201], v[78:81]
	v_mfma_f32_16x16x32_bf16 v[74:77], v[218:221], v[198:201], v[74:77]
	v_mfma_f32_16x16x32_bf16 v[70:73], v[210:213], v[206:209], v[70:73]
	v_mfma_f32_16x16x32_bf16 v[66:69], v[218:221], v[206:209], v[66:69]

; #define LDA(dst, b, h) for (int m = 0; m < 4; ++m) for (int k = 0; k < 2; ++k) \
;     dst[m][k] = *reinterpret_cast<const bf16x8*>((char*)SA(b, h) + a_thr + (m * 2 + k) * 1024)
; #define MMA(ai, bj, At, Btf) do { __builtin_amdgcn_s_setprio(1); \
;     for (int m = 0; m < 4; ++m) for (int n = 0; n < 2; ++n) for (int k = 0; k < 2; ++k) \
;       acc[ai][bj][m][n] = __builtin_amdgcn_mfma_f32_16x16x32_bf16(Btf[n][k], At[m][k], acc[ai][bj][m][n], 0, 0, 0); \
;     __builtin_amdgcn_s_setprio(0); } while (0)
; #define WAIT_V(n) asm volatile("s_waitcnt vmcnt(" #n ")" ::: "memory")
; #define WAIT_L(n) asm volatile("s_waitcnt lgkmcnt(" #n ")" ::: "memory")
; #define BAR __builtin_amdgcn_s_barrier()
; template <bool OVL, bool PANEL = false, class Epi>
; __device__ __forceinline__ void gemm_phase(const bf16_t* __restrict__ A, long lda, const bf16_t* __restrict__ Bt, long ldb, int nM, int nN, int K,
;                                            const Epi& epi, bf16_t* shm, int w0) {
;     ...
;       LDA(At, 0, 1); WAIT_V(4); BAR; WAIT_L(0); MMA(1, 0, At, B0); MMA(1, 1, At, B1); BAR; }
	s_barrier
	ds_read_b128 v[164:167], v147 offset:16384
	ds_read_b128 v[168:171], v147 offset:17408
	ds_read_b128 v[172:175], v147 offset:18432
	ds_read_b128 v[176:179], v147 offset:19456
	ds_read_b128 v[194:197], v147 offset:20480
	ds_read_b128 v[198:201], v147 offset:21504
	ds_read_b128 v[202:205], v147 offset:22528
	ds_read_b128 v[206:209], v147 offset:23552
	s_waitcnt vmcnt(4)
	s_barrier
	s_waitcnt lgkmcnt(0)

; #define LDA(dst, b, h) for (int m = 0; m < 4; ++m) for (int k = 0; k < 2; ++k) \
;     dst[m][k] = *reinterpret_cast<const bf16x8*>((char*)SA(b, h) + a_thr + (m * 2 + k) * 1024)
; #define MMA(ai, bj, At, Btf) do { __builtin_amdgcn_s_setprio(1); \
;     for (int m = 0; m < 4; ++m) for (int n = 0; n < 2; ++n) for (int k = 0; k < 2; ++k) \
;       acc[ai][bj][m][n] = __builtin_amdgcn_mfma_f32_16x16x32_bf16(Btf[n][k], At[m][k], acc[ai][bj][m][n], 0, 0, 0); \
;     __builtin_amdgcn_s_setprio(0); } while (0)
; #define WAIT_V(n) asm volatile("s_waitcnt vmcnt(" #n ")" ::: "memory")
; #define WAIT_L(n) asm volatile("s_waitcnt lgkmcnt(" #n ")" ::: "memory")
; #define BAR __builtin_amdgcn_s_barrier()
; template <bool OVL, bool PANEL = false, class Epi>
; __device__ __forceinline__ void gemm_phase(const bf16_t* __restrict__ A, long lda, const bf16_t* __restrict__ Bt, long ldb, int nM, int nN, int K,
;                                            const Epi& epi, bf16_t* shm, int w0) {
;     ...
;       LDA(At, 0, 1); WAIT_V(4); BAR; WAIT_L(0); MMA(1, 0, At, B0); MMA(1, 1, At, B1); BAR; }
	s_waitcnt lgkmcnt(0)
	v_mfma_f32_16x16x32_bf16 v[62:65], v[130:133], v[164:167], v[62:65]
	v_mfma_f32_16x16x32_bf16 v[58:61], v[156:159], v[164:167], v[58:61]
	v_mfma_f32_16x16x32_bf16 v[54:57], v[130:133], v[172:175], v[54:57]
	v_mfma_f32_16x16x32_bf16 v[50:53], v[156:159], v[172:175], v[50:53]
	v_mfma_f32_16x16x32_bf16 v[46:49], v[130:133], v[194:197], v[46:49]
	v_mfma_f32_16x16x32_bf16 v[42:45], v[156:159], v[194:197], v[42:45]
	v_mfma_f32_16x16x32_bf16 v[38:41], v[130:133], v[202:205], v[38:41]
	v_mfma_f32_16x16x32_bf16 v[34:37], v[156:159], v[202:205], v[34:37]
	v_mfma_f32_16x16x32_bf16 v[62:65], v[152:155], v[168:171], v[62:65]
	v_mfma_f32_16x16x32_bf16 v[58:61], v[160:163], v[168:171], v[58:61]
	v_mfma_f32_16x16x32_bf16 v[54:57], v[152:155], v[176:179], v[54:57]
	v_mfma_f32_16x16x32_bf16 v[50:53], v[160:163], v[176:179], v[50:53]
	v_mfma_f32_16x16x32_bf16 v[46:49], v[152:155], v[198:201], v[46:49]
	v_mfma_f32_16x16x32_bf16 v[42:45], v[160:163], v[198:201], v[42:45]
	v_mfma_f32_16x16x32_bf16 v[38:41], v[152:155], v[206:209], v[38:41]
	v_mfma_f32_16x16x32_bf16 v[34:37], v[160:163], v[206:209], v[34:37]


; #define LDA(dst, b, h) for (int m = 0; m < 4; ++m) for (int k = 0; k < 2; ++k) \
;     dst[m][k] = *reinterpret_cast<const bf16x8*>((char*)SA(b, h) + a_thr + (m * 2 + k) * 1024)
; #define MMA(ai, bj, At, Btf) do { __builtin_amdgcn_s_setprio(1); \
;     for (int m = 0; m < 4; ++m) for (int n = 0; n < 2; ++n) for (int k = 0; k < 2; ++k) \
;       acc[ai][bj][m][n] = __builtin_amdgcn_mfma_f32_16x16x32_bf16(Btf[n][k], At[m][k], acc[ai][bj][m][n], 0, 0, 0); \
;     __builtin_amdgcn_s_setprio(0); } while (0)
; #define WAIT_V(n) asm volatile("s_waitcnt vmcnt(" #n ")" ::: "memory")
; #define WAIT_L(n) asm volatile("s_waitcnt lgkmcnt(" #n ")" ::: "memory")
; #define BAR __builtin_amdgcn_s_barrier()
; template <bool OVL, bool PANEL = false, class Epi>
; __device__ __forceinline__ void gemm_phase(const bf16_t* __restrict__ A, long lda, const bf16_t* __restrict__ Bt, long ldb, int nM, int nN, int K,
;                                            const Epi& epi, bf16_t* shm, int w0) {
;     ...
;       LDA(At, 0, 1); WAIT_V(4); BAR; WAIT_L(0); MMA(1, 0, At, B0); MMA(1, 1, At, B1); BAR; }
	v_mfma_f32_16x16x32_bf16 v[30:33], v[148:151], v[164:167], v[30:33]
	v_mfma_f32_16x16x32_bf16 v[26:29], v[214:217], v[164:167], v[26:29]
	v_mfma_f32_16x16x32_bf16 v[22:25], v[148:151], v[172:175], v[22:25]
	v_mfma_f32_16x16x32_bf16 v[18:21], v[214:217], v[172:175], v[18:21]
	v_mfma_f32_16x16x32_bf16 v[14:17], v[148:151], v[194:197], v[14:17]
	v_mfma_f32_16x16x32_bf16 v[10:13], v[214:217], v[194:197], v[10:13]
	v_mfma_f32_16x16x32_bf16 v[6:9], v[148:151], v[202:205], v[6:9]
	v_mfma_f32_16x16x32_bf16 v[2:5], v[214:217], v[202:205], v[2:5]
	v_mfma_f32_16x16x32_bf16 v[30:33], v[210:213], v[168:171], v[30:33]
	v_mfma_f32_16x16x32_bf16 v[26:29], v[218:221], v[168:171], v[26:29]
	v_mfma_f32_16x16x32_bf16 v[22:25], v[210:213], v[176:179], v[22:25]
	v_mfma_f32_16x16x32_bf16 v[18:21], v[218:221], v[176:179], v[18:21]
	v_mfma_f32_16x16x32_bf16 v[14:17], v[210:213], v[198:201], v[14:17]
	v_mfma_f32_16x16x32_bf16 v[10:13], v[218:221], v[198:201], v[10:13]
	v_mfma_f32_16x16x32_bf16 v[6:9], v[210:213], v[206:209], v[6:9]
	v_mfma_f32_16x16x32_bf16 v[2:5], v[218:221], v[206:209], v[2:5]

; #define LDA(dst, b, h) for (int m = 0; m < 4; ++m) for (int k = 0; k < 2; ++k) \
;     dst[m][k] = *reinterpret_cast<const bf16x8*>((char*)SA(b, h) + a_thr + (m * 2 + k) * 1024)
; #define LDB(dst, b, h) for (int n = 0; n < 2; ++n) for (int k = 0; k < 2; ++k) \
;     dst[n][k] = *reinterpret_cast<const bf16x8*>((char*)SB(b, h) + b_thr + (n * 2 + k) * 1024)
; #define MMA(ai, bj, At, Btf) do { __builtin_amdgcn_s_setprio(1); \
;     for (int m = 0; m < 4; ++m) for (int n = 0; n < 2; ++n) for (int k = 0; k < 2; ++k) \
;       acc[ai][bj][m][n] = __builtin_amdgcn_mfma_f32_16x16x32_bf16(Btf[n][k], At[m][k], acc[ai][bj][m][n], 0, 0, 0); \
;     __builtin_amdgcn_s_setprio(0); } while (0)
; #define WAIT_V(n) asm volatile("s_waitcnt vmcnt(" #n ")" ::: "memory")
; #define WAIT_L(n) asm volatile("s_waitcnt lgkmcnt(" #n ")" ::: "memory")
; #define BAR __builtin_amdgcn_s_barrier()
; template <bool OVL, bool PANEL = false, class Epi>
; __device__ __forceinline__ void gemm_phase(const bf16_t* __restrict__ A, long lda, const bf16_t* __restrict__ Bt, long ldb, int nM, int nN, int K,
;                                            const Epi& epi, bf16_t* shm, int w0) {
;     ...
;     { LDB(B0, 1, 0); LDA(At, 1, 0); WAIT_V(2); BAR; WAIT_L(0); MMA(0, 0, At, B0); BAR;
	v_add_u32_e32 v0, 0x18000, v182
	s_barrier
	ds_read_b128 v[130:133], v0
	ds_read_b128 v[148:151], v0 offset:1024
	ds_read_b128 v[152:155], v0 offset:2048
	ds_read_b128 v[156:159], v0 offset:3072
	ds_read_b128 v[160:163], v147 offset:32768
	ds_read_b128 v[164:167], v147 offset:33792
	ds_read_b128 v[168:171], v147 offset:34816
	ds_read_b128 v[172:175], v147 offset:35840
	ds_read_b128 v[176:179], v147 offset:36864
	ds_read_b128 v[194:197], v147 offset:37888
	ds_read_b128 v[198:201], v147 offset:38912
	ds_read_b128 v[202:205], v147 offset:39936
	s_waitcnt vmcnt(2)
	s_barrier
	s_waitcnt lgkmcnt(0)

; #define LDA(dst, b, h) for (int m = 0; m < 4; ++m) for (int k = 0; k < 2; ++k) \
;     dst[m][k] = *reinterpret_cast<const bf16x8*>((char*)SA(b, h) + a_thr + (m * 2 + k) * 1024)
; #define LDB(dst, b, h) for (int n = 0; n < 2; ++n) for (int k = 0; k < 2; ++k) \
;     dst[n][k] = *reinterpret_cast<const bf16x8*>((char*)SB(b, h) + b_thr + (n * 2 + k) * 1024)
; #define MMA(ai, bj, At, Btf) do { __builtin_amdgcn_s_setprio(1); \
;     for (int m = 0; m < 4; ++m) for (int n = 0; n < 2; ++n) for (int k = 0; k < 2; ++k) \
;       acc[ai][bj][m][n] = __builtin_amdgcn_mfma_f32_16x16x32_bf16(Btf[n][k], At[m][k], acc[ai][bj][m][n], 0, 0, 0); \
;     __builtin_amdgcn_s_setprio(0); } while (0)
; #define WAIT_V(n) asm volatile("s_waitcnt vmcnt(" #n ")" ::: "memory")
; #define WAIT_L(n) asm volatile("s_waitcnt lgkmcnt(" #n ")" ::: "memory")
; #define BAR __builtin_amdgcn_s_barrier()
; template <bool OVL, bool PANEL = false, class Epi>
; __device__ __forceinline__ void gemm_phase(const bf16_t* __restrict__ A, long lda, const bf16_t* __restrict__ Bt, long ldb, int nM, int nN, int K,
;                                            const Epi& epi, bf16_t* shm, int w0) {
;     ...
;     { LDB(B0, 1, 0); LDA(At, 1, 0); WAIT_V(2); BAR; WAIT_L(0); MMA(0, 0, At, B0); BAR;
	s_waitcnt lgkmcnt(0)
	v_mfma_f32_16x16x32_bf16 v[126:129], v[130:133], v[160:163], v[126:129]
	v_mfma_f32_16x16x32_bf16 v[122:125], v[152:155], v[160:163], v[122:125]
	v_mfma_f32_16x16x32_bf16 v[118:121], v[130:133], v[168:171], v[118:121]
	v_mfma_f32_16x16x32_bf16 v[114:117], v[152:155], v[168:171], v[114:117]
	v_mfma_f32_16x16x32_bf16 v[110:113], v[130:133], v[176:179], v[110:113]
	v_mfma_f32_16x16x32_bf16 v[106:109], v[152:155], v[176:179], v[106:109]
	v_mfma_f32_16x16x32_bf16 v[102:105], v[130:133], v[198:201], v[102:105]
	v_mfma_f32_16x16x32_bf16 v[98:101], v[152:155], v[198:201], v[98:101]
	v_mfma_f32_16x16x32_bf16 v[126:129], v[148:151], v[164:167], v[126:129]
	v_mfma_f32_16x16x32_bf16 v[122:125], v[156:159], v[164:167], v[122:125]
	v_mfma_f32_16x16x32_bf16 v[118:121], v[148:151], v[172:175], v[118:121]
	v_mfma_f32_16x16x32_bf16 v[114:117], v[156:159], v[172:175], v[114:117]
	v_mfma_f32_16x16x32_bf16 v[110:113], v[148:151], v[194:197], v[110:113]
	v_mfma_f32_16x16x32_bf16 v[106:109], v[156:159], v[194:197], v[106:109]
	v_mfma_f32_16x16x32_bf16 v[102:105], v[148:151], v[202:205], v[102:105]
	v_mfma_f32_16x16x32_bf16 v[98:101], v[156:159], v[202:205], v[98:101]

; #define LDB(dst, b, h) for (int n = 0; n < 2; ++n) for (int k = 0; k < 2; ++k) \
;     dst[n][k] = *reinterpret_cast<const bf16x8*>((char*)SB(b, h) + b_thr + (n * 2 + k) * 1024)
; #define MMA(ai, bj, At, Btf) do { __builtin_amdgcn_s_setprio(1); \
;     for (int m = 0; m < 4; ++m) for (int n = 0; n < 2; ++n) for (int k = 0; k < 2; ++k) \
;       acc[ai][bj][m][n] = __builtin_amdgcn_mfma_f32_16x16x32_bf16(Btf[n][k], At[m][k], acc[ai][bj][m][n], 0, 0, 0); \
;     __builtin_amdgcn_s_setprio(0); } while (0)
; #define WAIT_V(n) asm volatile("s_waitcnt vmcnt(" #n ")" ::: "memory")
; #define WAIT_L(n) asm volatile("s_waitcnt lgkmcnt(" #n ")" ::: "memory")
; #define BAR __builtin_amdgcn_s_barrier()
; template <bool OVL, bool PANEL = false, class Epi>
; __device__ __forceinline__ void gemm_phase(const bf16_t* __restrict__ A, long lda, const bf16_t* __restrict__ Bt, long ldb, int nM, int nN, int K,
;                                            const Epi& epi, bf16_t* shm, int w0) {
;     ...
;       LDB(B1, 1, 1); WAIT_V(0); BAR; WAIT_L(0); MMA(0, 1, At, B1); BAR;
	v_add_u32_e32 v0, 0x1c000, v182
	s_barrier
	ds_read_b128 v[206:209], v0
	ds_read_b128 v[210:213], v0 offset:1024
	ds_read_b128 v[214:217], v0 offset:2048
	ds_read_b128 v[218:221], v0 offset:3072
	s_waitcnt vmcnt(0)
	s_barrier
	s_waitcnt lgkmcnt(0)

; #define LDB(dst, b, h) for (int n = 0; n < 2; ++n) for (int k = 0; k < 2; ++k) \
;     dst[n][k] = *reinterpret_cast<const bf16x8*>((char*)SB(b, h) + b_thr + (n * 2 + k) * 1024)
; #define MMA(ai, bj, At, Btf) do { __builtin_amdgcn_s_setprio(1); \
;     for (int m = 0; m < 4; ++m) for (int n = 0; n < 2; ++n) for (int k = 0; k < 2; ++k) \
;       acc[ai][bj][m][n] = __builtin_amdgcn_mfma_f32_16x16x32_bf16(Btf[n][k], At[m][k], acc[ai][bj][m][n], 0, 0, 0); \
;     __builtin_amdgcn_s_setprio(0); } while (0)
; #define WAIT_V(n) asm volatile("s_waitcnt vmcnt(" #n ")" ::: "memory")
; #define WAIT_L(n) asm volatile("s_waitcnt lgkmcnt(" #n ")" ::: "memory")
; #define BAR __builtin_amdgcn_s_barrier()
; template <bool OVL, bool PANEL = false, class Epi>
; __device__ __forceinline__ void gemm_phase(const bf16_t* __restrict__ A, long lda, const bf16_t* __restrict__ Bt, long ldb, int nM, int nN, int K,
;                                            const Epi& epi, bf16_t* shm, int w0) {
;     ...
;       LDB(B1, 1, 1); WAIT_V(0); BAR; WAIT_L(0); MMA(0, 1, At, B1); BAR;
	s_waitcnt lgkmcnt(0)
	v_mfma_f32_16x16x32_bf16 v[94:97], v[206:209], v[160:163], v[94:97]
	v_mfma_f32_16x16x32_bf16 v[90:93], v[214:217], v[160:163], v[90:93]
	v_mfma_f32_16x16x32_bf16 v[86:89], v[206:209], v[168:171], v[86:89]
	v_mfma_f32_16x16x32_bf16 v[82:85], v[214:217], v[168:171], v[82:85]
	v_mfma_f32_16x16x32_bf16 v[78:81], v[206:209], v[176:179], v[78:81]
	v_mfma_f32_16x16x32_bf16 v[74:77], v[214:217], v[176:179], v[74:77]
	v_mfma_f32_16x16x32_bf16 v[70:73], v[206:209], v[198:201], v[70:73]
	v_mfma_f32_16x16x32_bf16 v[66:69], v[214:217], v[198:201], v[66:69]
	v_mfma_f32_16x16x32_bf16 v[94:97], v[210:213], v[164:167], v[94:97]
	v_mfma_f32_16x16x32_bf16 v[90:93], v[218:221], v[164:167], v[90:93]
	v_mfma_f32_16x16x32_bf16 v[86:89], v[210:213], v[172:175], v[86:89]
	v_mfma_f32_16x16x32_bf16 v[82:85], v[218:221], v[172:175], v[82:85]
	v_mfma_f32_16x16x32_bf16 v[78:81], v[210:213], v[194:197], v[78:81]
	v_mfma_f32_16x16x32_bf16 v[74:77], v[218:221], v[194:197], v[74:77]
	v_mfma_f32_16x16x32_bf16 v[70:73], v[210:213], v[202:205], v[70:73]
	v_mfma_f32_16x16x32_bf16 v[66:69], v[218:221], v[202:205], v[66:69]

; #define LDA(dst, b, h) for (int m = 0; m < 4; ++m) for (int k = 0; k < 2; ++k) \
;     dst[m][k] = *reinterpret_cast<const bf16x8*>((char*)SA(b, h) + a_thr + (m * 2 + k) * 1024)
; #define MMA(ai, bj, At, Btf) do { __builtin_amdgcn_s_setprio(1); \
;     for (int m = 0; m < 4; ++m) for (int n = 0; n < 2; ++n) for (int k = 0; k < 2; ++k) \
;       acc[ai][bj][m][n] = __builtin_amdgcn_mfma_f32_16x16x32_bf16(Btf[n][k], At[m][k], acc[ai][bj][m][n], 0, 0, 0); \
;     __builtin_amdgcn_s_setprio(0); } while (0)
; #define WAIT_L(n) asm volatile("s_waitcnt lgkmcnt(" #n ")" ::: "memory")
; #define BAR __builtin_amdgcn_s_barrier()
; template <bool OVL, bool PANEL = false, class Epi>
; __device__ __forceinline__ void gemm_phase(const bf16_t* __restrict__ A, long lda, const bf16_t* __restrict__ Bt, long ldb, int nM, int nN, int K,
;                                            const Epi& epi, bf16_t* shm, int w0) {
;     ...
;       LDA(At, 1, 1); BAR; WAIT_L(0); MMA(1, 0, At, B0); MMA(1, 1, At, B1); BAR; }
	s_barrier
	ds_read_b128 v[160:163], v147 offset:49152
	ds_read_b128 v[164:167], v147 offset:50176
	ds_read_b128 v[168:171], v147 offset:51200
	ds_read_b128 v[172:175], v147 offset:52224
	ds_read_b128 v[176:179], v147 offset:53248
	ds_read_b128 v[194:197], v147 offset:54272
	ds_read_b128 v[198:201], v147 offset:55296
	ds_read_b128 v[202:205], v147 offset:56320
	s_barrier
	s_waitcnt lgkmcnt(0)

; #define LDA(dst, b, h) for (int m = 0; m < 4; ++m) for (int k = 0; k < 2; ++k) \
;     dst[m][k] = *reinterpret_cast<const bf16x8*>((char*)SA(b, h) + a_thr + (m * 2 + k) * 1024)
; #define MMA(ai, bj, At, Btf) do { __builtin_amdgcn_s_setprio(1); \
;     for (int m = 0; m < 4; ++m) for (int n = 0; n < 2; ++n) for (int k = 0; k < 2; ++k) \
;       acc[ai][bj][m][n] = __builtin_amdgcn_mfma_f32_16x16x32_bf16(Btf[n][k], At[m][k], acc[ai][bj][m][n], 0, 0, 0); \
;     __builtin_amdgcn_s_setprio(0); } while (0)
; #define WAIT_L(n) asm volatile("s_waitcnt lgkmcnt(" #n ")" ::: "memory")
; #define BAR __builtin_amdgcn_s_barrier()
; template <bool OVL, bool PANEL = false, class Epi>
; __device__ __forceinline__ void gemm_phase(const bf16_t* __restrict__ A, long lda, const bf16_t* __restrict__ Bt, long ldb, int nM, int nN, int K,
;                                            const Epi& epi, bf16_t* shm, int w0) {
;     ...
;       LDA(At, 1, 1); BAR; WAIT_L(0); MMA(1, 0, At, B0); MMA(1, 1, At, B1); BAR; }
	s_waitcnt lgkmcnt(0)
	v_mfma_f32_16x16x32_bf16 v[62:65], v[130:133], v[160:163], v[62:65]
	v_mfma_f32_16x16x32_bf16 v[58:61], v[152:155], v[160:163], v[58:61]
	v_mfma_f32_16x16x32_bf16 v[54:57], v[130:133], v[168:171], v[54:57]
	v_mfma_f32_16x16x32_bf16 v[50:53], v[152:155], v[168:171], v[50:53]
	v_mfma_f32_16x16x32_bf16 v[46:49], v[130:133], v[176:179], v[46:49]
	v_mfma_f32_16x16x32_bf16 v[42:45], v[152:155], v[176:179], v[42:45]
	v_mfma_f32_16x16x32_bf16 v[38:41], v[130:133], v[198:201], v[38:41]
	v_mfma_f32_16x16x32_bf16 v[34:37], v[152:155], v[198:201], v[34:37]
	v_mfma_f32_16x16x32_bf16 v[62:65], v[148:151], v[164:167], v[62:65]
	v_mfma_f32_16x16x32_bf16 v[58:61], v[156:159], v[164:167], v[58:61]
	v_mfma_f32_16x16x32_bf16 v[54:57], v[148:151], v[172:175], v[54:57]
	v_mfma_f32_16x16x32_bf16 v[50:53], v[156:159], v[172:175], v[50:53]
	v_mfma_f32_16x16x32_bf16 v[46:49], v[148:151], v[194:197], v[46:49]
	v_mfma_f32_16x16x32_bf16 v[42:45], v[156:159], v[194:197], v[42:45]
	v_mfma_f32_16x16x32_bf16 v[38:41], v[148:151], v[202:205], v[38:41]
	v_mfma_f32_16x16x32_bf16 v[34:37], v[156:159], v[202:205], v[34:37]


; #define LDA(dst, b, h) for (int m = 0; m < 4; ++m) for (int k = 0; k < 2; ++k) \
;     dst[m][k] = *reinterpret_cast<const bf16x8*>((char*)SA(b, h) + a_thr + (m * 2 + k) * 1024)
; #define MMA(ai, bj, At, Btf) do { __builtin_amdgcn_s_setprio(1); \
;     for (int m = 0; m < 4; ++m) for (int n = 0; n < 2; ++n) for (int k = 0; k < 2; ++k) \
;       acc[ai][bj][m][n] = __builtin_amdgcn_mfma_f32_16x16x32_bf16(Btf[n][k], At[m][k], acc[ai][bj][m][n], 0, 0, 0); \
;     __builtin_amdgcn_s_setprio(0); } while (0)
; #define WAIT_L(n) asm volatile("s_waitcnt lgkmcnt(" #n ")" ::: "memory")
; #define BAR __builtin_amdgcn_s_barrier()
; template <bool OVL, bool PANEL = false, class Epi>
; __device__ __forceinline__ void gemm_phase(const bf16_t* __restrict__ A, long lda, const bf16_t* __restrict__ Bt, long ldb, int nM, int nN, int K,
;                                            const Epi& epi, bf16_t* shm, int w0) {
;     ...
;       LDA(At, 1, 1); BAR; WAIT_L(0); MMA(1, 0, At, B0); MMA(1, 1, At, B1); BAR; }
	v_mfma_f32_16x16x32_bf16 v[30:33], v[206:209], v[160:163], v[30:33]
	v_mfma_f32_16x16x32_bf16 v[26:29], v[214:217], v[160:163], v[26:29]
	v_mfma_f32_16x16x32_bf16 v[22:25], v[206:209], v[168:171], v[22:25]
	v_mfma_f32_16x16x32_bf16 v[18:21], v[214:217], v[168:171], v[18:21]
	v_mfma_f32_16x16x32_bf16 v[14:17], v[206:209], v[176:179], v[14:17]
	v_mfma_f32_16x16x32_bf16 v[10:13], v[214:217], v[176:179], v[10:13]
	v_mfma_f32_16x16x32_bf16 v[6:9], v[206:209], v[198:201], v[6:9]
	v_mfma_f32_16x16x32_bf16 v[2:5], v[214:217], v[198:201], v[2:5]
	v_mfma_f32_16x16x32_bf16 v[30:33], v[210:213], v[164:167], v[30:33]
	v_mfma_f32_16x16x32_bf16 v[26:29], v[218:221], v[164:167], v[26:29]
	v_mfma_f32_16x16x32_bf16 v[22:25], v[210:213], v[172:175], v[22:25]
	v_mfma_f32_16x16x32_bf16 v[18:21], v[218:221], v[172:175], v[18:21]
	v_mfma_f32_16x16x32_bf16 v[14:17], v[210:213], v[194:197], v[14:17]
	v_mfma_f32_16x16x32_bf16 v[10:13], v[218:221], v[194:197], v[10:13]
	v_mfma_f32_16x16x32_bf16 v[6:9], v[210:213], v[202:205], v[6:9]
	v_mfma_f32_16x16x32_bf16 v[2:5], v[218:221], v[202:205], v[2:5]

; #define LDA(dst, b, h) for (int m = 0; m < 4; ++m) for (int k = 0; k < 2; ++k) \
;     dst[m][k] = *reinterpret_cast<const bf16x8*>((char*)SA(b, h) + a_thr + (m * 2 + k) * 1024)
; #define MMA(ai, bj, At, Btf) do { __builtin_amdgcn_s_setprio(1); \
;     for (int m = 0; m < 4; ++m) for (int n = 0; n < 2; ++n) for (int k = 0; k < 2; ++k) \
;       acc[ai][bj][m][n] = __builtin_amdgcn_mfma_f32_16x16x32_bf16(Btf[n][k], At[m][k], acc[ai][bj][m][n], 0, 0, 0); \
;     __builtin_amdgcn_s_setprio(0); } while (0)
; #define WAIT_L(n) asm volatile("s_waitcnt lgkmcnt(" #n ")" ::: "memory")
; #define BAR __builtin_amdgcn_s_barrier()
; template <bool OVL, bool PANEL = false, class Epi>
; __device__ __forceinline__ void gemm_phase(const bf16_t* __restrict__ A, long lda, const bf16_t* __restrict__ Bt, long ldb, int nM, int nN, int K,
;                                            const Epi& epi, bf16_t* shm, int w0) {
;     ...
;       LDA(At, 1, 1); BAR; WAIT_L(0); MMA(1, 0, At, B0); MMA(1, 1, At, B1); BAR; }
;     if (wr == 0) BAR;
	s_barrier
	s_and_saveexec_b64 s[8:9], s[6:7]
	s_cbranch_execz .LBB0_1056
	s_barrier
